# GEMM epilogues (in-proj, gate, MoE down): bf16 dwordx2 store pairs widened to dwordx4 via v_permlane16_swap (half the store instructions)
# speedup vs baseline: 1.0113x; 1.0071x over previous
.LBB0_648:
	ds_read_b128 v[2:5], v167
	ds_read_b128 v[6:9], v171
	ds_read_b128 v[10:13], v172
	ds_read_b128 v[14:17], v173
	s_add_u32 s30, s28, 0xfffe0080
	s_addc_u32 s31, s29, -1
	s_cmp_eq_u32 s68, 4
	s_cselect_b32 s35, s21, s31
	s_cselect_b32 s34, s62, s30
	s_cselect_b32 s31, s19, s65
	s_cselect_b32 s30, s63, s64
	v_lshl_add_u64 v[158:159], s[28:29], 0, v[152:153]
	s_add_i32 m0, s27, 0xc000
	ds_read_b128 v[186:189], v184
	ds_read_b128 v[190:193], v184 offset:1024
	ds_read_b128 v[194:197], v184 offset:2048
	ds_read_b128 v[198:201], v184 offset:3072
	ds_read_b128 v[202:205], v184 offset:4096
	ds_read_b128 v[206:209], v184 offset:5120
	ds_read_b128 v[210:213], v184 offset:6144
	ds_read_b128 v[214:217], v184 offset:7168
	global_load_lds_dwordx4 v[158:159], off
	v_lshl_add_u64 v[158:159], s[28:29], 0, v[150:151]
	s_add_i32 m0, s27, 0xe000
	s_nop 0
	global_load_lds_dwordx4 v[158:159], off
	s_waitcnt lgkmcnt(8)
	s_barrier
	s_waitcnt lgkmcnt(0)
	s_setprio 1
	s_waitcnt lgkmcnt(0)
	v_mfma_f32_16x16x128_f8f6f4 v[142:145], v[2:9], v[186:193], v[142:145]
	v_mfma_f32_16x16x128_f8f6f4 v[138:141], v[10:17], v[186:193], v[138:141]
	v_mfma_f32_16x16x128_f8f6f4 v[134:137], v[2:9], v[194:201], v[134:137]
	v_mfma_f32_16x16x128_f8f6f4 v[126:129], v[10:17], v[194:201], v[126:129]
	v_mfma_f32_16x16x128_f8f6f4 v[118:121], v[2:9], v[202:209], v[118:121]
	v_mfma_f32_16x16x128_f8f6f4 v[110:113], v[10:17], v[202:209], v[110:113]
	v_mfma_f32_16x16x128_f8f6f4 v[102:105], v[2:9], v[210:217], v[102:105]
	v_mfma_f32_16x16x128_f8f6f4 v[94:97], v[10:17], v[210:217], v[94:97]
	s_setprio 0
	s_barrier
	s_mov_b32 m0, s37
	v_lshl_add_u64 v[158:159], s[30:31], 0, v[148:149]
	ds_read_b128 v[220:223], v168
	ds_read_b128 v[224:227], v174
	ds_read_b128 v[228:231], v175
	ds_read_b128 v[232:235], v176
	global_load_lds_dwordx4 v[158:159], off
	v_lshl_add_u64 v[160:161], s[30:31], 0, v[146:147]
	s_mov_b32 m0, s38
	s_nop 0
	global_load_lds_dwordx4 v[160:161], off
	s_barrier
	s_waitcnt lgkmcnt(0)
	s_setprio 1
	s_waitcnt lgkmcnt(0)
	v_mfma_f32_16x16x128_f8f6f4 v[130:133], v[220:227], v[186:193], v[130:133]
	v_mfma_f32_16x16x128_f8f6f4 v[122:125], v[228:235], v[186:193], v[122:125]
	v_mfma_f32_16x16x128_f8f6f4 v[114:117], v[220:227], v[194:201], v[114:117]
	v_mfma_f32_16x16x128_f8f6f4 v[106:109], v[228:235], v[194:201], v[106:109]
	v_mfma_f32_16x16x128_f8f6f4 v[98:101], v[220:227], v[202:209], v[98:101]
	v_mfma_f32_16x16x128_f8f6f4 v[90:93], v[228:235], v[202:209], v[90:93]
	v_mfma_f32_16x16x128_f8f6f4 v[86:89], v[220:227], v[210:217], v[86:89]
	v_mfma_f32_16x16x128_f8f6f4 v[82:85], v[228:235], v[210:217], v[82:85]
	s_setprio 0
	s_mov_b32 m0, s27
	v_lshl_add_u64 v[162:163], s[34:35], 0, v[148:149]
	s_barrier
	ds_read_b128 v[186:189], v184 offset:16384
	ds_read_b128 v[190:193], v184 offset:17408
	ds_read_b128 v[194:197], v184 offset:18432
	ds_read_b128 v[198:201], v184 offset:19456
	ds_read_b128 v[202:205], v184 offset:20480
	ds_read_b128 v[206:209], v184 offset:21504
	ds_read_b128 v[210:213], v184 offset:22528
	ds_read_b128 v[214:217], v184 offset:23552
	global_load_lds_dwordx4 v[162:163], off
	v_lshl_add_u64 v[164:165], s[34:35], 0, v[146:147]
	s_mov_b32 m0, s39
	s_nop 0
	global_load_lds_dwordx4 v[164:165], off
	s_barrier
	s_waitcnt lgkmcnt(0)
	s_setprio 1
	s_waitcnt lgkmcnt(0)
	v_mfma_f32_16x16x128_f8f6f4 v[78:81], v[2:9], v[186:193], v[78:81]
	v_mfma_f32_16x16x128_f8f6f4 v[74:77], v[10:17], v[186:193], v[74:77]
	v_mfma_f32_16x16x128_f8f6f4 v[70:73], v[2:9], v[194:201], v[70:73]
	v_mfma_f32_16x16x128_f8f6f4 v[62:65], v[10:17], v[194:201], v[62:65]
	v_mfma_f32_16x16x128_f8f6f4 v[54:57], v[2:9], v[202:209], v[54:57]
	v_mfma_f32_16x16x128_f8f6f4 v[46:49], v[10:17], v[202:209], v[46:49]
	v_mfma_f32_16x16x128_f8f6f4 v[38:41], v[2:9], v[210:217], v[38:41]
	v_mfma_f32_16x16x128_f8f6f4 v[30:33], v[10:17], v[210:217], v[30:33]
	s_setprio 0
	s_barrier
	s_add_u32 s70, s30, 0x20000
	s_addc_u32 s71, s31, 0
	s_mov_b32 m0, s40
	v_lshl_add_u64 v[2:3], s[70:71], 0, v[148:149]
	global_load_lds_dwordx4 v[2:3], off
	v_lshl_add_u64 v[2:3], s[70:71], 0, v[146:147]
	s_mov_b32 m0, s41
	s_nop 0
	global_load_lds_dwordx4 v[2:3], off
	s_waitcnt vmcnt(6)
	s_barrier
	s_setprio 1
	v_mfma_f32_16x16x128_f8f6f4 v[66:69], v[220:227], v[186:193], v[66:69]
	v_mfma_f32_16x16x128_f8f6f4 v[58:61], v[228:235], v[186:193], v[58:61]
	v_mfma_f32_16x16x128_f8f6f4 v[50:53], v[220:227], v[194:201], v[50:53]
	v_mfma_f32_16x16x128_f8f6f4 v[42:45], v[228:235], v[194:201], v[42:45]
	v_mfma_f32_16x16x128_f8f6f4 v[34:37], v[220:227], v[202:209], v[34:37]
	v_mfma_f32_16x16x128_f8f6f4 v[26:29], v[228:235], v[202:209], v[26:29]
	v_mfma_f32_16x16x128_f8f6f4 v[22:25], v[220:227], v[210:217], v[22:25]
	v_mfma_f32_16x16x128_f8f6f4 v[18:21], v[228:235], v[210:217], v[18:21]
	s_setprio 0
	s_barrier
	ds_read_b128 v[2:5], v169
	ds_read_b128 v[6:9], v177
	ds_read_b128 v[10:13], v178
	ds_read_b128 v[14:17], v179
	s_add_u32 s34, s34, 0x20000
	s_addc_u32 s35, s35, 0
	s_mov_b32 m0, s42
	v_lshl_add_u64 v[220:221], s[34:35], 0, v[148:149]
	ds_read_b128 v[186:189], v184 offset:32768
	ds_read_b128 v[190:193], v184 offset:33792
	ds_read_b128 v[194:197], v184 offset:34816
	ds_read_b128 v[198:201], v184 offset:35840
	ds_read_b128 v[202:205], v184 offset:36864
	ds_read_b128 v[206:209], v184 offset:37888
	ds_read_b128 v[210:213], v184 offset:38912
	ds_read_b128 v[214:217], v184 offset:39936
	global_load_lds_dwordx4 v[220:221], off
	v_lshl_add_u64 v[220:221], s[34:35], 0, v[146:147]
	s_mov_b32 m0, s43
	s_nop 0
	global_load_lds_dwordx4 v[220:221], off
	s_waitcnt lgkmcnt(8)
	s_barrier
	s_waitcnt lgkmcnt(0)
	s_setprio 1
	s_waitcnt lgkmcnt(0)
	v_mfma_f32_16x16x128_f8f6f4 v[142:145], v[2:9], v[186:193], v[142:145]
	v_mfma_f32_16x16x128_f8f6f4 v[138:141], v[10:17], v[186:193], v[138:141]
	v_mfma_f32_16x16x128_f8f6f4 v[134:137], v[2:9], v[194:201], v[134:137]
	v_mfma_f32_16x16x128_f8f6f4 v[126:129], v[10:17], v[194:201], v[126:129]
	v_mfma_f32_16x16x128_f8f6f4 v[118:121], v[2:9], v[202:209], v[118:121]
	v_mfma_f32_16x16x128_f8f6f4 v[110:113], v[10:17], v[202:209], v[110:113]
	v_mfma_f32_16x16x128_f8f6f4 v[102:105], v[2:9], v[210:217], v[102:105]
	v_mfma_f32_16x16x128_f8f6f4 v[94:97], v[10:17], v[210:217], v[94:97]
	s_setprio 0
	s_barrier
	s_mov_b32 m0, s46
	v_lshl_add_u64 v[158:159], v[158:159], 0, s[14:15]
	ds_read_b128 v[220:223], v170
	ds_read_b128 v[224:227], v180
	ds_read_b128 v[228:231], v181
	ds_read_b128 v[232:235], v182
	global_load_lds_dwordx4 v[158:159], off
	v_lshl_add_u64 v[158:159], v[160:161], 0, s[14:15]
	s_mov_b32 m0, s47
	s_nop 0
	global_load_lds_dwordx4 v[158:159], off
	s_barrier
	s_waitcnt lgkmcnt(0)
	s_setprio 1
	s_waitcnt lgkmcnt(0)
	v_mfma_f32_16x16x128_f8f6f4 v[130:133], v[220:227], v[186:193], v[130:133]
	v_mfma_f32_16x16x128_f8f6f4 v[122:125], v[228:235], v[186:193], v[122:125]
	v_mfma_f32_16x16x128_f8f6f4 v[114:117], v[220:227], v[194:201], v[114:117]
	v_mfma_f32_16x16x128_f8f6f4 v[106:109], v[228:235], v[194:201], v[106:109]
	v_mfma_f32_16x16x128_f8f6f4 v[98:101], v[220:227], v[202:209], v[98:101]
	v_mfma_f32_16x16x128_f8f6f4 v[90:93], v[228:235], v[202:209], v[90:93]
	v_mfma_f32_16x16x128_f8f6f4 v[86:89], v[220:227], v[210:217], v[86:89]
	v_mfma_f32_16x16x128_f8f6f4 v[82:85], v[228:235], v[210:217], v[82:85]
	s_setprio 0
	s_mov_b32 m0, s48
	v_lshl_add_u64 v[158:159], v[162:163], 0, s[14:15]
	s_barrier
	ds_read_b128 v[186:189], v184 offset:49152
	ds_read_b128 v[190:193], v184 offset:50176
	ds_read_b128 v[194:197], v184 offset:51200
	ds_read_b128 v[198:201], v184 offset:52224
	ds_read_b128 v[202:205], v184 offset:53248
	ds_read_b128 v[206:209], v184 offset:54272
	ds_read_b128 v[210:213], v184 offset:55296
	ds_read_b128 v[214:217], v184 offset:56320
	global_load_lds_dwordx4 v[158:159], off
	v_lshl_add_u64 v[158:159], v[164:165], 0, s[14:15]
	s_mov_b32 m0, s49
	s_nop 0
	global_load_lds_dwordx4 v[158:159], off
	s_barrier
	s_waitcnt lgkmcnt(0)
	s_setprio 1
	s_waitcnt lgkmcnt(0)
	v_mfma_f32_16x16x128_f8f6f4 v[78:81], v[2:9], v[186:193], v[78:81]
	v_mfma_f32_16x16x128_f8f6f4 v[74:77], v[10:17], v[186:193], v[74:77]
	v_mfma_f32_16x16x128_f8f6f4 v[70:73], v[2:9], v[194:201], v[70:73]
	v_mfma_f32_16x16x128_f8f6f4 v[62:65], v[10:17], v[194:201], v[62:65]
	v_mfma_f32_16x16x128_f8f6f4 v[54:57], v[2:9], v[202:209], v[54:57]
	v_mfma_f32_16x16x128_f8f6f4 v[46:49], v[10:17], v[202:209], v[46:49]
	v_mfma_f32_16x16x128_f8f6f4 v[38:41], v[2:9], v[210:217], v[38:41]
	v_mfma_f32_16x16x128_f8f6f4 v[30:33], v[10:17], v[210:217], v[30:33]
	s_setprio 0
	s_barrier
	s_add_u32 s30, s30, 0x20080
	s_addc_u32 s31, s31, 0
	s_mov_b32 m0, s50
	v_lshl_add_u64 v[2:3], s[30:31], 0, v[148:149]
	global_load_lds_dwordx4 v[2:3], off
	v_lshl_add_u64 v[2:3], s[30:31], 0, v[146:147]
	s_mov_b32 m0, s51
	s_nop 0
	global_load_lds_dwordx4 v[2:3], off
	s_waitcnt vmcnt(6)
	s_barrier
	s_setprio 1
	v_mfma_f32_16x16x128_f8f6f4 v[66:69], v[220:227], v[186:193], v[66:69]
	v_mfma_f32_16x16x128_f8f6f4 v[58:61], v[228:235], v[186:193], v[58:61]
	v_mfma_f32_16x16x128_f8f6f4 v[50:53], v[220:227], v[194:201], v[50:53]
	v_mfma_f32_16x16x128_f8f6f4 v[42:45], v[228:235], v[194:201], v[42:45]
	v_mfma_f32_16x16x128_f8f6f4 v[34:37], v[220:227], v[202:209], v[34:37]
	v_mfma_f32_16x16x128_f8f6f4 v[26:29], v[228:235], v[202:209], v[26:29]
	v_mfma_f32_16x16x128_f8f6f4 v[22:25], v[220:227], v[210:217], v[22:25]
	v_mfma_f32_16x16x128_f8f6f4 v[18:21], v[228:235], v[210:217], v[18:21]
	s_setprio 0
	s_add_i32 s68, s68, 2
	s_add_u32 s64, s64, 0x100
	s_addc_u32 s65, s65, 0
	s_add_u32 s28, s28, 0x100
	s_addc_u32 s29, s29, 0
	s_cmp_gt_u32 s68, 5
	s_barrier
	s_cbranch_scc0 .LBB0_648
	v_bfe_u32 v160, v0, 4, 1
	v_mul_u32_u24_e32 v160, 24, v160
	v_mov_b32_e32 v161, 0
	v_lshl_or_b32 v4, s55, 8, v183
	v_pk_mul_f32 v[2:3], v[144:145], s[16:17] op_sel_hi:[1,0]
	v_pk_mul_f32 v[6:7], v[142:143], s[16:17] op_sel_hi:[1,0]
	v_lshl_add_u32 v12, s26, 8, v166
	v_cvt_pk_bf16_f32 v6, v6, v7
	v_cvt_pk_bf16_f32 v7, v2, v3
	v_mov_b64_e32 v[2:3], s[10:11]
	v_ashrrev_i32_e32 v5, 31, v4
	v_mad_i64_i32 v[8:9], s[28:29], v12, s53, v[2:3]
	v_lshlrev_b64 v[4:5], 1, v[4:5]
	v_lshl_add_u64 v[8:9], v[8:9], 0, v[4:5]
	s_nop 15
	s_nop 15
	v_mov_b32_e32 v188, v6
	v_mov_b32_e32 v189, v7
	v_pk_mul_f32 v[6:7], v[140:141], s[16:17] op_sel_hi:[1,0]
	v_pk_mul_f32 v[10:11], v[138:139], s[16:17] op_sel_hi:[1,0]
	s_and_b64 vcc, exec, s[6:7]
	v_cvt_pk_bf16_f32 v10, v10, v11
	v_cvt_pk_bf16_f32 v11, v6, v7
	v_mov_b32_e32 v190, v10
	v_mov_b32_e32 v191, v11
	v_lshl_add_u64 v[162:163], v[8:9], 0, v[160:161]
	s_nop 0
	v_permlane16_swap_b32 v188, v190
	v_permlane16_swap_b32 v189, v191
	global_store_dwordx4 v[162:163], v[188:191], off
	v_pk_mul_f32 v[6:7], v[132:133], s[16:17] op_sel_hi:[1,0]
	v_pk_mul_f32 v[10:11], v[130:131], s[16:17] op_sel_hi:[1,0]
	s_mov_b32 s55, s18
	v_cvt_pk_bf16_f32 v10, v10, v11
	v_cvt_pk_bf16_f32 v11, v6, v7
	v_mov_b32_e32 v192, v10
	v_mov_b32_e32 v193, v11
	v_pk_mul_f32 v[6:7], v[124:125], s[16:17] op_sel_hi:[1,0]
	v_pk_mul_f32 v[10:11], v[122:123], s[16:17] op_sel_hi:[1,0]
	s_mov_b32 s26, s20
	v_cvt_pk_bf16_f32 v10, v10, v11
	v_cvt_pk_bf16_f32 v11, v6, v7
	v_mov_b32_e32 v194, v10
	v_mov_b32_e32 v195, v11
	v_lshl_add_u64 v[162:163], v[8:9], 0, v[160:161]
	s_nop 0
	v_permlane16_swap_b32 v192, v194
	v_permlane16_swap_b32 v193, v195
	global_store_dwordx4 v[162:163], v[192:195], off offset:256
	v_or_b32_e32 v10, 16, v12
	v_pk_mul_f32 v[6:7], v[136:137], s[16:17] op_sel_hi:[1,0]
	v_pk_mul_f32 v[8:9], v[134:135], s[16:17] op_sel_hi:[1,0]
	s_mov_b64 s[30:31], s[22:23]
	v_cvt_pk_bf16_f32 v8, v8, v9
	v_cvt_pk_bf16_f32 v9, v6, v7
	v_mad_i64_i32 v[6:7], s[28:29], v10, s53, v[2:3]
	v_lshl_add_u64 v[6:7], v[6:7], 0, v[4:5]
	v_mov_b32_e32 v196, v8
	v_mov_b32_e32 v197, v9
	v_pk_mul_f32 v[8:9], v[128:129], s[16:17] op_sel_hi:[1,0]
	v_pk_mul_f32 v[10:11], v[126:127], s[16:17] op_sel_hi:[1,0]
	s_nop 0
	v_cvt_pk_bf16_f32 v10, v10, v11
	v_cvt_pk_bf16_f32 v11, v8, v9
	v_mov_b32_e32 v198, v10
	v_mov_b32_e32 v199, v11
	v_lshl_add_u64 v[162:163], v[6:7], 0, v[160:161]
	s_nop 0
	v_permlane16_swap_b32 v196, v198
	v_permlane16_swap_b32 v197, v199
	global_store_dwordx4 v[162:163], v[196:199], off
	v_pk_mul_f32 v[8:9], v[116:117], s[16:17] op_sel_hi:[1,0]
	v_pk_mul_f32 v[10:11], v[114:115], s[16:17] op_sel_hi:[1,0]
	s_nop 0
	v_cvt_pk_bf16_f32 v10, v10, v11
	v_cvt_pk_bf16_f32 v11, v8, v9
	v_mov_b32_e32 v188, v10
	v_mov_b32_e32 v189, v11
	v_pk_mul_f32 v[8:9], v[108:109], s[16:17] op_sel_hi:[1,0]
	v_pk_mul_f32 v[10:11], v[106:107], s[16:17] op_sel_hi:[1,0]
	s_nop 0
	v_cvt_pk_bf16_f32 v10, v10, v11
	v_cvt_pk_bf16_f32 v11, v8, v9
	v_mov_b32_e32 v190, v10
	v_mov_b32_e32 v191, v11
	v_lshl_add_u64 v[162:163], v[6:7], 0, v[160:161]
	s_nop 0
	v_permlane16_swap_b32 v188, v190
	v_permlane16_swap_b32 v189, v191
	global_store_dwordx4 v[162:163], v[188:191], off offset:256
	v_or_b32_e32 v10, 32, v12
	v_pk_mul_f32 v[6:7], v[120:121], s[16:17] op_sel_hi:[1,0]
	v_pk_mul_f32 v[8:9], v[118:119], s[16:17] op_sel_hi:[1,0]
	s_nop 0
	v_cvt_pk_bf16_f32 v8, v8, v9
	v_cvt_pk_bf16_f32 v9, v6, v7
	v_mad_i64_i32 v[6:7], s[28:29], v10, s53, v[2:3]
	v_lshl_add_u64 v[6:7], v[6:7], 0, v[4:5]
	v_mov_b32_e32 v192, v8
	v_mov_b32_e32 v193, v9
	v_pk_mul_f32 v[8:9], v[112:113], s[16:17] op_sel_hi:[1,0]
	v_pk_mul_f32 v[10:11], v[110:111], s[16:17] op_sel_hi:[1,0]
	s_nop 0
	v_cvt_pk_bf16_f32 v10, v10, v11
	v_cvt_pk_bf16_f32 v11, v8, v9
	v_mov_b32_e32 v194, v10
	v_mov_b32_e32 v195, v11
	v_lshl_add_u64 v[162:163], v[6:7], 0, v[160:161]
	s_nop 0
	v_permlane16_swap_b32 v192, v194
	v_permlane16_swap_b32 v193, v195
	global_store_dwordx4 v[162:163], v[192:195], off
	v_pk_mul_f32 v[8:9], v[100:101], s[16:17] op_sel_hi:[1,0]
	v_pk_mul_f32 v[10:11], v[98:99], s[16:17] op_sel_hi:[1,0]
	s_nop 0
	v_cvt_pk_bf16_f32 v10, v10, v11
	v_cvt_pk_bf16_f32 v11, v8, v9
	v_mov_b32_e32 v196, v10
	v_mov_b32_e32 v197, v11
	v_pk_mul_f32 v[8:9], v[92:93], s[16:17] op_sel_hi:[1,0]
	v_pk_mul_f32 v[10:11], v[90:91], s[16:17] op_sel_hi:[1,0]
	s_nop 0
	v_cvt_pk_bf16_f32 v10, v10, v11
	v_cvt_pk_bf16_f32 v11, v8, v9
	v_mov_b32_e32 v198, v10
	v_mov_b32_e32 v199, v11
	v_lshl_add_u64 v[162:163], v[6:7], 0, v[160:161]
	s_nop 0
	v_permlane16_swap_b32 v196, v198
	v_permlane16_swap_b32 v197, v199
	global_store_dwordx4 v[162:163], v[196:199], off offset:256
	v_or_b32_e32 v10, 48, v12
	v_pk_mul_f32 v[6:7], v[104:105], s[16:17] op_sel_hi:[1,0]
	v_pk_mul_f32 v[8:9], v[102:103], s[16:17] op_sel_hi:[1,0]
	s_nop 0
	v_cvt_pk_bf16_f32 v8, v8, v9
	v_cvt_pk_bf16_f32 v9, v6, v7
	v_mad_i64_i32 v[6:7], s[28:29], v10, s53, v[2:3]
	v_lshl_add_u64 v[6:7], v[6:7], 0, v[4:5]
	v_mov_b32_e32 v188, v8
	v_mov_b32_e32 v189, v9
	v_pk_mul_f32 v[8:9], v[96:97], s[16:17] op_sel_hi:[1,0]
	v_pk_mul_f32 v[10:11], v[94:95], s[16:17] op_sel_hi:[1,0]
	s_nop 0
	v_cvt_pk_bf16_f32 v10, v10, v11
	v_cvt_pk_bf16_f32 v11, v8, v9
	v_mov_b32_e32 v190, v10
	v_mov_b32_e32 v191, v11
	v_lshl_add_u64 v[162:163], v[6:7], 0, v[160:161]
	s_nop 0
	v_permlane16_swap_b32 v188, v190
	v_permlane16_swap_b32 v189, v191
	global_store_dwordx4 v[162:163], v[188:191], off
	v_pk_mul_f32 v[8:9], v[88:89], s[16:17] op_sel_hi:[1,0]
	v_pk_mul_f32 v[10:11], v[86:87], s[16:17] op_sel_hi:[1,0]
	s_nop 0
	v_cvt_pk_bf16_f32 v10, v10, v11
	v_cvt_pk_bf16_f32 v11, v8, v9
	v_mov_b32_e32 v192, v10
	v_mov_b32_e32 v193, v11
	v_pk_mul_f32 v[8:9], v[84:85], s[16:17] op_sel_hi:[1,0]
	v_pk_mul_f32 v[10:11], v[82:83], s[16:17] op_sel_hi:[1,0]
	s_nop 0
	v_cvt_pk_bf16_f32 v10, v10, v11
	v_cvt_pk_bf16_f32 v11, v8, v9
	v_mov_b32_e32 v194, v10
	v_mov_b32_e32 v195, v11
	v_lshl_add_u64 v[162:163], v[6:7], 0, v[160:161]
	s_nop 0
	v_permlane16_swap_b32 v192, v194
	v_permlane16_swap_b32 v193, v195
	global_store_dwordx4 v[162:163], v[192:195], off offset:256
	v_add_u32_e32 v10, 0x80, v12
	v_pk_mul_f32 v[6:7], v[80:81], s[16:17] op_sel_hi:[1,0]
	v_pk_mul_f32 v[8:9], v[78:79], s[16:17] op_sel_hi:[1,0]
	s_nop 0
	v_cvt_pk_bf16_f32 v8, v8, v9
	v_cvt_pk_bf16_f32 v9, v6, v7
	v_mad_i64_i32 v[6:7], s[28:29], v10, s53, v[2:3]
	v_lshl_add_u64 v[6:7], v[6:7], 0, v[4:5]
	v_mov_b32_e32 v196, v8
	v_mov_b32_e32 v197, v9
	v_pk_mul_f32 v[8:9], v[76:77], s[16:17] op_sel_hi:[1,0]
	v_pk_mul_f32 v[10:11], v[74:75], s[16:17] op_sel_hi:[1,0]
	s_nop 0
	v_cvt_pk_bf16_f32 v10, v10, v11
	v_cvt_pk_bf16_f32 v11, v8, v9
	v_mov_b32_e32 v198, v10
	v_mov_b32_e32 v199, v11
	v_lshl_add_u64 v[162:163], v[6:7], 0, v[160:161]
	s_nop 0
	v_permlane16_swap_b32 v196, v198
	v_permlane16_swap_b32 v197, v199
	global_store_dwordx4 v[162:163], v[196:199], off
	v_pk_mul_f32 v[8:9], v[68:69], s[16:17] op_sel_hi:[1,0]
	v_pk_mul_f32 v[10:11], v[66:67], s[16:17] op_sel_hi:[1,0]
	s_nop 0
	v_cvt_pk_bf16_f32 v10, v10, v11
	v_cvt_pk_bf16_f32 v11, v8, v9
	v_mov_b32_e32 v188, v10
	v_mov_b32_e32 v189, v11
	v_pk_mul_f32 v[8:9], v[60:61], s[16:17] op_sel_hi:[1,0]
	v_pk_mul_f32 v[10:11], v[58:59], s[16:17] op_sel_hi:[1,0]
	s_nop 0
	v_cvt_pk_bf16_f32 v10, v10, v11
	v_cvt_pk_bf16_f32 v11, v8, v9
	v_mov_b32_e32 v190, v10
	v_mov_b32_e32 v191, v11
	v_lshl_add_u64 v[162:163], v[6:7], 0, v[160:161]
	s_nop 0
	v_permlane16_swap_b32 v188, v190
	v_permlane16_swap_b32 v189, v191
	global_store_dwordx4 v[162:163], v[188:191], off offset:256
	v_add_u32_e32 v10, 0x90, v12
	v_pk_mul_f32 v[6:7], v[72:73], s[16:17] op_sel_hi:[1,0]
	v_pk_mul_f32 v[8:9], v[70:71], s[16:17] op_sel_hi:[1,0]
	s_nop 0
	v_cvt_pk_bf16_f32 v8, v8, v9
	v_cvt_pk_bf16_f32 v9, v6, v7
	v_mad_i64_i32 v[6:7], s[28:29], v10, s53, v[2:3]
	v_lshl_add_u64 v[6:7], v[6:7], 0, v[4:5]
	v_mov_b32_e32 v192, v8
	v_mov_b32_e32 v193, v9
	v_pk_mul_f32 v[8:9], v[64:65], s[16:17] op_sel_hi:[1,0]
	v_pk_mul_f32 v[10:11], v[62:63], s[16:17] op_sel_hi:[1,0]
	s_nop 0
	v_cvt_pk_bf16_f32 v10, v10, v11
	v_cvt_pk_bf16_f32 v11, v8, v9
	v_mov_b32_e32 v194, v10
	v_mov_b32_e32 v195, v11
	v_lshl_add_u64 v[162:163], v[6:7], 0, v[160:161]
	s_nop 0
	v_permlane16_swap_b32 v192, v194
	v_permlane16_swap_b32 v193, v195
	global_store_dwordx4 v[162:163], v[192:195], off
	v_pk_mul_f32 v[8:9], v[52:53], s[16:17] op_sel_hi:[1,0]
	v_pk_mul_f32 v[10:11], v[50:51], s[16:17] op_sel_hi:[1,0]
	s_nop 0
	v_cvt_pk_bf16_f32 v10, v10, v11
	v_cvt_pk_bf16_f32 v11, v8, v9
	v_mov_b32_e32 v196, v10
	v_mov_b32_e32 v197, v11
	v_pk_mul_f32 v[8:9], v[44:45], s[16:17] op_sel_hi:[1,0]
	v_pk_mul_f32 v[10:11], v[42:43], s[16:17] op_sel_hi:[1,0]
	s_nop 0
	v_cvt_pk_bf16_f32 v10, v10, v11
	v_cvt_pk_bf16_f32 v11, v8, v9
	v_mov_b32_e32 v198, v10
	v_mov_b32_e32 v199, v11
	v_lshl_add_u64 v[162:163], v[6:7], 0, v[160:161]
	s_nop 0
	v_permlane16_swap_b32 v196, v198
	v_permlane16_swap_b32 v197, v199
	global_store_dwordx4 v[162:163], v[196:199], off offset:256
	v_add_u32_e32 v10, 0xa0, v12
	v_pk_mul_f32 v[6:7], v[56:57], s[16:17] op_sel_hi:[1,0]
	v_pk_mul_f32 v[8:9], v[54:55], s[16:17] op_sel_hi:[1,0]
	s_nop 0
	v_cvt_pk_bf16_f32 v8, v8, v9
	v_cvt_pk_bf16_f32 v9, v6, v7
	v_mad_i64_i32 v[6:7], s[28:29], v10, s53, v[2:3]
	v_lshl_add_u64 v[6:7], v[6:7], 0, v[4:5]
	v_mov_b32_e32 v188, v8
	v_mov_b32_e32 v189, v9
	v_pk_mul_f32 v[8:9], v[48:49], s[16:17] op_sel_hi:[1,0]
	v_pk_mul_f32 v[10:11], v[46:47], s[16:17] op_sel_hi:[1,0]
	s_nop 0
	v_cvt_pk_bf16_f32 v10, v10, v11
	v_cvt_pk_bf16_f32 v11, v8, v9
	v_mov_b32_e32 v190, v10
	v_mov_b32_e32 v191, v11
	v_lshl_add_u64 v[162:163], v[6:7], 0, v[160:161]
	s_nop 0
	v_permlane16_swap_b32 v188, v190
	v_permlane16_swap_b32 v189, v191
	global_store_dwordx4 v[162:163], v[188:191], off
	v_pk_mul_f32 v[8:9], v[36:37], s[16:17] op_sel_hi:[1,0]
	v_pk_mul_f32 v[10:11], v[34:35], s[16:17] op_sel_hi:[1,0]
	s_nop 0
	v_cvt_pk_bf16_f32 v10, v10, v11
	v_cvt_pk_bf16_f32 v11, v8, v9
	v_mov_b32_e32 v192, v10
	v_mov_b32_e32 v193, v11
	v_pk_mul_f32 v[8:9], v[28:29], s[16:17] op_sel_hi:[1,0]
	v_pk_mul_f32 v[10:11], v[26:27], s[16:17] op_sel_hi:[1,0]
	s_nop 0
	v_cvt_pk_bf16_f32 v10, v10, v11
	v_cvt_pk_bf16_f32 v11, v8, v9
	v_mov_b32_e32 v194, v10
	v_mov_b32_e32 v195, v11
	v_lshl_add_u64 v[162:163], v[6:7], 0, v[160:161]
	s_nop 0
	v_permlane16_swap_b32 v192, v194
	v_permlane16_swap_b32 v193, v195
	global_store_dwordx4 v[162:163], v[192:195], off offset:256
	v_add_u32_e32 v10, 0xb0, v12
	v_pk_mul_f32 v[6:7], v[40:41], s[16:17] op_sel_hi:[1,0]
	v_pk_mul_f32 v[8:9], v[38:39], s[16:17] op_sel_hi:[1,0]
	v_mad_i64_i32 v[2:3], s[28:29], v10, s53, v[2:3]
	v_cvt_pk_bf16_f32 v8, v8, v9
	v_cvt_pk_bf16_f32 v9, v6, v7
	v_lshl_add_u64 v[2:3], v[2:3], 0, v[4:5]
	v_pk_mul_f32 v[4:5], v[32:33], s[16:17] op_sel_hi:[1,0]
	v_pk_mul_f32 v[6:7], v[30:31], s[16:17] op_sel_hi:[1,0]
	s_mov_b64 s[28:29], s[24:25]
	v_cvt_pk_bf16_f32 v6, v6, v7
	v_cvt_pk_bf16_f32 v7, v4, v5
	v_mov_b32_e32 v198, v6
	v_mov_b32_e32 v199, v7
	v_pk_mul_f32 v[4:5], v[24:25], s[16:17] op_sel_hi:[1,0]
	v_pk_mul_f32 v[6:7], v[22:23], s[16:17] op_sel_hi:[1,0]
	v_mov_b32_e32 v196, v8
	v_mov_b32_e32 v197, v9
	v_lshl_add_u64 v[162:163], v[2:3], 0, v[160:161]
	s_nop 0
	v_permlane16_swap_b32 v196, v198
	v_permlane16_swap_b32 v197, v199
	global_store_dwordx4 v[162:163], v[196:199], off
	v_cvt_pk_bf16_f32 v6, v6, v7
	v_cvt_pk_bf16_f32 v7, v4, v5
	v_mov_b32_e32 v188, v6
	v_mov_b32_e32 v189, v7
	v_pk_mul_f32 v[4:5], v[20:21], s[16:17] op_sel_hi:[1,0]
	v_pk_mul_f32 v[6:7], v[18:19], s[16:17] op_sel_hi:[1,0]
	s_nop 0
	v_cvt_pk_bf16_f32 v6, v6, v7
	v_cvt_pk_bf16_f32 v7, v4, v5
	v_mov_b32_e32 v190, v6
	v_mov_b32_e32 v191, v7
	v_lshl_add_u64 v[162:163], v[2:3], 0, v[160:161]
	s_nop 0
	v_permlane16_swap_b32 v188, v190
	v_permlane16_swap_b32 v189, v191
	global_store_dwordx4 v[162:163], v[188:191], off offset:256
	s_cbranch_vccz .LBB0_645
	s_waitcnt vmcnt(0)
	s_cmpk_gt_u32 s3, 0xff
	v_readlane_b32 s2, v252, 8
	s_cbranch_scc1 .LBB0_652
	s_barrier

.LBB0_1551:
	ds_read_b128 v[2:5], v167
	ds_read_b128 v[6:9], v171
	ds_read_b128 v[10:13], v172
	ds_read_b128 v[14:17], v173
	s_add_u32 s40, s38, 0xfffe0080
	s_addc_u32 s41, s39, -1
	s_cmp_eq_u32 s77, 4
	s_cselect_b32 s43, s29, s41
	s_cselect_b32 s42, s73, s40
	s_cselect_b32 s41, s27, s76
	s_cselect_b32 s40, s74, s75
	v_lshl_add_u64 v[158:159], s[38:39], 0, v[152:153]
	s_add_i32 m0, s37, 0xc000
	ds_read_b128 v[186:189], v184
	ds_read_b128 v[190:193], v184 offset:1024
	ds_read_b128 v[194:197], v184 offset:2048
	ds_read_b128 v[198:201], v184 offset:3072
	ds_read_b128 v[202:205], v184 offset:4096
	ds_read_b128 v[206:209], v184 offset:5120
	ds_read_b128 v[210:213], v184 offset:6144
	ds_read_b128 v[214:217], v184 offset:7168
	global_load_lds_dwordx4 v[158:159], off
	v_lshl_add_u64 v[158:159], s[38:39], 0, v[150:151]
	s_add_i32 m0, s37, 0xe000
	s_nop 0
	global_load_lds_dwordx4 v[158:159], off
	s_waitcnt lgkmcnt(8)
	s_barrier
	s_waitcnt lgkmcnt(0)
	s_setprio 1
	s_waitcnt lgkmcnt(0)
	v_mfma_f32_16x16x128_f8f6f4 v[142:145], v[2:9], v[186:193], v[142:145]
	v_mfma_f32_16x16x128_f8f6f4 v[138:141], v[10:17], v[186:193], v[138:141]
	v_mfma_f32_16x16x128_f8f6f4 v[126:129], v[2:9], v[194:201], v[126:129]
	v_mfma_f32_16x16x128_f8f6f4 v[122:125], v[10:17], v[194:201], v[122:125]
	v_mfma_f32_16x16x128_f8f6f4 v[110:113], v[2:9], v[202:209], v[110:113]
	v_mfma_f32_16x16x128_f8f6f4 v[106:109], v[10:17], v[202:209], v[106:109]
	v_mfma_f32_16x16x128_f8f6f4 v[94:97], v[2:9], v[210:217], v[94:97]
	v_mfma_f32_16x16x128_f8f6f4 v[90:93], v[10:17], v[210:217], v[90:93]
	s_setprio 0
	s_barrier
	s_mov_b32 m0, s45
	v_lshl_add_u64 v[158:159], s[40:41], 0, v[148:149]
	ds_read_b128 v[220:223], v168
	ds_read_b128 v[224:227], v174
	ds_read_b128 v[228:231], v175
	ds_read_b128 v[232:235], v176
	global_load_lds_dwordx4 v[158:159], off
	v_lshl_add_u64 v[160:161], s[40:41], 0, v[146:147]
	s_mov_b32 m0, s46
	s_nop 0
	global_load_lds_dwordx4 v[160:161], off
	s_barrier
	s_waitcnt lgkmcnt(0)
	s_setprio 1
	s_waitcnt lgkmcnt(0)
	v_mfma_f32_16x16x128_f8f6f4 v[134:137], v[220:227], v[186:193], v[134:137]
	v_mfma_f32_16x16x128_f8f6f4 v[130:133], v[228:235], v[186:193], v[130:133]
	v_mfma_f32_16x16x128_f8f6f4 v[118:121], v[220:227], v[194:201], v[118:121]
	v_mfma_f32_16x16x128_f8f6f4 v[114:117], v[228:235], v[194:201], v[114:117]
	v_mfma_f32_16x16x128_f8f6f4 v[102:105], v[220:227], v[202:209], v[102:105]
	v_mfma_f32_16x16x128_f8f6f4 v[98:101], v[228:235], v[202:209], v[98:101]
	v_mfma_f32_16x16x128_f8f6f4 v[86:89], v[220:227], v[210:217], v[86:89]
	v_mfma_f32_16x16x128_f8f6f4 v[82:85], v[228:235], v[210:217], v[82:85]
	s_setprio 0
	s_mov_b32 m0, s37
	v_lshl_add_u64 v[162:163], s[42:43], 0, v[148:149]
	s_barrier
	ds_read_b128 v[186:189], v184 offset:16384
	ds_read_b128 v[190:193], v184 offset:17408
	ds_read_b128 v[194:197], v184 offset:18432
	ds_read_b128 v[198:201], v184 offset:19456
	ds_read_b128 v[202:205], v184 offset:20480
	ds_read_b128 v[206:209], v184 offset:21504
	ds_read_b128 v[210:213], v184 offset:22528
	ds_read_b128 v[214:217], v184 offset:23552
	global_load_lds_dwordx4 v[162:163], off
	v_lshl_add_u64 v[164:165], s[42:43], 0, v[146:147]
	s_mov_b32 m0, s47
	s_nop 0
	global_load_lds_dwordx4 v[164:165], off
	s_barrier
	s_waitcnt lgkmcnt(0)
	s_setprio 1
	s_waitcnt lgkmcnt(0)
	v_mfma_f32_16x16x128_f8f6f4 v[78:81], v[2:9], v[186:193], v[78:81]
	v_mfma_f32_16x16x128_f8f6f4 v[74:77], v[10:17], v[186:193], v[74:77]
	v_mfma_f32_16x16x128_f8f6f4 v[62:65], v[2:9], v[194:201], v[62:65]
	v_mfma_f32_16x16x128_f8f6f4 v[58:61], v[10:17], v[194:201], v[58:61]
	v_mfma_f32_16x16x128_f8f6f4 v[46:49], v[2:9], v[202:209], v[46:49]
	v_mfma_f32_16x16x128_f8f6f4 v[42:45], v[10:17], v[202:209], v[42:45]
	v_mfma_f32_16x16x128_f8f6f4 v[30:33], v[2:9], v[210:217], v[30:33]
	v_mfma_f32_16x16x128_f8f6f4 v[26:29], v[10:17], v[210:217], v[26:29]
	s_setprio 0
	s_barrier
	s_add_u32 s66, s40, 0x20000
	s_addc_u32 s67, s41, 0
	s_mov_b32 m0, s48
	v_lshl_add_u64 v[2:3], s[66:67], 0, v[148:149]
	global_load_lds_dwordx4 v[2:3], off
	v_lshl_add_u64 v[2:3], s[66:67], 0, v[146:147]
	s_mov_b32 m0, s49
	s_nop 0
	global_load_lds_dwordx4 v[2:3], off
	s_waitcnt vmcnt(6)
	s_barrier
	s_setprio 1
	v_mfma_f32_16x16x128_f8f6f4 v[70:73], v[220:227], v[186:193], v[70:73]
	v_mfma_f32_16x16x128_f8f6f4 v[66:69], v[228:235], v[186:193], v[66:69]
	v_mfma_f32_16x16x128_f8f6f4 v[54:57], v[220:227], v[194:201], v[54:57]
	v_mfma_f32_16x16x128_f8f6f4 v[50:53], v[228:235], v[194:201], v[50:53]
	v_mfma_f32_16x16x128_f8f6f4 v[38:41], v[220:227], v[202:209], v[38:41]
	v_mfma_f32_16x16x128_f8f6f4 v[34:37], v[228:235], v[202:209], v[34:37]
	v_mfma_f32_16x16x128_f8f6f4 v[22:25], v[220:227], v[210:217], v[22:25]
	v_mfma_f32_16x16x128_f8f6f4 v[18:21], v[228:235], v[210:217], v[18:21]
	s_setprio 0
	s_barrier
	ds_read_b128 v[2:5], v169
	ds_read_b128 v[6:9], v177
	ds_read_b128 v[10:13], v178
	ds_read_b128 v[14:17], v179
	s_add_u32 s42, s42, 0x20000
	s_addc_u32 s43, s43, 0
	s_mov_b32 m0, s50
	v_lshl_add_u64 v[220:221], s[42:43], 0, v[148:149]
	ds_read_b128 v[186:189], v184 offset:32768
	ds_read_b128 v[190:193], v184 offset:33792
	ds_read_b128 v[194:197], v184 offset:34816
	ds_read_b128 v[198:201], v184 offset:35840
	ds_read_b128 v[202:205], v184 offset:36864
	ds_read_b128 v[206:209], v184 offset:37888
	ds_read_b128 v[210:213], v184 offset:38912
	ds_read_b128 v[214:217], v184 offset:39936
	global_load_lds_dwordx4 v[220:221], off
	v_lshl_add_u64 v[220:221], s[42:43], 0, v[146:147]
	s_mov_b32 m0, s51
	s_nop 0
	global_load_lds_dwordx4 v[220:221], off
	s_waitcnt lgkmcnt(8)
	s_barrier
	s_waitcnt lgkmcnt(0)
	s_setprio 1
	s_waitcnt lgkmcnt(0)
	v_mfma_f32_16x16x128_f8f6f4 v[142:145], v[2:9], v[186:193], v[142:145]
	v_mfma_f32_16x16x128_f8f6f4 v[138:141], v[10:17], v[186:193], v[138:141]
	v_mfma_f32_16x16x128_f8f6f4 v[126:129], v[2:9], v[194:201], v[126:129]
	v_mfma_f32_16x16x128_f8f6f4 v[122:125], v[10:17], v[194:201], v[122:125]
	v_mfma_f32_16x16x128_f8f6f4 v[110:113], v[2:9], v[202:209], v[110:113]
	v_mfma_f32_16x16x128_f8f6f4 v[106:109], v[10:17], v[202:209], v[106:109]
	v_mfma_f32_16x16x128_f8f6f4 v[94:97], v[2:9], v[210:217], v[94:97]
	v_mfma_f32_16x16x128_f8f6f4 v[90:93], v[10:17], v[210:217], v[90:93]
	s_setprio 0
	s_barrier
	s_mov_b32 m0, s53
	v_lshl_add_u64 v[158:159], v[158:159], 0, s[20:21]
	ds_read_b128 v[220:223], v170
	ds_read_b128 v[224:227], v180
	ds_read_b128 v[228:231], v181
	ds_read_b128 v[232:235], v182
	global_load_lds_dwordx4 v[158:159], off
	v_lshl_add_u64 v[158:159], v[160:161], 0, s[20:21]
	s_mov_b32 m0, s55
	s_nop 0
	global_load_lds_dwordx4 v[158:159], off
	s_barrier
	s_waitcnt lgkmcnt(0)
	s_setprio 1
	s_waitcnt lgkmcnt(0)
	v_mfma_f32_16x16x128_f8f6f4 v[134:137], v[220:227], v[186:193], v[134:137]
	v_mfma_f32_16x16x128_f8f6f4 v[130:133], v[228:235], v[186:193], v[130:133]
	v_mfma_f32_16x16x128_f8f6f4 v[118:121], v[220:227], v[194:201], v[118:121]
	v_mfma_f32_16x16x128_f8f6f4 v[114:117], v[228:235], v[194:201], v[114:117]
	v_mfma_f32_16x16x128_f8f6f4 v[102:105], v[220:227], v[202:209], v[102:105]
	v_mfma_f32_16x16x128_f8f6f4 v[98:101], v[228:235], v[202:209], v[98:101]
	v_mfma_f32_16x16x128_f8f6f4 v[86:89], v[220:227], v[210:217], v[86:89]
	v_mfma_f32_16x16x128_f8f6f4 v[82:85], v[228:235], v[210:217], v[82:85]
	s_setprio 0
	s_mov_b32 m0, s64
	v_lshl_add_u64 v[158:159], v[162:163], 0, s[20:21]
	s_barrier
	ds_read_b128 v[186:189], v184 offset:49152
	ds_read_b128 v[190:193], v184 offset:50176
	ds_read_b128 v[194:197], v184 offset:51200
	ds_read_b128 v[198:201], v184 offset:52224
	ds_read_b128 v[202:205], v184 offset:53248
	ds_read_b128 v[206:209], v184 offset:54272
	ds_read_b128 v[210:213], v184 offset:55296
	ds_read_b128 v[214:217], v184 offset:56320
	global_load_lds_dwordx4 v[158:159], off
	v_lshl_add_u64 v[158:159], v[164:165], 0, s[20:21]
	s_mov_b32 m0, s65
	s_nop 0
	global_load_lds_dwordx4 v[158:159], off
	s_barrier
	s_waitcnt lgkmcnt(0)
	s_setprio 1
	s_waitcnt lgkmcnt(0)
	v_mfma_f32_16x16x128_f8f6f4 v[78:81], v[2:9], v[186:193], v[78:81]
	v_mfma_f32_16x16x128_f8f6f4 v[74:77], v[10:17], v[186:193], v[74:77]
	v_mfma_f32_16x16x128_f8f6f4 v[62:65], v[2:9], v[194:201], v[62:65]
	v_mfma_f32_16x16x128_f8f6f4 v[58:61], v[10:17], v[194:201], v[58:61]
	v_mfma_f32_16x16x128_f8f6f4 v[46:49], v[2:9], v[202:209], v[46:49]
	v_mfma_f32_16x16x128_f8f6f4 v[42:45], v[10:17], v[202:209], v[42:45]
	v_mfma_f32_16x16x128_f8f6f4 v[30:33], v[2:9], v[210:217], v[30:33]
	v_mfma_f32_16x16x128_f8f6f4 v[26:29], v[10:17], v[210:217], v[26:29]
	s_setprio 0
	s_barrier
	s_add_u32 s40, s40, 0x20080
	s_addc_u32 s41, s41, 0
	s_mov_b32 m0, s68
	v_lshl_add_u64 v[2:3], s[40:41], 0, v[148:149]
	global_load_lds_dwordx4 v[2:3], off
	v_lshl_add_u64 v[2:3], s[40:41], 0, v[146:147]
	s_mov_b32 m0, s69
	s_nop 0
	global_load_lds_dwordx4 v[2:3], off
	s_waitcnt vmcnt(6)
	s_barrier
	s_setprio 1
	v_mfma_f32_16x16x128_f8f6f4 v[70:73], v[220:227], v[186:193], v[70:73]
	v_mfma_f32_16x16x128_f8f6f4 v[66:69], v[228:235], v[186:193], v[66:69]
	v_mfma_f32_16x16x128_f8f6f4 v[54:57], v[220:227], v[194:201], v[54:57]
	v_mfma_f32_16x16x128_f8f6f4 v[50:53], v[228:235], v[194:201], v[50:53]
	v_mfma_f32_16x16x128_f8f6f4 v[38:41], v[220:227], v[202:209], v[38:41]
	v_mfma_f32_16x16x128_f8f6f4 v[34:37], v[228:235], v[202:209], v[34:37]
	v_mfma_f32_16x16x128_f8f6f4 v[22:25], v[220:227], v[210:217], v[22:25]
	v_mfma_f32_16x16x128_f8f6f4 v[18:21], v[228:235], v[210:217], v[18:21]
	s_setprio 0
	s_add_i32 s77, s77, 2
	s_add_u32 s75, s75, 0x100
	s_addc_u32 s76, s76, 0
	s_add_u32 s38, s38, 0x100
	s_addc_u32 s39, s39, 0
	s_cmp_gt_u32 s77, 5
	s_barrier
	s_cbranch_scc0 .LBB0_1551
	v_bfe_u32 v192, v0, 4, 1
	v_mul_u32_u24_e32 v192, 24, v192
	v_mov_b32_e32 v193, 0
	v_lshl_or_b32 v10, s72, 8, v183
	v_ashrrev_i32_e32 v11, 31, v10
	s_nop 15
	s_nop 15
	v_lshl_add_u64 v[14:15], v[10:11], 2, s[16:17]
	global_load_dwordx4 v[158:161], v[14:15], off
	global_load_dwordx4 v[162:165], v[14:15], off offset:64
	global_load_dwordx4 v[6:9], v[14:15], off offset:512
	global_load_dwordx4 v[2:5], v[14:15], off offset:576
	v_lshl_add_u32 v16, s36, 8, v166
	v_mov_b64_e32 v[12:13], s[14:15]
	v_mad_i64_i32 v[186:187], s[38:39], v16, s71, v[12:13]
	v_lshlrev_b64 v[10:11], 1, v[10:11]
	v_lshl_add_u64 v[186:187], v[186:187], 0, v[10:11]
	s_and_b64 vcc, exec, s[10:11]
	s_mov_b32 s72, s26
	s_mov_b32 s36, s28
	s_mov_b64 s[40:41], s[30:31]
	s_waitcnt vmcnt(0)
	v_pk_fma_f32 v[144:145], v[144:145], s[22:23], v[160:161] op_sel_hi:[1,0,1]
	v_pk_fma_f32 v[142:143], v[142:143], s[22:23], v[158:159] op_sel_hi:[1,0,1]
	v_pk_fma_f32 v[140:141], v[140:141], s[22:23], v[164:165] op_sel_hi:[1,0,1]
	v_pk_fma_f32 v[138:139], v[138:139], s[22:23], v[162:163] op_sel_hi:[1,0,1]
	v_pk_fma_f32 v[136:137], v[136:137], s[22:23], v[8:9] op_sel_hi:[1,0,1]
	v_pk_fma_f32 v[134:135], v[134:135], s[22:23], v[6:7] op_sel_hi:[1,0,1]
	v_mul_f32_e32 v17, 0xbfb8aa3b, v142
	v_mul_f32_e32 v142, 0xbfb8aa3b, v143
	v_mul_f32_e32 v143, 0xbfb8aa3b, v144
	v_mul_f32_e32 v144, 0xbfb8aa3b, v145
	v_mul_f32_e32 v138, 0xbfb8aa3b, v138
	v_mul_f32_e32 v139, 0xbfb8aa3b, v139
	v_mul_f32_e32 v140, 0xbfb8aa3b, v140
	v_mul_f32_e32 v141, 0xbfb8aa3b, v141
	v_mul_f32_e32 v134, 0xbfb8aa3b, v134
	v_mul_f32_e32 v135, 0xbfb8aa3b, v135
	v_mul_f32_e32 v136, 0xbfb8aa3b, v136
	v_mul_f32_e32 v137, 0xbfb8aa3b, v137
	v_exp_f32_e32 v17, v17
	v_exp_f32_e32 v142, v142
	v_exp_f32_e32 v143, v143
	v_exp_f32_e32 v144, v144
	v_exp_f32_e32 v138, v138
	v_exp_f32_e32 v139, v139
	v_exp_f32_e32 v140, v140
	v_exp_f32_e32 v141, v141
	v_exp_f32_e32 v134, v134
	v_exp_f32_e32 v135, v135
	v_exp_f32_e32 v136, v136
	v_exp_f32_e32 v137, v137
	v_pk_fma_f32 v[130:131], v[130:131], s[22:23], v[2:3] op_sel_hi:[1,0,1]
	v_pk_fma_f32 v[132:133], v[132:133], s[22:23], v[4:5] op_sel_hi:[1,0,1]
	v_mul_f32_e32 v130, 0xbfb8aa3b, v130
	v_mul_f32_e32 v131, 0xbfb8aa3b, v131
	v_mul_f32_e32 v132, 0xbfb8aa3b, v132
	v_mul_f32_e32 v133, 0xbfb8aa3b, v133
	v_exp_f32_e32 v130, v130
	v_exp_f32_e32 v131, v131
	v_add_f32_e32 v17, 1.0, v17
	v_add_f32_e32 v142, 1.0, v142
	v_add_f32_e32 v143, 1.0, v143
	v_add_f32_e32 v144, 1.0, v144
	v_exp_f32_e32 v132, v132
	v_exp_f32_e32 v133, v133
	v_add_f32_e32 v138, 1.0, v138
	v_add_f32_e32 v139, 1.0, v139
	v_add_f32_e32 v140, 1.0, v140
	v_add_f32_e32 v141, 1.0, v141
	v_add_f32_e32 v134, 1.0, v134
	v_add_f32_e32 v135, 1.0, v135
	v_add_f32_e32 v136, 1.0, v136
	v_add_f32_e32 v137, 1.0, v137
	v_rcp_f32_e32 v17, v17
	v_rcp_f32_e32 v142, v142
	v_rcp_f32_e32 v143, v143
	v_rcp_f32_e32 v144, v144
	v_rcp_f32_e32 v138, v138
	v_rcp_f32_e32 v139, v139
	v_rcp_f32_e32 v140, v140
	v_rcp_f32_e32 v141, v141
	v_rcp_f32_e32 v134, v134
	v_rcp_f32_e32 v135, v135
	v_rcp_f32_e32 v136, v136
	v_rcp_f32_e32 v137, v137
	v_add_f32_e32 v130, 1.0, v130
	v_add_f32_e32 v131, 1.0, v131
	v_pk_fma_f32 v[126:127], v[126:127], s[22:23], v[158:159] op_sel_hi:[1,0,1]
	v_add_f32_e32 v132, 1.0, v132
	v_add_f32_e32 v133, 1.0, v133
	v_rcp_f32_e32 v145, v130
	v_rcp_f32_e32 v185, v131
	v_cvt_pk_bf16_f32 v130, v17, v142
	v_cvt_pk_bf16_f32 v131, v143, v144
	v_mul_f32_e32 v17, 0xbfb8aa3b, v126
	v_mul_f32_e32 v126, 0xbfb8aa3b, v127
	v_rcp_f32_e32 v188, v132
	v_rcp_f32_e32 v189, v133
	v_cvt_pk_bf16_f32 v132, v138, v139
	v_cvt_pk_bf16_f32 v133, v140, v141
	v_cvt_pk_bf16_f32 v134, v134, v135
	v_cvt_pk_bf16_f32 v135, v136, v137
	v_mov_b32_e32 v196, v130
	v_mov_b32_e32 v197, v131
	v_mov_b32_e32 v198, v132
	v_mov_b32_e32 v199, v133
	v_lshl_add_u64 v[194:195], v[186:187], 0, v[192:193]
	s_nop 0
	v_permlane16_swap_b32 v196, v198
	v_permlane16_swap_b32 v197, v199
	global_store_dwordx4 v[194:195], v[196:199], off
	v_mov_b32_e32 v200, v134
	v_mov_b32_e32 v201, v135
	v_exp_f32_e32 v130, v126
	v_pk_fma_f32 v[126:127], v[128:129], s[22:23], v[160:161] op_sel_hi:[1,0,1]
	v_exp_f32_e32 v17, v17
	v_mul_f32_e32 v126, 0xbfb8aa3b, v126
	v_exp_f32_e32 v126, v126
	v_mul_f32_e32 v127, 0xbfb8aa3b, v127
	v_exp_f32_e32 v127, v127
	v_add_f32_e32 v17, 1.0, v17
	v_add_f32_e32 v128, 1.0, v130
	v_add_f32_e32 v126, 1.0, v126
	v_rcp_f32_e32 v17, v17
	v_rcp_f32_e32 v128, v128
	v_rcp_f32_e32 v129, v126
	v_add_f32_e32 v126, 1.0, v127
	v_rcp_f32_e32 v127, v126
	v_pk_fma_f32 v[122:123], v[122:123], s[22:23], v[162:163] op_sel_hi:[1,0,1]
	v_or_b32_e32 v130, 16, v16
	v_cvt_pk_bf16_f32 v126, v17, v128
	v_mul_f32_e32 v17, 0xbfb8aa3b, v122
	v_mul_f32_e32 v122, 0xbfb8aa3b, v123
	v_cvt_pk_bf16_f32 v127, v129, v127
	v_mad_i64_i32 v[128:129], s[38:39], v130, s71, v[12:13]
	v_exp_f32_e32 v17, v17
	v_exp_f32_e32 v130, v122
	v_pk_fma_f32 v[122:123], v[124:125], s[22:23], v[164:165] op_sel_hi:[1,0,1]
	v_pk_fma_f32 v[6:7], v[118:119], s[22:23], v[6:7] op_sel_hi:[1,0,1]
	v_add_f32_e32 v17, 1.0, v17
	v_add_f32_e32 v124, 1.0, v130
	v_rcp_f32_e32 v17, v17
	v_rcp_f32_e32 v124, v124
	v_mul_f32_e32 v6, 0xbfb8aa3b, v6
	v_pk_fma_f32 v[2:3], v[114:115], s[22:23], v[2:3] op_sel_hi:[1,0,1]
	v_mul_f32_e32 v122, 0xbfb8aa3b, v122
	v_cvt_pk_bf16_f32 v124, v17, v124
	v_exp_f32_e32 v17, v6
	v_mul_f32_e32 v6, 0xbfb8aa3b, v7
	v_exp_f32_e32 v118, v6
	v_pk_fma_f32 v[6:7], v[120:121], s[22:23], v[8:9] op_sel_hi:[1,0,1]
	v_add_f32_e32 v8, 1.0, v17
	v_rcp_f32_e32 v8, v8
	v_add_f32_e32 v9, 1.0, v118
	v_rcp_f32_e32 v9, v9
	v_mul_f32_e32 v6, 0xbfb8aa3b, v6
	v_exp_f32_e32 v17, v6
	v_mul_f32_e32 v6, 0xbfb8aa3b, v7
	v_mul_f32_e32 v2, 0xbfb8aa3b, v2
	v_exp_f32_e32 v7, v6
	v_cvt_pk_bf16_f32 v6, v8, v9
	v_exp_f32_e32 v9, v2
	v_mul_f32_e32 v2, 0xbfb8aa3b, v3
	v_add_f32_e32 v8, 1.0, v17
	v_exp_f32_e32 v17, v2
	v_pk_fma_f32 v[2:3], v[116:117], s[22:23], v[4:5] op_sel_hi:[1,0,1]
	v_exp_f32_e32 v122, v122
	v_mul_f32_e32 v2, 0xbfb8aa3b, v2
	v_mul_f32_e32 v123, 0xbfb8aa3b, v123
	v_exp_f32_e32 v2, v2
	v_mul_f32_e32 v3, 0xbfb8aa3b, v3
	v_exp_f32_e32 v123, v123
	v_exp_f32_e32 v3, v3
	v_add_f32_e32 v122, 1.0, v122
	v_add_f32_e32 v2, 1.0, v2
	v_rcp_f32_e32 v125, v122
	v_add_f32_e32 v122, 1.0, v123
	v_add_f32_e32 v7, 1.0, v7
	v_add_f32_e32 v4, 1.0, v9
	v_add_f32_e32 v5, 1.0, v17
	v_rcp_f32_e32 v9, v2
	v_add_f32_e32 v2, 1.0, v3
	v_rcp_f32_e32 v130, v122
	v_rcp_f32_e32 v8, v8
	v_rcp_f32_e32 v7, v7
	v_rcp_f32_e32 v4, v4
	v_rcp_f32_e32 v5, v5
	v_rcp_f32_e32 v3, v2
	v_cvt_pk_bf16_f32 v136, v145, v185
	v_cvt_pk_bf16_f32 v137, v188, v189
	v_lshl_add_u64 v[122:123], v[128:129], 0, v[10:11]
	v_cvt_pk_bf16_f32 v125, v125, v130
	v_cvt_pk_bf16_f32 v7, v8, v7
	v_cvt_pk_bf16_f32 v2, v4, v5
	v_cvt_pk_bf16_f32 v3, v9, v3
	v_mov_b32_e32 v202, v136
	v_mov_b32_e32 v203, v137
	v_lshl_add_u64 v[194:195], v[186:187], 0, v[192:193]
	s_nop 0
	v_permlane16_swap_b32 v200, v202
	v_permlane16_swap_b32 v201, v203
	global_store_dwordx4 v[194:195], v[200:203], off offset:256
	v_mov_b32_e32 v204, v126
	v_mov_b32_e32 v205, v127
	v_mov_b32_e32 v206, v124
	v_mov_b32_e32 v207, v125
	v_lshl_add_u64 v[194:195], v[122:123], 0, v[192:193]
	s_nop 0
	v_permlane16_swap_b32 v204, v206
	v_permlane16_swap_b32 v205, v207
	global_store_dwordx4 v[194:195], v[204:207], off
	v_mov_b32_e32 v196, v6
	v_mov_b32_e32 v197, v7
	v_mov_b32_e32 v198, v2
	v_mov_b32_e32 v199, v3
	v_lshl_add_u64 v[194:195], v[122:123], 0, v[192:193]
	s_nop 0
	v_permlane16_swap_b32 v196, v198
	v_permlane16_swap_b32 v197, v199
	global_store_dwordx4 v[194:195], v[196:199], off offset:256
	global_load_dwordx4 v[6:9], v[14:15], off
	s_nop 0
	global_load_dwordx4 v[114:117], v[14:15], off offset:64
	global_load_dwordx4 v[118:121], v[14:15], off offset:512
	global_load_dwordx4 v[2:5], v[14:15], off offset:576
	s_waitcnt vmcnt(0)
	v_pk_fma_f32 v[110:111], v[110:111], s[22:23], v[6:7] op_sel_hi:[1,0,1]
	s_nop 0
	v_mul_f32_e32 v17, 0xbfb8aa3b, v110
	v_mul_f32_e32 v110, 0xbfb8aa3b, v111
	v_exp_f32_e32 v122, v110
	v_pk_fma_f32 v[110:111], v[112:113], s[22:23], v[8:9] op_sel_hi:[1,0,1]
	v_exp_f32_e32 v17, v17
	v_mul_f32_e32 v110, 0xbfb8aa3b, v110
	v_exp_f32_e32 v110, v110
	v_mul_f32_e32 v111, 0xbfb8aa3b, v111
	v_exp_f32_e32 v111, v111
	v_add_f32_e32 v17, 1.0, v17
	v_add_f32_e32 v112, 1.0, v122
	v_add_f32_e32 v110, 1.0, v110
	v_rcp_f32_e32 v17, v17
	v_rcp_f32_e32 v112, v112
	v_rcp_f32_e32 v113, v110
	v_add_f32_e32 v110, 1.0, v111
	v_rcp_f32_e32 v111, v110
	v_pk_fma_f32 v[106:107], v[106:107], s[22:23], v[114:115] op_sel_hi:[1,0,1]
	v_or_b32_e32 v122, 32, v16
	v_cvt_pk_bf16_f32 v110, v17, v112
	v_mul_f32_e32 v17, 0xbfb8aa3b, v106
	v_mul_f32_e32 v106, 0xbfb8aa3b, v107
	v_cvt_pk_bf16_f32 v111, v113, v111
	v_mad_i64_i32 v[112:113], s[38:39], v122, s71, v[12:13]
	v_exp_f32_e32 v122, v106
	v_pk_fma_f32 v[106:107], v[108:109], s[22:23], v[116:117] op_sel_hi:[1,0,1]
	v_exp_f32_e32 v17, v17
	v_mul_f32_e32 v106, 0xbfb8aa3b, v106
	v_exp_f32_e32 v106, v106
	v_mul_f32_e32 v107, 0xbfb8aa3b, v107
	v_exp_f32_e32 v107, v107
	v_add_f32_e32 v17, 1.0, v17
	v_add_f32_e32 v106, 1.0, v106
	v_add_f32_e32 v108, 1.0, v122
	v_rcp_f32_e32 v109, v106
	v_add_f32_e32 v106, 1.0, v107
	v_rcp_f32_e32 v17, v17
	v_rcp_f32_e32 v108, v108
	v_rcp_f32_e32 v122, v106
	v_pk_fma_f32 v[102:103], v[102:103], s[22:23], v[118:119] op_sel_hi:[1,0,1]
	v_lshl_add_u64 v[106:107], v[112:113], 0, v[10:11]
	v_cvt_pk_bf16_f32 v108, v17, v108
	v_cvt_pk_bf16_f32 v109, v109, v122
	v_mul_f32_e32 v17, 0xbfb8aa3b, v102
	v_mul_f32_e32 v102, 0xbfb8aa3b, v103
	global_store_dwordx2 v[106:107], v[108:109], off offset:32
	v_exp_f32_e32 v17, v17
	v_exp_f32_e32 v108, v102
	v_pk_fma_f32 v[102:103], v[104:105], s[22:23], v[120:121] op_sel_hi:[1,0,1]
	v_pk_fma_f32 v[6:7], v[94:95], s[22:23], v[6:7] op_sel_hi:[1,0,1]
	v_mul_f32_e32 v102, 0xbfb8aa3b, v102
	v_add_f32_e32 v17, 1.0, v17
	v_add_f32_e32 v104, 1.0, v108
	v_exp_f32_e32 v105, v102
	v_mul_f32_e32 v102, 0xbfb8aa3b, v103
	v_rcp_f32_e32 v17, v17
	v_rcp_f32_e32 v104, v104
	v_exp_f32_e32 v103, v102
	v_mul_f32_e32 v6, 0xbfb8aa3b, v6
	v_pk_fma_f32 v[90:91], v[90:91], s[22:23], v[114:115] op_sel_hi:[1,0,1]
	v_cvt_pk_bf16_f32 v102, v17, v104
	v_add_f32_e32 v17, 1.0, v105
	v_add_f32_e32 v103, 1.0, v103
	v_rcp_f32_e32 v17, v17
	v_rcp_f32_e32 v103, v103
	v_pk_fma_f32 v[98:99], v[98:99], s[22:23], v[2:3] op_sel_hi:[1,0,1]
	v_pk_fma_f32 v[2:3], v[82:83], s[22:23], v[2:3] op_sel_hi:[1,0,1]
	v_mul_f32_e32 v98, 0xbfb8aa3b, v98
	v_cvt_pk_bf16_f32 v103, v17, v103
	v_exp_f32_e32 v17, v6
	v_mul_f32_e32 v6, 0xbfb8aa3b, v7
	v_exp_f32_e32 v94, v6
	v_pk_fma_f32 v[6:7], v[96:97], s[22:23], v[8:9] op_sel_hi:[1,0,1]
	v_add_f32_e32 v8, 1.0, v17
	v_mul_f32_e32 v6, 0xbfb8aa3b, v6
	v_exp_f32_e32 v6, v6
	v_mul_f32_e32 v7, 0xbfb8aa3b, v7
	v_exp_f32_e32 v7, v7
	v_add_f32_e32 v9, 1.0, v94
	v_add_f32_e32 v6, 1.0, v6
	v_rcp_f32_e32 v17, v6
	v_add_f32_e32 v6, 1.0, v7
	v_rcp_f32_e32 v7, v6
	v_rcp_f32_e32 v8, v8
	v_rcp_f32_e32 v9, v9
	v_or_b32_e32 v94, 48, v16
	v_cvt_pk_bf16_f32 v7, v17, v7
	v_mul_f32_e32 v17, 0xbfb8aa3b, v90
	v_mul_f32_e32 v90, 0xbfb8aa3b, v91
	v_cvt_pk_bf16_f32 v6, v8, v9
	v_mad_i64_i32 v[8:9], s[38:39], v94, s71, v[12:13]
	v_exp_f32_e32 v94, v90
	v_pk_fma_f32 v[90:91], v[92:93], s[22:23], v[116:117] op_sel_hi:[1,0,1]
	v_exp_f32_e32 v17, v17
	v_mul_f32_e32 v90, 0xbfb8aa3b, v90
	v_mul_f32_e32 v91, 0xbfb8aa3b, v91
	v_exp_f32_e32 v90, v90
	v_exp_f32_e32 v91, v91
	v_add_f32_e32 v17, 1.0, v17
	v_add_f32_e32 v92, 1.0, v94
	v_add_f32_e32 v90, 1.0, v90
	v_add_f32_e32 v91, 1.0, v91
	v_rcp_f32_e32 v17, v17
	v_rcp_f32_e32 v92, v92
	v_rcp_f32_e32 v90, v90
	v_rcp_f32_e32 v91, v91
	v_lshl_add_u64 v[8:9], v[8:9], 0, v[10:11]
	v_mov_b32_e32 v200, v6
	v_mov_b32_e32 v201, v7
	v_cvt_pk_bf16_f32 v6, v17, v92
	v_cvt_pk_bf16_f32 v7, v90, v91
	v_mov_b32_e32 v202, v6
	v_mov_b32_e32 v203, v7
	v_lshl_add_u64 v[194:195], v[8:9], 0, v[192:193]
	s_nop 0
	v_permlane16_swap_b32 v200, v202
	v_permlane16_swap_b32 v201, v203
	global_store_dwordx4 v[194:195], v[200:203], off
	v_pk_fma_f32 v[6:7], v[86:87], s[22:23], v[118:119] op_sel_hi:[1,0,1]
	v_mul_f32_e32 v2, 0xbfb8aa3b, v2
	v_mul_f32_e32 v6, 0xbfb8aa3b, v6
	v_exp_f32_e32 v17, v6
	v_mul_f32_e32 v6, 0xbfb8aa3b, v7
	v_exp_f32_e32 v86, v6
	v_exp_f32_e32 v104, v98
	v_mul_f32_e32 v98, 0xbfb8aa3b, v99
	v_exp_f32_e32 v82, v2
	v_mul_f32_e32 v2, 0xbfb8aa3b, v3
	v_exp_f32_e32 v105, v98
	v_pk_fma_f32 v[98:99], v[100:101], s[22:23], v[4:5] op_sel_hi:[1,0,1]
	v_pk_fma_f32 v[6:7], v[88:89], s[22:23], v[120:121] op_sel_hi:[1,0,1]
	v_exp_f32_e32 v83, v2
	v_pk_fma_f32 v[2:3], v[84:85], s[22:23], v[4:5] op_sel_hi:[1,0,1]
	v_mul_f32_e32 v98, 0xbfb8aa3b, v98
	v_mul_f32_e32 v6, 0xbfb8aa3b, v6
	v_mul_f32_e32 v2, 0xbfb8aa3b, v2
	v_exp_f32_e32 v98, v98
	v_mul_f32_e32 v99, 0xbfb8aa3b, v99
	v_add_f32_e32 v17, 1.0, v17
	v_add_f32_e32 v86, 1.0, v86
	v_exp_f32_e32 v87, v6
	v_mul_f32_e32 v6, 0xbfb8aa3b, v7
	v_exp_f32_e32 v2, v2
	v_mul_f32_e32 v3, 0xbfb8aa3b, v3
	v_exp_f32_e32 v99, v99
	v_rcp_f32_e32 v17, v17
	v_rcp_f32_e32 v86, v86
	v_exp_f32_e32 v7, v6
	v_exp_f32_e32 v3, v3
	v_add_f32_e32 v98, 1.0, v98
	v_add_f32_e32 v2, 1.0, v2
	v_add_f32_e32 v100, 1.0, v104
	v_add_f32_e32 v101, 1.0, v105
	v_rcp_f32_e32 v104, v98
	v_add_f32_e32 v98, 1.0, v99
	v_cvt_pk_bf16_f32 v6, v17, v86
	v_add_f32_e32 v17, 1.0, v87
	v_add_f32_e32 v7, 1.0, v7
	v_add_f32_e32 v4, 1.0, v82
	v_add_f32_e32 v5, 1.0, v83
	v_rcp_f32_e32 v82, v2
	v_add_f32_e32 v2, 1.0, v3
	v_rcp_f32_e32 v100, v100
	v_rcp_f32_e32 v101, v101
	v_rcp_f32_e32 v99, v98
	v_rcp_f32_e32 v17, v17
	v_rcp_f32_e32 v7, v7
	v_rcp_f32_e32 v4, v4
	v_rcp_f32_e32 v5, v5
	v_rcp_f32_e32 v3, v2
	v_cvt_pk_bf16_f32 v98, v100, v101
	v_cvt_pk_bf16_f32 v99, v104, v99
	v_cvt_pk_bf16_f32 v7, v17, v7
	v_cvt_pk_bf16_f32 v2, v4, v5
	v_cvt_pk_bf16_f32 v3, v82, v3
	global_store_dwordx2 v[106:107], v[110:111], off
	v_mov_b32_e32 v204, v102
	v_mov_b32_e32 v205, v103
	v_mov_b32_e32 v206, v98
	v_mov_b32_e32 v207, v99
	v_lshl_add_u64 v[194:195], v[106:107], 0, v[192:193]
	s_nop 0
	v_permlane16_swap_b32 v204, v206
	v_permlane16_swap_b32 v205, v207
	global_store_dwordx4 v[194:195], v[204:207], off offset:256
	v_mov_b32_e32 v196, v6
	v_mov_b32_e32 v197, v7
	v_mov_b32_e32 v198, v2
	v_mov_b32_e32 v199, v3
	v_lshl_add_u64 v[194:195], v[8:9], 0, v[192:193]
	s_nop 0
	v_permlane16_swap_b32 v196, v198
	v_permlane16_swap_b32 v197, v199
	global_store_dwordx4 v[194:195], v[196:199], off offset:256
	global_load_dwordx4 v[6:9], v[14:15], off
	s_nop 0
	global_load_dwordx4 v[82:85], v[14:15], off offset:64
	global_load_dwordx4 v[86:89], v[14:15], off offset:512
	global_load_dwordx4 v[2:5], v[14:15], off offset:576
	s_waitcnt vmcnt(0)
	v_pk_fma_f32 v[78:79], v[78:79], s[22:23], v[6:7] op_sel_hi:[1,0,1]
	s_nop 0
	v_mul_f32_e32 v17, 0xbfb8aa3b, v78
	v_mul_f32_e32 v78, 0xbfb8aa3b, v79
	v_exp_f32_e32 v90, v78
	v_pk_fma_f32 v[78:79], v[80:81], s[22:23], v[8:9] op_sel_hi:[1,0,1]
	v_exp_f32_e32 v17, v17
	v_mul_f32_e32 v78, 0xbfb8aa3b, v78
	v_exp_f32_e32 v78, v78
	v_mul_f32_e32 v79, 0xbfb8aa3b, v79
	v_exp_f32_e32 v79, v79
	v_add_f32_e32 v17, 1.0, v17
	v_add_f32_e32 v80, 1.0, v90
	v_add_f32_e32 v78, 1.0, v78
	v_rcp_f32_e32 v17, v17
	v_rcp_f32_e32 v80, v80
	v_rcp_f32_e32 v81, v78
	v_add_f32_e32 v78, 1.0, v79
	v_rcp_f32_e32 v79, v78
	v_pk_fma_f32 v[74:75], v[74:75], s[22:23], v[82:83] op_sel_hi:[1,0,1]
	v_add_u32_e32 v90, 0x80, v16
	v_cvt_pk_bf16_f32 v78, v17, v80
	v_mul_f32_e32 v17, 0xbfb8aa3b, v74
	v_mul_f32_e32 v74, 0xbfb8aa3b, v75
	v_cvt_pk_bf16_f32 v79, v81, v79
	v_mad_i64_i32 v[80:81], s[38:39], v90, s71, v[12:13]
	v_exp_f32_e32 v90, v74
	v_pk_fma_f32 v[74:75], v[76:77], s[22:23], v[84:85] op_sel_hi:[1,0,1]
	v_exp_f32_e32 v17, v17
	v_mul_f32_e32 v74, 0xbfb8aa3b, v74
	v_exp_f32_e32 v74, v74
	v_mul_f32_e32 v75, 0xbfb8aa3b, v75
	v_exp_f32_e32 v75, v75
	v_add_f32_e32 v17, 1.0, v17
	v_add_f32_e32 v74, 1.0, v74
	v_add_f32_e32 v76, 1.0, v90
	v_rcp_f32_e32 v77, v74
	v_add_f32_e32 v74, 1.0, v75
	v_rcp_f32_e32 v17, v17
	v_rcp_f32_e32 v76, v76
	v_rcp_f32_e32 v90, v74
	v_pk_fma_f32 v[70:71], v[70:71], s[22:23], v[86:87] op_sel_hi:[1,0,1]
	v_lshl_add_u64 v[74:75], v[80:81], 0, v[10:11]
	v_cvt_pk_bf16_f32 v76, v17, v76
	v_cvt_pk_bf16_f32 v77, v77, v90
	v_mul_f32_e32 v17, 0xbfb8aa3b, v70
	v_mul_f32_e32 v70, 0xbfb8aa3b, v71
	global_store_dwordx2 v[74:75], v[76:77], off offset:32
	v_exp_f32_e32 v17, v17
	v_exp_f32_e32 v76, v70
	v_pk_fma_f32 v[70:71], v[72:73], s[22:23], v[88:89] op_sel_hi:[1,0,1]
	v_pk_fma_f32 v[6:7], v[62:63], s[22:23], v[6:7] op_sel_hi:[1,0,1]
	v_mul_f32_e32 v70, 0xbfb8aa3b, v70
	v_add_f32_e32 v17, 1.0, v17
	v_add_f32_e32 v72, 1.0, v76
	v_exp_f32_e32 v73, v70
	v_mul_f32_e32 v70, 0xbfb8aa3b, v71
	v_rcp_f32_e32 v17, v17
	v_rcp_f32_e32 v72, v72
	v_exp_f32_e32 v71, v70
	v_mul_f32_e32 v6, 0xbfb8aa3b, v6
	v_pk_fma_f32 v[58:59], v[58:59], s[22:23], v[82:83] op_sel_hi:[1,0,1]
	v_cvt_pk_bf16_f32 v70, v17, v72
	v_add_f32_e32 v17, 1.0, v73
	v_add_f32_e32 v71, 1.0, v71
	v_rcp_f32_e32 v17, v17
	v_rcp_f32_e32 v71, v71
	v_pk_fma_f32 v[66:67], v[66:67], s[22:23], v[2:3] op_sel_hi:[1,0,1]
	v_pk_fma_f32 v[2:3], v[50:51], s[22:23], v[2:3] op_sel_hi:[1,0,1]
	v_mul_f32_e32 v66, 0xbfb8aa3b, v66
	v_cvt_pk_bf16_f32 v71, v17, v71
	v_exp_f32_e32 v17, v6
	v_mul_f32_e32 v6, 0xbfb8aa3b, v7
	v_exp_f32_e32 v62, v6
	v_pk_fma_f32 v[6:7], v[64:65], s[22:23], v[8:9] op_sel_hi:[1,0,1]
	v_add_f32_e32 v8, 1.0, v17
	v_mul_f32_e32 v6, 0xbfb8aa3b, v6
	v_exp_f32_e32 v6, v6
	v_mul_f32_e32 v7, 0xbfb8aa3b, v7
	v_exp_f32_e32 v7, v7
	v_add_f32_e32 v9, 1.0, v62
	v_add_f32_e32 v6, 1.0, v6
	v_rcp_f32_e32 v17, v6
	v_add_f32_e32 v6, 1.0, v7
	v_rcp_f32_e32 v7, v6
	v_rcp_f32_e32 v8, v8
	v_rcp_f32_e32 v9, v9
	v_add_u32_e32 v62, 0x90, v16
	v_cvt_pk_bf16_f32 v7, v17, v7
	v_mul_f32_e32 v17, 0xbfb8aa3b, v58
	v_mul_f32_e32 v58, 0xbfb8aa3b, v59
	v_cvt_pk_bf16_f32 v6, v8, v9
	v_mad_i64_i32 v[8:9], s[38:39], v62, s71, v[12:13]
	v_exp_f32_e32 v62, v58
	v_pk_fma_f32 v[58:59], v[60:61], s[22:23], v[84:85] op_sel_hi:[1,0,1]
	v_exp_f32_e32 v17, v17
	v_mul_f32_e32 v58, 0xbfb8aa3b, v58
	v_mul_f32_e32 v59, 0xbfb8aa3b, v59
	v_exp_f32_e32 v58, v58
	v_exp_f32_e32 v59, v59
	v_add_f32_e32 v17, 1.0, v17
	v_add_f32_e32 v60, 1.0, v62
	v_add_f32_e32 v58, 1.0, v58
	v_add_f32_e32 v59, 1.0, v59
	v_rcp_f32_e32 v17, v17
	v_rcp_f32_e32 v60, v60
	v_rcp_f32_e32 v58, v58
	v_rcp_f32_e32 v59, v59
	v_lshl_add_u64 v[8:9], v[8:9], 0, v[10:11]
	v_mov_b32_e32 v200, v6
	v_mov_b32_e32 v201, v7
	v_cvt_pk_bf16_f32 v6, v17, v60
	v_cvt_pk_bf16_f32 v7, v58, v59
	v_mov_b32_e32 v202, v6
	v_mov_b32_e32 v203, v7
	v_lshl_add_u64 v[194:195], v[8:9], 0, v[192:193]
	s_nop 0
	v_permlane16_swap_b32 v200, v202
	v_permlane16_swap_b32 v201, v203
	global_store_dwordx4 v[194:195], v[200:203], off
	v_pk_fma_f32 v[6:7], v[54:55], s[22:23], v[86:87] op_sel_hi:[1,0,1]
	v_mul_f32_e32 v2, 0xbfb8aa3b, v2
	v_mul_f32_e32 v6, 0xbfb8aa3b, v6
	v_exp_f32_e32 v17, v6
	v_mul_f32_e32 v6, 0xbfb8aa3b, v7
	v_exp_f32_e32 v54, v6
	v_exp_f32_e32 v72, v66
	v_mul_f32_e32 v66, 0xbfb8aa3b, v67
	v_exp_f32_e32 v50, v2
	v_mul_f32_e32 v2, 0xbfb8aa3b, v3
	v_exp_f32_e32 v73, v66
	v_pk_fma_f32 v[66:67], v[68:69], s[22:23], v[4:5] op_sel_hi:[1,0,1]
	v_pk_fma_f32 v[6:7], v[56:57], s[22:23], v[88:89] op_sel_hi:[1,0,1]
	v_exp_f32_e32 v51, v2
	v_pk_fma_f32 v[2:3], v[52:53], s[22:23], v[4:5] op_sel_hi:[1,0,1]
	v_mul_f32_e32 v66, 0xbfb8aa3b, v66
	v_mul_f32_e32 v6, 0xbfb8aa3b, v6
	v_mul_f32_e32 v2, 0xbfb8aa3b, v2
	v_exp_f32_e32 v66, v66
	v_mul_f32_e32 v67, 0xbfb8aa3b, v67
	v_add_f32_e32 v17, 1.0, v17
	v_add_f32_e32 v54, 1.0, v54
	v_exp_f32_e32 v55, v6
	v_mul_f32_e32 v6, 0xbfb8aa3b, v7
	v_exp_f32_e32 v2, v2
	v_mul_f32_e32 v3, 0xbfb8aa3b, v3
	v_exp_f32_e32 v67, v67
	v_rcp_f32_e32 v17, v17
	v_rcp_f32_e32 v54, v54
	v_exp_f32_e32 v7, v6
	v_exp_f32_e32 v3, v3
	v_add_f32_e32 v66, 1.0, v66
	v_add_f32_e32 v2, 1.0, v2
	v_add_f32_e32 v68, 1.0, v72
	v_add_f32_e32 v69, 1.0, v73
	v_rcp_f32_e32 v72, v66
	v_add_f32_e32 v66, 1.0, v67
	v_cvt_pk_bf16_f32 v6, v17, v54
	v_add_f32_e32 v17, 1.0, v55
	v_add_f32_e32 v7, 1.0, v7
	v_add_f32_e32 v4, 1.0, v50
	v_add_f32_e32 v5, 1.0, v51
	v_rcp_f32_e32 v50, v2
	v_add_f32_e32 v2, 1.0, v3
	v_rcp_f32_e32 v68, v68
	v_rcp_f32_e32 v69, v69
	v_rcp_f32_e32 v67, v66
	v_rcp_f32_e32 v17, v17
	v_rcp_f32_e32 v7, v7
	v_rcp_f32_e32 v4, v4
	v_rcp_f32_e32 v5, v5
	v_rcp_f32_e32 v3, v2
	v_cvt_pk_bf16_f32 v66, v68, v69
	v_cvt_pk_bf16_f32 v67, v72, v67
	v_cvt_pk_bf16_f32 v7, v17, v7
	v_cvt_pk_bf16_f32 v2, v4, v5
	v_cvt_pk_bf16_f32 v3, v50, v3
	global_store_dwordx2 v[74:75], v[78:79], off
	v_mov_b32_e32 v204, v70
	v_mov_b32_e32 v205, v71
	v_mov_b32_e32 v206, v66
	v_mov_b32_e32 v207, v67
	v_lshl_add_u64 v[194:195], v[74:75], 0, v[192:193]
	s_nop 0
	v_permlane16_swap_b32 v204, v206
	v_permlane16_swap_b32 v205, v207
	global_store_dwordx4 v[194:195], v[204:207], off offset:256
	v_mov_b32_e32 v196, v6
	v_mov_b32_e32 v197, v7
	v_mov_b32_e32 v198, v2
	v_mov_b32_e32 v199, v3
	v_lshl_add_u64 v[194:195], v[8:9], 0, v[192:193]
	s_nop 0
	v_permlane16_swap_b32 v196, v198
	v_permlane16_swap_b32 v197, v199
	global_store_dwordx4 v[194:195], v[196:199], off offset:256
	global_load_dwordx4 v[6:9], v[14:15], off
	s_nop 0
	global_load_dwordx4 v[50:53], v[14:15], off offset:64
	global_load_dwordx4 v[54:57], v[14:15], off offset:512
	global_load_dwordx4 v[2:5], v[14:15], off offset:576
	s_waitcnt vmcnt(0)
	v_pk_fma_f32 v[14:15], v[46:47], s[22:23], v[6:7] op_sel_hi:[1,0,1]
	s_nop 0
	v_mul_f32_e32 v14, 0xbfb8aa3b, v14
	v_exp_f32_e32 v17, v14
	v_mul_f32_e32 v14, 0xbfb8aa3b, v15
	v_exp_f32_e32 v46, v14
	v_pk_fma_f32 v[14:15], v[48:49], s[22:23], v[8:9] op_sel_hi:[1,0,1]
	v_add_f32_e32 v17, 1.0, v17
	v_mul_f32_e32 v14, 0xbfb8aa3b, v14
	v_exp_f32_e32 v14, v14
	v_mul_f32_e32 v15, 0xbfb8aa3b, v15
	v_exp_f32_e32 v15, v15
	v_add_f32_e32 v46, 1.0, v46
	v_add_f32_e32 v14, 1.0, v14
	v_rcp_f32_e32 v17, v17
	v_rcp_f32_e32 v46, v46
	v_rcp_f32_e32 v47, v14
	v_add_f32_e32 v14, 1.0, v15
	v_rcp_f32_e32 v15, v14
	v_pk_fma_f32 v[42:43], v[42:43], s[22:23], v[50:51] op_sel_hi:[1,0,1]
	v_add_u32_e32 v48, 0xa0, v16
	v_cvt_pk_bf16_f32 v14, v17, v46
	v_mul_f32_e32 v17, 0xbfb8aa3b, v42
	v_mul_f32_e32 v42, 0xbfb8aa3b, v43
	v_cvt_pk_bf16_f32 v15, v47, v15
	v_mad_i64_i32 v[46:47], s[38:39], v48, s71, v[12:13]
	v_exp_f32_e32 v48, v42
	v_pk_fma_f32 v[42:43], v[44:45], s[22:23], v[52:53] op_sel_hi:[1,0,1]
	v_exp_f32_e32 v17, v17
	v_mul_f32_e32 v42, 0xbfb8aa3b, v42
	v_exp_f32_e32 v42, v42
	v_mul_f32_e32 v43, 0xbfb8aa3b, v43
	v_exp_f32_e32 v43, v43
	v_add_f32_e32 v17, 1.0, v17
	v_add_f32_e32 v42, 1.0, v42
	v_add_f32_e32 v44, 1.0, v48
	v_rcp_f32_e32 v45, v42
	v_add_f32_e32 v42, 1.0, v43
	v_rcp_f32_e32 v17, v17
	v_rcp_f32_e32 v44, v44
	v_rcp_f32_e32 v48, v42
	v_lshl_add_u64 v[42:43], v[46:47], 0, v[10:11]
	v_mov_b32_e32 v200, v14
	v_mov_b32_e32 v201, v15
	v_cvt_pk_bf16_f32 v14, v17, v44
	v_cvt_pk_bf16_f32 v15, v45, v48
	v_mov_b32_e32 v202, v14
	v_mov_b32_e32 v203, v15
	v_lshl_add_u64 v[194:195], v[42:43], 0, v[192:193]
	s_nop 0
	v_permlane16_swap_b32 v200, v202
	v_permlane16_swap_b32 v201, v203
	global_store_dwordx4 v[194:195], v[200:203], off
	v_pk_fma_f32 v[14:15], v[38:39], s[22:23], v[54:55] op_sel_hi:[1,0,1]
	v_pk_fma_f32 v[34:35], v[34:35], s[22:23], v[2:3] op_sel_hi:[1,0,1]
	v_mul_f32_e32 v14, 0xbfb8aa3b, v14
	v_exp_f32_e32 v17, v14
	v_mul_f32_e32 v14, 0xbfb8aa3b, v15
	v_exp_f32_e32 v38, v14
	v_pk_fma_f32 v[14:15], v[40:41], s[22:23], v[56:57] op_sel_hi:[1,0,1]
	v_add_f32_e32 v17, 1.0, v17
	v_mul_f32_e32 v14, 0xbfb8aa3b, v14
	v_add_f32_e32 v38, 1.0, v38
	v_exp_f32_e32 v39, v14
	v_mul_f32_e32 v14, 0xbfb8aa3b, v15
	v_rcp_f32_e32 v17, v17
	v_rcp_f32_e32 v38, v38
	v_exp_f32_e32 v15, v14
	v_mul_f32_e32 v34, 0xbfb8aa3b, v34
	v_pk_fma_f32 v[6:7], v[30:31], s[22:23], v[6:7] op_sel_hi:[1,0,1]
	v_cvt_pk_bf16_f32 v14, v17, v38
	v_add_f32_e32 v17, 1.0, v39
	v_add_f32_e32 v15, 1.0, v15
	v_rcp_f32_e32 v17, v17
	v_rcp_f32_e32 v15, v15
	v_exp_f32_e32 v38, v34
	v_mul_f32_e32 v34, 0xbfb8aa3b, v35
	v_exp_f32_e32 v39, v34
	v_pk_fma_f32 v[34:35], v[36:37], s[22:23], v[4:5] op_sel_hi:[1,0,1]
	v_mul_f32_e32 v6, 0xbfb8aa3b, v6
	v_mul_f32_e32 v34, 0xbfb8aa3b, v34
	v_mul_f32_e32 v35, 0xbfb8aa3b, v35
	v_exp_f32_e32 v34, v34
	v_exp_f32_e32 v35, v35
	v_cvt_pk_bf16_f32 v15, v17, v15
	v_exp_f32_e32 v17, v6
	v_mul_f32_e32 v6, 0xbfb8aa3b, v7
	v_exp_f32_e32 v30, v6
	v_pk_fma_f32 v[6:7], v[32:33], s[22:23], v[8:9] op_sel_hi:[1,0,1]
	v_add_f32_e32 v36, 1.0, v38
	v_add_f32_e32 v37, 1.0, v39
	v_add_f32_e32 v34, 1.0, v34
	v_add_f32_e32 v35, 1.0, v35
	v_mul_f32_e32 v6, 0xbfb8aa3b, v6
	v_rcp_f32_e32 v36, v36
	v_rcp_f32_e32 v37, v37
	v_rcp_f32_e32 v34, v34
	v_rcp_f32_e32 v35, v35
	v_exp_f32_e32 v6, v6
	v_mul_f32_e32 v7, 0xbfb8aa3b, v7
	v_add_f32_e32 v8, 1.0, v17
	v_add_f32_e32 v9, 1.0, v30
	v_exp_f32_e32 v7, v7
	v_rcp_f32_e32 v8, v8
	v_rcp_f32_e32 v9, v9
	v_mov_b32_e32 v204, v14
	v_mov_b32_e32 v205, v15
	v_cvt_pk_bf16_f32 v14, v36, v37
	v_cvt_pk_bf16_f32 v15, v34, v35
	v_add_f32_e32 v6, 1.0, v6
	v_rcp_f32_e32 v17, v6
	v_add_f32_e32 v6, 1.0, v7
	v_mov_b32_e32 v206, v14
	v_mov_b32_e32 v207, v15
	v_lshl_add_u64 v[194:195], v[42:43], 0, v[192:193]
	s_nop 0
	v_permlane16_swap_b32 v204, v206
	v_permlane16_swap_b32 v205, v207
	global_store_dwordx4 v[194:195], v[204:207], off offset:256
	v_add_u32_e32 v14, 0xb0, v16
	v_rcp_f32_e32 v7, v6
	v_cvt_pk_bf16_f32 v6, v8, v9
	v_mad_i64_i32 v[8:9], s[38:39], v14, s71, v[12:13]
	v_pk_fma_f32 v[12:13], v[26:27], s[22:23], v[50:51] op_sel_hi:[1,0,1]
	v_cvt_pk_bf16_f32 v7, v17, v7
	v_mul_f32_e32 v12, 0xbfb8aa3b, v12
	v_exp_f32_e32 v14, v12
	v_mul_f32_e32 v12, 0xbfb8aa3b, v13
	v_exp_f32_e32 v15, v12
	v_pk_fma_f32 v[12:13], v[28:29], s[22:23], v[52:53] op_sel_hi:[1,0,1]
	v_add_f32_e32 v14, 1.0, v14
	v_mul_f32_e32 v12, 0xbfb8aa3b, v12
	v_mul_f32_e32 v13, 0xbfb8aa3b, v13
	v_exp_f32_e32 v12, v12
	v_exp_f32_e32 v13, v13
	v_add_f32_e32 v15, 1.0, v15
	v_rcp_f32_e32 v14, v14
	v_add_f32_e32 v12, 1.0, v12
	v_add_f32_e32 v13, 1.0, v13
	v_rcp_f32_e32 v15, v15
	v_rcp_f32_e32 v12, v12
	v_rcp_f32_e32 v13, v13
	v_lshl_add_u64 v[8:9], v[8:9], 0, v[10:11]
	v_mov_b32_e32 v196, v6
	v_mov_b32_e32 v197, v7
	v_cvt_pk_bf16_f32 v6, v14, v15
	v_cvt_pk_bf16_f32 v7, v12, v13
	v_mov_b32_e32 v198, v6
	v_mov_b32_e32 v199, v7
	v_lshl_add_u64 v[194:195], v[8:9], 0, v[192:193]
	s_nop 0
	v_permlane16_swap_b32 v196, v198
	v_permlane16_swap_b32 v197, v199
	global_store_dwordx4 v[194:195], v[196:199], off
	v_pk_fma_f32 v[6:7], v[22:23], s[22:23], v[54:55] op_sel_hi:[1,0,1]
	v_pk_fma_f32 v[2:3], v[18:19], s[22:23], v[2:3] op_sel_hi:[1,0,1]
	v_mul_f32_e32 v6, 0xbfb8aa3b, v6
	v_exp_f32_e32 v10, v6
	v_mul_f32_e32 v6, 0xbfb8aa3b, v7
	v_exp_f32_e32 v11, v6
	v_pk_fma_f32 v[6:7], v[24:25], s[22:23], v[56:57] op_sel_hi:[1,0,1]
	v_add_f32_e32 v10, 1.0, v10
	v_rcp_f32_e32 v10, v10
	v_add_f32_e32 v11, 1.0, v11
	v_rcp_f32_e32 v11, v11
	v_mul_f32_e32 v6, 0xbfb8aa3b, v6
	v_exp_f32_e32 v12, v6
	v_mul_f32_e32 v6, 0xbfb8aa3b, v7
	v_mul_f32_e32 v2, 0xbfb8aa3b, v2
	v_exp_f32_e32 v7, v6
	v_cvt_pk_bf16_f32 v6, v10, v11
	v_exp_f32_e32 v11, v2
	v_mul_f32_e32 v2, 0xbfb8aa3b, v3
	v_add_f32_e32 v10, 1.0, v12
	v_exp_f32_e32 v12, v2
	v_pk_fma_f32 v[2:3], v[20:21], s[22:23], v[4:5] op_sel_hi:[1,0,1]
	v_add_f32_e32 v7, 1.0, v7
	v_mul_f32_e32 v2, 0xbfb8aa3b, v2
	v_exp_f32_e32 v2, v2
	v_mul_f32_e32 v3, 0xbfb8aa3b, v3
	v_exp_f32_e32 v3, v3
	v_add_f32_e32 v4, 1.0, v11
	v_add_f32_e32 v2, 1.0, v2
	v_add_f32_e32 v5, 1.0, v12
	v_rcp_f32_e32 v11, v2
	v_add_f32_e32 v2, 1.0, v3
	v_rcp_f32_e32 v10, v10
	v_rcp_f32_e32 v7, v7
	v_rcp_f32_e32 v4, v4
	v_rcp_f32_e32 v5, v5
	v_rcp_f32_e32 v3, v2
	v_cvt_pk_bf16_f32 v7, v10, v7
	s_mov_b64 s[38:39], s[34:35]
	v_cvt_pk_bf16_f32 v2, v4, v5
	v_cvt_pk_bf16_f32 v3, v11, v3
	v_mov_b32_e32 v200, v6
	v_mov_b32_e32 v201, v7
	v_mov_b32_e32 v202, v2
	v_mov_b32_e32 v203, v3
	v_lshl_add_u64 v[194:195], v[8:9], 0, v[192:193]
	s_nop 0
	v_permlane16_swap_b32 v200, v202
	v_permlane16_swap_b32 v201, v203
	global_store_dwordx4 v[194:195], v[200:203], off offset:256
	s_cbranch_vccz .LBB0_1548
	s_waitcnt vmcnt(0)
	s_cmpk_gt_u32 s3, 0xff
	s_cbranch_scc1 .LBB0_1555
	s_barrier

.LBB0_3123:
	ds_read_b128 v[2:5], v167
	ds_read_b128 v[6:9], v171
	ds_read_b128 v[10:13], v172
	ds_read_b128 v[14:17], v173
	s_add_u32 s40, s38, 0x100
	s_addc_u32 s41, s39, 0
	s_cmp_eq_u32 s86, 18
	s_cselect_b32 s45, s15, s41
	s_cselect_b32 s44, s14, s40
	s_cselect_b32 s43, s17, s85
	s_cselect_b32 s42, s16, s84
	v_lshl_add_u64 v[158:159], s[38:39], 0, v[152:153]
	s_add_i32 m0, s47, 0xc000
	ds_read_b128 v[186:189], v184
	ds_read_b128 v[190:193], v184 offset:1024
	ds_read_b128 v[194:197], v184 offset:2048
	ds_read_b128 v[198:201], v184 offset:3072
	ds_read_b128 v[202:205], v184 offset:4096
	ds_read_b128 v[206:209], v184 offset:5120
	ds_read_b128 v[210:213], v184 offset:6144
	ds_read_b128 v[214:217], v184 offset:7168
	global_load_lds_dwordx4 v[158:159], off
	v_lshl_add_u64 v[158:159], s[38:39], 0, v[150:151]
	s_add_i32 m0, s47, 0xe000
	s_nop 0
	global_load_lds_dwordx4 v[158:159], off
	s_waitcnt lgkmcnt(8)
	s_barrier
	s_waitcnt lgkmcnt(0)
	s_setprio 1
	s_waitcnt lgkmcnt(0)
	v_mfma_f32_16x16x128_f8f6f4 v[142:145], v[2:9], v[186:193], v[142:145]
	v_mfma_f32_16x16x128_f8f6f4 v[138:141], v[10:17], v[186:193], v[138:141]
	v_mfma_f32_16x16x128_f8f6f4 v[134:137], v[2:9], v[194:201], v[134:137]
	v_mfma_f32_16x16x128_f8f6f4 v[130:133], v[10:17], v[194:201], v[130:133]
	v_mfma_f32_16x16x128_f8f6f4 v[110:113], v[2:9], v[202:209], v[110:113]
	v_mfma_f32_16x16x128_f8f6f4 v[106:109], v[10:17], v[202:209], v[106:109]
	v_mfma_f32_16x16x128_f8f6f4 v[102:105], v[2:9], v[210:217], v[102:105]
	v_mfma_f32_16x16x128_f8f6f4 v[98:101], v[10:17], v[210:217], v[98:101]
	s_setprio 0
	s_barrier
	s_mov_b32 m0, s48
	v_lshl_add_u64 v[158:159], s[42:43], 0, v[146:147]
	ds_read_b128 v[220:223], v168
	ds_read_b128 v[224:227], v174
	ds_read_b128 v[228:231], v175
	ds_read_b128 v[232:235], v176
	global_load_lds_dwordx4 v[158:159], off
	v_lshl_add_u64 v[160:161], s[42:43], 0, v[148:149]
	s_mov_b32 m0, s49
	s_nop 0
	global_load_lds_dwordx4 v[160:161], off
	s_barrier
	s_waitcnt lgkmcnt(0)
	s_setprio 1
	s_waitcnt lgkmcnt(0)
	v_mfma_f32_16x16x128_f8f6f4 v[126:129], v[220:227], v[186:193], v[126:129]
	v_mfma_f32_16x16x128_f8f6f4 v[122:125], v[228:235], v[186:193], v[122:125]
	v_mfma_f32_16x16x128_f8f6f4 v[118:121], v[220:227], v[194:201], v[118:121]
	v_mfma_f32_16x16x128_f8f6f4 v[114:117], v[228:235], v[194:201], v[114:117]
	v_mfma_f32_16x16x128_f8f6f4 v[94:97], v[220:227], v[202:209], v[94:97]
	v_mfma_f32_16x16x128_f8f6f4 v[90:93], v[228:235], v[202:209], v[90:93]
	v_mfma_f32_16x16x128_f8f6f4 v[86:89], v[220:227], v[210:217], v[86:89]
	v_mfma_f32_16x16x128_f8f6f4 v[82:85], v[228:235], v[210:217], v[82:85]
	s_setprio 0
	s_mov_b32 m0, s47
	v_lshl_add_u64 v[162:163], s[44:45], 0, v[146:147]
	s_barrier
	ds_read_b128 v[186:189], v184 offset:16384
	ds_read_b128 v[190:193], v184 offset:17408
	ds_read_b128 v[194:197], v184 offset:18432
	ds_read_b128 v[198:201], v184 offset:19456
	ds_read_b128 v[202:205], v184 offset:20480
	ds_read_b128 v[206:209], v184 offset:21504
	ds_read_b128 v[210:213], v184 offset:22528
	ds_read_b128 v[214:217], v184 offset:23552
	global_load_lds_dwordx4 v[162:163], off
	v_lshl_add_u64 v[164:165], s[44:45], 0, v[148:149]
	s_mov_b32 m0, s52
	s_nop 0
	global_load_lds_dwordx4 v[164:165], off
	s_barrier
	s_waitcnt lgkmcnt(0)
	s_setprio 1
	s_waitcnt lgkmcnt(0)
	v_mfma_f32_16x16x128_f8f6f4 v[78:81], v[2:9], v[186:193], v[78:81]
	v_mfma_f32_16x16x128_f8f6f4 v[74:77], v[10:17], v[186:193], v[74:77]
	v_mfma_f32_16x16x128_f8f6f4 v[70:73], v[2:9], v[194:201], v[70:73]
	v_mfma_f32_16x16x128_f8f6f4 v[66:69], v[10:17], v[194:201], v[66:69]
	v_mfma_f32_16x16x128_f8f6f4 v[46:49], v[2:9], v[202:209], v[46:49]
	v_mfma_f32_16x16x128_f8f6f4 v[42:45], v[10:17], v[202:209], v[42:45]
	v_mfma_f32_16x16x128_f8f6f4 v[38:41], v[2:9], v[210:217], v[38:41]
	v_mfma_f32_16x16x128_f8f6f4 v[34:37], v[10:17], v[210:217], v[34:37]
	s_setprio 0
	s_barrier
	s_add_u32 s38, s42, 0x58000
	s_addc_u32 s39, s43, 0
	s_mov_b32 m0, s53
	v_lshl_add_u64 v[2:3], s[38:39], 0, v[146:147]
	global_load_lds_dwordx4 v[2:3], off
	v_lshl_add_u64 v[2:3], s[38:39], 0, v[148:149]
	s_mov_b32 m0, s55
	s_nop 0
	global_load_lds_dwordx4 v[2:3], off
	s_waitcnt vmcnt(6)
	s_barrier
	s_setprio 1
	v_mfma_f32_16x16x128_f8f6f4 v[62:65], v[220:227], v[186:193], v[62:65]
	v_mfma_f32_16x16x128_f8f6f4 v[58:61], v[228:235], v[186:193], v[58:61]
	v_mfma_f32_16x16x128_f8f6f4 v[54:57], v[220:227], v[194:201], v[54:57]
	v_mfma_f32_16x16x128_f8f6f4 v[50:53], v[228:235], v[194:201], v[50:53]
	v_mfma_f32_16x16x128_f8f6f4 v[30:33], v[220:227], v[202:209], v[30:33]
	v_mfma_f32_16x16x128_f8f6f4 v[26:29], v[228:235], v[202:209], v[26:29]
	v_mfma_f32_16x16x128_f8f6f4 v[22:25], v[220:227], v[210:217], v[22:25]
	v_mfma_f32_16x16x128_f8f6f4 v[18:21], v[228:235], v[210:217], v[18:21]
	s_setprio 0
	s_barrier
	ds_read_b128 v[2:5], v169
	ds_read_b128 v[6:9], v177
	ds_read_b128 v[10:13], v178
	ds_read_b128 v[14:17], v179
	s_add_u32 s38, s44, 0x58000
	s_addc_u32 s39, s45, 0
	s_mov_b32 m0, s64
	v_lshl_add_u64 v[220:221], s[38:39], 0, v[146:147]
	ds_read_b128 v[186:189], v184 offset:32768
	ds_read_b128 v[190:193], v184 offset:33792
	ds_read_b128 v[194:197], v184 offset:34816
	ds_read_b128 v[198:201], v184 offset:35840
	ds_read_b128 v[202:205], v184 offset:36864
	ds_read_b128 v[206:209], v184 offset:37888
	ds_read_b128 v[210:213], v184 offset:38912
	ds_read_b128 v[214:217], v184 offset:39936
	global_load_lds_dwordx4 v[220:221], off
	v_lshl_add_u64 v[220:221], s[38:39], 0, v[148:149]
	s_mov_b32 m0, s65
	s_nop 0
	global_load_lds_dwordx4 v[220:221], off
	s_waitcnt lgkmcnt(8)
	s_barrier
	s_waitcnt lgkmcnt(0)
	s_setprio 1
	s_waitcnt lgkmcnt(0)
	v_mfma_f32_16x16x128_f8f6f4 v[142:145], v[2:9], v[186:193], v[142:145]
	v_mfma_f32_16x16x128_f8f6f4 v[138:141], v[10:17], v[186:193], v[138:141]
	v_mfma_f32_16x16x128_f8f6f4 v[134:137], v[2:9], v[194:201], v[134:137]
	v_mfma_f32_16x16x128_f8f6f4 v[130:133], v[10:17], v[194:201], v[130:133]
	v_mfma_f32_16x16x128_f8f6f4 v[110:113], v[2:9], v[202:209], v[110:113]
	v_mfma_f32_16x16x128_f8f6f4 v[106:109], v[10:17], v[202:209], v[106:109]
	v_mfma_f32_16x16x128_f8f6f4 v[102:105], v[2:9], v[210:217], v[102:105]
	v_mfma_f32_16x16x128_f8f6f4 v[98:101], v[10:17], v[210:217], v[98:101]
	s_setprio 0
	s_barrier
	s_mov_b32 m0, s69
	v_lshl_add_u64 v[158:159], v[158:159], 0, s[28:29]
	ds_read_b128 v[220:223], v170
	ds_read_b128 v[224:227], v180
	ds_read_b128 v[228:231], v181
	ds_read_b128 v[232:235], v182
	global_load_lds_dwordx4 v[158:159], off
	v_lshl_add_u64 v[158:159], v[160:161], 0, s[28:29]
	s_mov_b32 m0, s70
	s_nop 0
	global_load_lds_dwordx4 v[158:159], off
	s_barrier
	s_waitcnt lgkmcnt(0)
	s_setprio 1
	s_waitcnt lgkmcnt(0)
	v_mfma_f32_16x16x128_f8f6f4 v[126:129], v[220:227], v[186:193], v[126:129]
	v_mfma_f32_16x16x128_f8f6f4 v[122:125], v[228:235], v[186:193], v[122:125]
	v_mfma_f32_16x16x128_f8f6f4 v[118:121], v[220:227], v[194:201], v[118:121]
	v_mfma_f32_16x16x128_f8f6f4 v[114:117], v[228:235], v[194:201], v[114:117]
	v_mfma_f32_16x16x128_f8f6f4 v[94:97], v[220:227], v[202:209], v[94:97]
	v_mfma_f32_16x16x128_f8f6f4 v[90:93], v[228:235], v[202:209], v[90:93]
	v_mfma_f32_16x16x128_f8f6f4 v[86:89], v[220:227], v[210:217], v[86:89]
	v_mfma_f32_16x16x128_f8f6f4 v[82:85], v[228:235], v[210:217], v[82:85]
	s_setprio 0
	s_mov_b32 m0, s71
	v_lshl_add_u64 v[158:159], v[162:163], 0, s[28:29]
	s_barrier
	ds_read_b128 v[186:189], v184 offset:49152
	ds_read_b128 v[190:193], v184 offset:50176
	ds_read_b128 v[194:197], v184 offset:51200
	ds_read_b128 v[198:201], v184 offset:52224
	ds_read_b128 v[202:205], v184 offset:53248
	ds_read_b128 v[206:209], v184 offset:54272
	ds_read_b128 v[210:213], v184 offset:55296
	ds_read_b128 v[214:217], v184 offset:56320
	global_load_lds_dwordx4 v[158:159], off
	v_lshl_add_u64 v[158:159], v[164:165], 0, s[28:29]
	s_mov_b32 m0, s72
	s_nop 0
	global_load_lds_dwordx4 v[158:159], off
	s_barrier
	s_waitcnt lgkmcnt(0)
	s_setprio 1
	s_waitcnt lgkmcnt(0)
	v_mfma_f32_16x16x128_f8f6f4 v[78:81], v[2:9], v[186:193], v[78:81]
	v_mfma_f32_16x16x128_f8f6f4 v[74:77], v[10:17], v[186:193], v[74:77]
	v_mfma_f32_16x16x128_f8f6f4 v[70:73], v[2:9], v[194:201], v[70:73]
	v_mfma_f32_16x16x128_f8f6f4 v[66:69], v[10:17], v[194:201], v[66:69]
	v_mfma_f32_16x16x128_f8f6f4 v[46:49], v[2:9], v[202:209], v[46:49]
	v_mfma_f32_16x16x128_f8f6f4 v[42:45], v[10:17], v[202:209], v[42:45]
	v_mfma_f32_16x16x128_f8f6f4 v[38:41], v[2:9], v[210:217], v[38:41]
	v_mfma_f32_16x16x128_f8f6f4 v[34:37], v[10:17], v[210:217], v[34:37]
	s_setprio 0
	s_barrier
	s_add_u32 s38, s42, 0x58080
	s_addc_u32 s39, s43, 0
	s_mov_b32 m0, s73
	v_lshl_add_u64 v[2:3], s[38:39], 0, v[146:147]
	global_load_lds_dwordx4 v[2:3], off
	v_lshl_add_u64 v[2:3], s[38:39], 0, v[148:149]
	s_mov_b32 m0, s74
	s_nop 0
	global_load_lds_dwordx4 v[2:3], off
	s_waitcnt vmcnt(6)
	s_barrier
	s_setprio 1
	v_mfma_f32_16x16x128_f8f6f4 v[62:65], v[220:227], v[186:193], v[62:65]
	v_mfma_f32_16x16x128_f8f6f4 v[58:61], v[228:235], v[186:193], v[58:61]
	v_mfma_f32_16x16x128_f8f6f4 v[54:57], v[220:227], v[194:201], v[54:57]
	v_mfma_f32_16x16x128_f8f6f4 v[50:53], v[228:235], v[194:201], v[50:53]
	v_mfma_f32_16x16x128_f8f6f4 v[30:33], v[220:227], v[202:209], v[30:33]
	v_mfma_f32_16x16x128_f8f6f4 v[26:29], v[228:235], v[202:209], v[26:29]
	v_mfma_f32_16x16x128_f8f6f4 v[22:25], v[220:227], v[210:217], v[22:25]
	v_mfma_f32_16x16x128_f8f6f4 v[18:21], v[228:235], v[210:217], v[18:21]
	s_setprio 0
	s_add_i32 s86, s86, 2
	s_add_u32 s84, s84, 0x100
	s_addc_u32 s85, s85, 0
	s_cmp_gt_u32 s86, 19
	s_mov_b64 s[38:39], s[40:41]
	s_barrier
	s_cbranch_scc0 .LBB0_3123
	v_bfe_u32 v160, v0, 4, 1
	v_mul_u32_u24_e32 v160, 24, v160
	v_mov_b32_e32 v161, 0
	v_lshl_add_u32 v6, s83, 8, v166
	v_ashrrev_i32_e32 v7, 31, v6
	v_or_b32_e32 v4, 16, v6
	s_nop 15
	s_nop 15
	v_lshl_add_u64 v[2:3], v[6:7], 2, s[20:21]
	v_ashrrev_i32_e32 v5, 31, v4
	global_load_dword v158, v[2:3], off
	v_lshl_add_u64 v[8:9], v[4:5], 2, s[20:21]
	global_load_dword v159, v[8:9], off
	s_ashr_i32 s0, s82, 31
	s_lshr_b32 s0, s0, 30
	s_add_i32 s0, s82, s0
	s_and_b32 s0, s0, 0xfffffc
	v_lshlrev_b64 v[4:5], 11, v[4:5]
	s_sub_i32 s0, s82, s0
	v_lshl_add_u64 v[14:15], s[18:19], 0, v[4:5]
	v_lshl_or_b32 v4, s0, 8, v183
	v_lshlrev_b64 v[10:11], 11, v[6:7]
	v_ashrrev_i32_e32 v5, 31, v4
	v_lshl_add_u64 v[10:11], s[18:19], 0, v[10:11]
	v_lshlrev_b64 v[16:17], 1, v[4:5]
	v_lshl_add_u64 v[4:5], v[10:11], 0, v[16:17]
	v_lshl_add_u64 v[10:11], v[14:15], 0, v[16:17]
	v_or_b32_e32 v8, 32, v6
	v_ashrrev_i32_e32 v9, 31, v8
	v_lshl_add_u64 v[12:13], v[8:9], 2, s[20:21]
	v_or_b32_e32 v6, 48, v6
	v_ashrrev_i32_e32 v7, 31, v6
	v_lshlrev_b64 v[8:9], 11, v[8:9]
	v_lshlrev_b64 v[6:7], 11, v[6:7]
	v_lshl_add_u64 v[8:9], s[18:19], 0, v[8:9]
	v_lshl_add_u64 v[6:7], s[18:19], 0, v[6:7]
	v_lshl_add_u64 v[8:9], v[8:9], 0, v[16:17]
	v_lshl_add_u64 v[6:7], v[6:7], 0, v[16:17]
	s_mov_b32 s83, s80
	s_mov_b64 s[40:41], s[16:17]
	s_mov_b64 s[38:39], s[14:15]
	s_mov_b32 s82, s81
	s_waitcnt vmcnt(0)
	v_mul_f32_e32 v14, 0x3b800000, v158
	v_pk_mul_f32 v[142:143], v[142:143], v[14:15] op_sel_hi:[1,0]
	v_pk_mul_f32 v[144:145], v[144:145], v[14:15] op_sel_hi:[1,0]
	v_pk_mul_f32 v[138:139], v[138:139], v[14:15] op_sel_hi:[1,0]
	v_pk_mul_f32 v[140:141], v[140:141], v[14:15] op_sel_hi:[1,0]
	v_pk_mul_f32 v[126:127], v[126:127], v[14:15] op_sel_hi:[1,0]
	v_pk_mul_f32 v[128:129], v[128:129], v[14:15] op_sel_hi:[1,0]
	v_pk_mul_f32 v[122:123], v[122:123], v[14:15] op_sel_hi:[1,0]
	v_pk_mul_f32 v[14:15], v[124:125], v[14:15] op_sel_hi:[1,0]
	v_mul_f32_e32 v124, 0x3b800000, v159
	v_cvt_pk_bf16_f32 v126, v126, v127
	v_cvt_pk_bf16_f32 v127, v128, v129
	v_cvt_pk_bf16_f32 v122, v122, v123
	v_cvt_pk_bf16_f32 v123, v14, v15
	v_pk_mul_f32 v[14:15], v[134:135], v[124:125] op_sel_hi:[1,0]
	v_pk_mul_f32 v[128:129], v[136:137], v[124:125] op_sel_hi:[1,0]
	v_cvt_pk_bf16_f32 v142, v142, v143
	v_cvt_pk_bf16_f32 v143, v144, v145
	v_pk_mul_f32 v[130:131], v[130:131], v[124:125] op_sel_hi:[1,0]
	v_pk_mul_f32 v[132:133], v[132:133], v[124:125] op_sel_hi:[1,0]
	v_pk_mul_f32 v[118:119], v[118:119], v[124:125] op_sel_hi:[1,0]
	v_pk_mul_f32 v[120:121], v[120:121], v[124:125] op_sel_hi:[1,0]
	v_pk_mul_f32 v[114:115], v[114:115], v[124:125] op_sel_hi:[1,0]
	v_pk_mul_f32 v[116:117], v[116:117], v[124:125] op_sel_hi:[1,0]
	v_cvt_pk_bf16_f32 v14, v14, v15
	v_cvt_pk_bf16_f32 v15, v128, v129
	v_cvt_pk_bf16_f32 v138, v138, v139
	v_cvt_pk_bf16_f32 v139, v140, v141
	v_mov_b32_e32 v188, v142
	v_mov_b32_e32 v189, v143
	v_mov_b32_e32 v190, v138
	v_mov_b32_e32 v191, v139
	v_lshl_add_u64 v[162:163], v[4:5], 0, v[160:161]
	s_nop 0
	v_permlane16_swap_b32 v188, v190
	v_permlane16_swap_b32 v189, v191
	global_store_dwordx4 v[162:163], v[188:191], off
	v_mov_b32_e32 v192, v126
	v_mov_b32_e32 v193, v127
	v_mov_b32_e32 v194, v122
	v_mov_b32_e32 v195, v123
	v_lshl_add_u64 v[162:163], v[4:5], 0, v[160:161]
	s_nop 0
	v_permlane16_swap_b32 v192, v194
	v_permlane16_swap_b32 v193, v195
	global_store_dwordx4 v[162:163], v[192:195], off offset:256
	v_cvt_pk_bf16_f32 v122, v130, v131
	v_cvt_pk_bf16_f32 v123, v132, v133
	v_cvt_pk_bf16_f32 v118, v118, v119
	v_cvt_pk_bf16_f32 v119, v120, v121
	v_cvt_pk_bf16_f32 v114, v114, v115
	v_cvt_pk_bf16_f32 v115, v116, v117
	v_mov_b32_e32 v196, v14
	v_mov_b32_e32 v197, v15
	v_mov_b32_e32 v198, v122
	v_mov_b32_e32 v199, v123
	v_lshl_add_u64 v[162:163], v[10:11], 0, v[160:161]
	s_nop 0
	v_permlane16_swap_b32 v196, v198
	v_permlane16_swap_b32 v197, v199
	global_store_dwordx4 v[162:163], v[196:199], off
	v_mov_b32_e32 v188, v118
	v_mov_b32_e32 v189, v119
	v_mov_b32_e32 v190, v114
	v_mov_b32_e32 v191, v115
	v_lshl_add_u64 v[162:163], v[10:11], 0, v[160:161]
	s_nop 0
	v_permlane16_swap_b32 v188, v190
	v_permlane16_swap_b32 v189, v191
	global_store_dwordx4 v[162:163], v[188:191], off offset:256
	global_load_dword v10, v[12:13], off
	s_nop 0
	global_load_dword v11, v[2:3], off offset:192
	s_waitcnt vmcnt(0)
	v_mul_f32_e32 v10, 0x3b800000, v10
	v_mul_f32_e32 v12, 0x3b800000, v11
	v_pk_mul_f32 v[14:15], v[110:111], v[10:11] op_sel_hi:[1,0]
	v_pk_mul_f32 v[16:17], v[112:113], v[10:11] op_sel_hi:[1,0]
	v_pk_mul_f32 v[106:107], v[106:107], v[10:11] op_sel_hi:[1,0]
	v_pk_mul_f32 v[108:109], v[108:109], v[10:11] op_sel_hi:[1,0]
	v_pk_mul_f32 v[94:95], v[94:95], v[10:11] op_sel_hi:[1,0]
	v_pk_mul_f32 v[96:97], v[96:97], v[10:11] op_sel_hi:[1,0]
	v_pk_mul_f32 v[90:91], v[90:91], v[10:11] op_sel_hi:[1,0]
	v_pk_mul_f32 v[10:11], v[92:93], v[10:11] op_sel_hi:[1,0]
	v_pk_mul_f32 v[92:93], v[102:103], v[12:13] op_sel_hi:[1,0]
	v_pk_mul_f32 v[102:103], v[104:105], v[12:13] op_sel_hi:[1,0]
	v_pk_mul_f32 v[98:99], v[98:99], v[12:13] op_sel_hi:[1,0]
	v_pk_mul_f32 v[100:101], v[100:101], v[12:13] op_sel_hi:[1,0]
	v_pk_mul_f32 v[86:87], v[86:87], v[12:13] op_sel_hi:[1,0]
	v_pk_mul_f32 v[88:89], v[88:89], v[12:13] op_sel_hi:[1,0]
	v_pk_mul_f32 v[82:83], v[82:83], v[12:13] op_sel_hi:[1,0]
	v_pk_mul_f32 v[12:13], v[84:85], v[12:13] op_sel_hi:[1,0]
	v_cvt_pk_bf16_f32 v14, v14, v15
	v_cvt_pk_bf16_f32 v15, v16, v17
	v_cvt_pk_bf16_f32 v16, v106, v107
	v_cvt_pk_bf16_f32 v17, v108, v109
	v_cvt_pk_bf16_f32 v84, v94, v95
	v_cvt_pk_bf16_f32 v85, v96, v97
	v_cvt_pk_bf16_f32 v90, v90, v91
	v_cvt_pk_bf16_f32 v91, v10, v11
	v_cvt_pk_bf16_f32 v10, v92, v93
	v_cvt_pk_bf16_f32 v11, v102, v103
	v_cvt_pk_bf16_f32 v92, v98, v99
	v_cvt_pk_bf16_f32 v93, v100, v101
	v_cvt_pk_bf16_f32 v86, v86, v87
	v_cvt_pk_bf16_f32 v87, v88, v89
	v_cvt_pk_bf16_f32 v82, v82, v83
	v_cvt_pk_bf16_f32 v83, v12, v13
	v_mov_b32_e32 v192, v14
	v_mov_b32_e32 v193, v15
	v_mov_b32_e32 v194, v16
	v_mov_b32_e32 v195, v17
	v_lshl_add_u64 v[162:163], v[8:9], 0, v[160:161]
	s_nop 0
	v_permlane16_swap_b32 v192, v194
	v_permlane16_swap_b32 v193, v195
	global_store_dwordx4 v[162:163], v[192:195], off
	v_mov_b32_e32 v196, v84
	v_mov_b32_e32 v197, v85
	v_mov_b32_e32 v198, v90
	v_mov_b32_e32 v199, v91
	v_lshl_add_u64 v[162:163], v[8:9], 0, v[160:161]
	s_nop 0
	v_permlane16_swap_b32 v196, v198
	v_permlane16_swap_b32 v197, v199
	global_store_dwordx4 v[162:163], v[196:199], off offset:256
	v_mov_b32_e32 v188, v10
	v_mov_b32_e32 v189, v11
	v_mov_b32_e32 v190, v92
	v_mov_b32_e32 v191, v93
	v_lshl_add_u64 v[162:163], v[6:7], 0, v[160:161]
	s_nop 0
	v_permlane16_swap_b32 v188, v190
	v_permlane16_swap_b32 v189, v191
	global_store_dwordx4 v[162:163], v[188:191], off
	v_mov_b32_e32 v192, v86
	v_mov_b32_e32 v193, v87
	v_mov_b32_e32 v194, v82
	v_mov_b32_e32 v195, v83
	v_lshl_add_u64 v[162:163], v[6:7], 0, v[160:161]
	s_nop 0
	v_permlane16_swap_b32 v192, v194
	v_permlane16_swap_b32 v193, v195
	global_store_dwordx4 v[162:163], v[192:195], off offset:256
	global_load_dword v14, v[2:3], off offset:512
	global_load_dword v15, v[2:3], off offset:576
	v_add_co_u32_e32 v8, vcc, s76, v4
	v_lshl_add_u64 v[6:7], v[4:5], 0, s[30:31]
	s_nop 0
	v_addc_co_u32_e32 v9, vcc, 0, v5, vcc
	v_add_co_u32_e32 v12, vcc, s77, v4
	v_lshl_add_u64 v[10:11], v[4:5], 0, s[34:35]
	s_nop 0
	v_addc_co_u32_e32 v13, vcc, 0, v5, vcc
	s_and_b64 vcc, exec, s[12:13]
	s_waitcnt vmcnt(0)
	v_mul_f32_e32 v14, 0x3b800000, v14
	v_mul_f32_e32 v16, 0x3b800000, v15
	v_pk_mul_f32 v[78:79], v[78:79], v[14:15] op_sel_hi:[1,0]
	v_pk_mul_f32 v[80:81], v[80:81], v[14:15] op_sel_hi:[1,0]
	v_pk_mul_f32 v[74:75], v[74:75], v[14:15] op_sel_hi:[1,0]
	v_pk_mul_f32 v[76:77], v[76:77], v[14:15] op_sel_hi:[1,0]
	v_pk_mul_f32 v[62:63], v[62:63], v[14:15] op_sel_hi:[1,0]
	v_pk_mul_f32 v[64:65], v[64:65], v[14:15] op_sel_hi:[1,0]
	v_pk_mul_f32 v[58:59], v[58:59], v[14:15] op_sel_hi:[1,0]
	v_pk_mul_f32 v[14:15], v[60:61], v[14:15] op_sel_hi:[1,0]
	v_pk_mul_f32 v[60:61], v[70:71], v[16:17] op_sel_hi:[1,0]
	v_pk_mul_f32 v[70:71], v[72:73], v[16:17] op_sel_hi:[1,0]
	v_pk_mul_f32 v[66:67], v[66:67], v[16:17] op_sel_hi:[1,0]
	v_pk_mul_f32 v[68:69], v[68:69], v[16:17] op_sel_hi:[1,0]
	v_pk_mul_f32 v[54:55], v[54:55], v[16:17] op_sel_hi:[1,0]
	v_pk_mul_f32 v[56:57], v[56:57], v[16:17] op_sel_hi:[1,0]
	v_pk_mul_f32 v[50:51], v[50:51], v[16:17] op_sel_hi:[1,0]
	v_pk_mul_f32 v[16:17], v[52:53], v[16:17] op_sel_hi:[1,0]
	v_cvt_pk_bf16_f32 v52, v78, v79
	v_cvt_pk_bf16_f32 v53, v80, v81
	v_cvt_pk_bf16_f32 v72, v74, v75
	v_cvt_pk_bf16_f32 v73, v76, v77
	v_cvt_pk_bf16_f32 v62, v62, v63
	v_cvt_pk_bf16_f32 v63, v64, v65
	v_cvt_pk_bf16_f32 v58, v58, v59
	v_cvt_pk_bf16_f32 v59, v14, v15
	v_cvt_pk_bf16_f32 v14, v60, v61
	v_cvt_pk_bf16_f32 v15, v70, v71
	v_cvt_pk_bf16_f32 v60, v66, v67
	v_cvt_pk_bf16_f32 v61, v68, v69
	v_cvt_pk_bf16_f32 v54, v54, v55
	v_cvt_pk_bf16_f32 v55, v56, v57
	v_cvt_pk_bf16_f32 v50, v50, v51
	v_cvt_pk_bf16_f32 v51, v16, v17
	global_store_dwordx2 v[8:9], v[52:53], off
	global_store_dwordx2 v[6:7], v[72:73], off offset:32
	v_mov_b32_e32 v196, v62
	v_mov_b32_e32 v197, v63
	v_mov_b32_e32 v198, v58
	v_mov_b32_e32 v199, v59
	v_lshl_add_u64 v[162:163], v[6:7], 0, v[160:161]
	s_nop 0
	v_permlane16_swap_b32 v196, v198
	v_permlane16_swap_b32 v197, v199
	global_store_dwordx4 v[162:163], v[196:199], off offset:256
	global_store_dwordx2 v[12:13], v[14:15], off
	global_store_dwordx2 v[10:11], v[60:61], off offset:32
	v_mov_b32_e32 v188, v54
	v_mov_b32_e32 v189, v55
	v_mov_b32_e32 v190, v50
	v_mov_b32_e32 v191, v51
	v_lshl_add_u64 v[162:163], v[10:11], 0, v[160:161]
	s_nop 0
	v_permlane16_swap_b32 v188, v190
	v_permlane16_swap_b32 v189, v191
	global_store_dwordx4 v[162:163], v[188:191], off offset:256
	global_load_dword v10, v[2:3], off offset:640
	s_nop 0
	global_load_dword v11, v[2:3], off offset:704
	v_add_co_u32_e64 v6, s[12:13], s78, v4
	v_lshl_add_u64 v[2:3], v[4:5], 0, s[36:37]
	s_nop 0
	v_addc_co_u32_e64 v7, s[12:13], 0, v5, s[12:13]
	v_lshl_add_u64 v[8:9], v[4:5], 0, s[26:27]
	v_add_co_u32_e64 v4, s[12:13], s79, v4
	s_waitcnt vmcnt(0)
	v_mul_f32_e32 v10, 0x3b800000, v10
	v_mul_f32_e32 v12, 0x3b800000, v11
	v_pk_mul_f32 v[14:15], v[46:47], v[10:11] op_sel_hi:[1,0]
	v_pk_mul_f32 v[16:17], v[48:49], v[10:11] op_sel_hi:[1,0]
	v_pk_mul_f32 v[42:43], v[42:43], v[10:11] op_sel_hi:[1,0]
	v_pk_mul_f32 v[44:45], v[44:45], v[10:11] op_sel_hi:[1,0]
	v_pk_mul_f32 v[30:31], v[30:31], v[10:11] op_sel_hi:[1,0]
	v_pk_mul_f32 v[32:33], v[32:33], v[10:11] op_sel_hi:[1,0]
	v_pk_mul_f32 v[26:27], v[26:27], v[10:11] op_sel_hi:[1,0]
	v_pk_mul_f32 v[10:11], v[28:29], v[10:11] op_sel_hi:[1,0]
	v_pk_mul_f32 v[28:29], v[38:39], v[12:13] op_sel_hi:[1,0]
	v_pk_mul_f32 v[38:39], v[40:41], v[12:13] op_sel_hi:[1,0]
	v_pk_mul_f32 v[34:35], v[34:35], v[12:13] op_sel_hi:[1,0]
	v_pk_mul_f32 v[36:37], v[36:37], v[12:13] op_sel_hi:[1,0]
	v_pk_mul_f32 v[22:23], v[22:23], v[12:13] op_sel_hi:[1,0]
	v_pk_mul_f32 v[24:25], v[24:25], v[12:13] op_sel_hi:[1,0]
	v_pk_mul_f32 v[18:19], v[18:19], v[12:13] op_sel_hi:[1,0]
	v_pk_mul_f32 v[12:13], v[20:21], v[12:13] op_sel_hi:[1,0]
	v_cvt_pk_bf16_f32 v14, v14, v15
	v_cvt_pk_bf16_f32 v15, v16, v17
	v_addc_co_u32_e64 v5, s[12:13], 0, v5, s[12:13]
	v_cvt_pk_bf16_f32 v16, v42, v43
	v_cvt_pk_bf16_f32 v17, v44, v45
	v_cvt_pk_bf16_f32 v20, v30, v31
	v_cvt_pk_bf16_f32 v21, v32, v33
	v_cvt_pk_bf16_f32 v26, v26, v27
	v_cvt_pk_bf16_f32 v27, v10, v11
	v_cvt_pk_bf16_f32 v10, v28, v29
	v_cvt_pk_bf16_f32 v11, v38, v39
	v_cvt_pk_bf16_f32 v28, v34, v35
	v_cvt_pk_bf16_f32 v29, v36, v37
	v_cvt_pk_bf16_f32 v22, v22, v23
	v_cvt_pk_bf16_f32 v23, v24, v25
	v_cvt_pk_bf16_f32 v18, v18, v19
	v_cvt_pk_bf16_f32 v19, v12, v13
	global_store_dwordx2 v[6:7], v[14:15], off
	global_store_dwordx2 v[2:3], v[16:17], off offset:32
	v_mov_b32_e32 v192, v20
	v_mov_b32_e32 v193, v21
	v_mov_b32_e32 v194, v26
	v_mov_b32_e32 v195, v27
	v_lshl_add_u64 v[162:163], v[2:3], 0, v[160:161]
	s_nop 0
	v_permlane16_swap_b32 v192, v194
	v_permlane16_swap_b32 v193, v195
	global_store_dwordx4 v[162:163], v[192:195], off offset:256
	global_store_dwordx2 v[4:5], v[10:11], off
	global_store_dwordx2 v[8:9], v[28:29], off offset:32
	v_mov_b32_e32 v196, v22
	v_mov_b32_e32 v197, v23
	v_mov_b32_e32 v198, v18
	v_mov_b32_e32 v199, v19
	v_lshl_add_u64 v[162:163], v[8:9], 0, v[160:161]
	s_nop 0
	v_permlane16_swap_b32 v196, v198
	v_permlane16_swap_b32 v197, v199
	global_store_dwordx4 v[162:163], v[196:199], off offset:256
	s_cbranch_vccz .LBB0_3112
	s_waitcnt vmcnt(0)
	s_cmpk_gt_u32 s3, 0xff
	s_cbranch_scc1 .LBB0_3127
	s_barrier

.LBB0_3420:
	ds_read_b128 v[2:5], v167
	ds_read_b128 v[6:9], v171
	ds_read_b128 v[10:13], v172
	ds_read_b128 v[14:17], v173
	s_add_u32 s0, s36, 0xfffe0080
	s_addc_u32 s1, s37, -1
	s_cmp_eq_u32 s76, 4
	s_cselect_b32 s41, s27, s1
	s_cselect_b32 s40, s72, s0
	s_cselect_b32 s39, s25, s75
	s_cselect_b32 s38, s73, s74
	v_lshl_add_u64 v[158:159], s[36:37], 0, v[152:153]
	s_add_i32 m0, s35, 0xc000
	ds_read_b128 v[186:189], v184
	ds_read_b128 v[190:193], v184 offset:1024
	ds_read_b128 v[194:197], v184 offset:2048
	ds_read_b128 v[198:201], v184 offset:3072
	ds_read_b128 v[202:205], v184 offset:4096
	ds_read_b128 v[206:209], v184 offset:5120
	ds_read_b128 v[210:213], v184 offset:6144
	ds_read_b128 v[214:217], v184 offset:7168
	global_load_lds_dwordx4 v[158:159], off
	v_lshl_add_u64 v[158:159], s[36:37], 0, v[150:151]
	s_add_i32 m0, s35, 0xe000
	s_nop 0
	global_load_lds_dwordx4 v[158:159], off
	s_waitcnt lgkmcnt(8)
	s_barrier
	s_waitcnt lgkmcnt(0)
	s_setprio 1
	s_waitcnt lgkmcnt(0)
	v_mfma_f32_16x16x128_f8f6f4 v[142:145], v[2:9], v[186:193], v[142:145]
	v_mfma_f32_16x16x128_f8f6f4 v[138:141], v[10:17], v[186:193], v[138:141]
	v_mfma_f32_16x16x128_f8f6f4 v[134:137], v[2:9], v[194:201], v[134:137]
	v_mfma_f32_16x16x128_f8f6f4 v[126:129], v[10:17], v[194:201], v[126:129]
	v_mfma_f32_16x16x128_f8f6f4 v[118:121], v[2:9], v[202:209], v[118:121]
	v_mfma_f32_16x16x128_f8f6f4 v[110:113], v[10:17], v[202:209], v[110:113]
	v_mfma_f32_16x16x128_f8f6f4 v[102:105], v[2:9], v[210:217], v[102:105]
	v_mfma_f32_16x16x128_f8f6f4 v[94:97], v[10:17], v[210:217], v[94:97]
	s_setprio 0
	s_barrier
	s_mov_b32 m0, s43
	v_lshl_add_u64 v[158:159], s[38:39], 0, v[148:149]
	ds_read_b128 v[220:223], v168
	ds_read_b128 v[224:227], v174
	ds_read_b128 v[228:231], v175
	ds_read_b128 v[232:235], v176
	global_load_lds_dwordx4 v[158:159], off
	v_lshl_add_u64 v[160:161], s[38:39], 0, v[146:147]
	s_mov_b32 m0, s44
	s_nop 0
	global_load_lds_dwordx4 v[160:161], off
	s_barrier
	s_waitcnt lgkmcnt(0)
	s_setprio 1
	s_waitcnt lgkmcnt(0)
	v_mfma_f32_16x16x128_f8f6f4 v[130:133], v[220:227], v[186:193], v[130:133]
	v_mfma_f32_16x16x128_f8f6f4 v[122:125], v[228:235], v[186:193], v[122:125]
	v_mfma_f32_16x16x128_f8f6f4 v[114:117], v[220:227], v[194:201], v[114:117]
	v_mfma_f32_16x16x128_f8f6f4 v[106:109], v[228:235], v[194:201], v[106:109]
	v_mfma_f32_16x16x128_f8f6f4 v[98:101], v[220:227], v[202:209], v[98:101]
	v_mfma_f32_16x16x128_f8f6f4 v[90:93], v[228:235], v[202:209], v[90:93]
	v_mfma_f32_16x16x128_f8f6f4 v[86:89], v[220:227], v[210:217], v[86:89]
	v_mfma_f32_16x16x128_f8f6f4 v[82:85], v[228:235], v[210:217], v[82:85]
	s_setprio 0
	s_mov_b32 m0, s35
	v_lshl_add_u64 v[162:163], s[40:41], 0, v[148:149]
	s_barrier
	ds_read_b128 v[186:189], v184 offset:16384
	ds_read_b128 v[190:193], v184 offset:17408
	ds_read_b128 v[194:197], v184 offset:18432
	ds_read_b128 v[198:201], v184 offset:19456
	ds_read_b128 v[202:205], v184 offset:20480
	ds_read_b128 v[206:209], v184 offset:21504
	ds_read_b128 v[210:213], v184 offset:22528
	ds_read_b128 v[214:217], v184 offset:23552
	global_load_lds_dwordx4 v[162:163], off
	v_lshl_add_u64 v[164:165], s[40:41], 0, v[146:147]
	s_mov_b32 m0, s45
	s_nop 0
	global_load_lds_dwordx4 v[164:165], off
	s_barrier
	s_waitcnt lgkmcnt(0)
	s_setprio 1
	s_waitcnt lgkmcnt(0)
	v_mfma_f32_16x16x128_f8f6f4 v[78:81], v[2:9], v[186:193], v[78:81]
	v_mfma_f32_16x16x128_f8f6f4 v[74:77], v[10:17], v[186:193], v[74:77]
	v_mfma_f32_16x16x128_f8f6f4 v[70:73], v[2:9], v[194:201], v[70:73]
	v_mfma_f32_16x16x128_f8f6f4 v[62:65], v[10:17], v[194:201], v[62:65]
	v_mfma_f32_16x16x128_f8f6f4 v[54:57], v[2:9], v[202:209], v[54:57]
	v_mfma_f32_16x16x128_f8f6f4 v[46:49], v[10:17], v[202:209], v[46:49]
	v_mfma_f32_16x16x128_f8f6f4 v[38:41], v[2:9], v[210:217], v[38:41]
	v_mfma_f32_16x16x128_f8f6f4 v[30:33], v[10:17], v[210:217], v[30:33]
	s_setprio 0
	s_barrier
	s_add_u32 s78, s38, 0x20000
	s_addc_u32 s79, s39, 0
	s_mov_b32 m0, s46
	v_lshl_add_u64 v[2:3], s[78:79], 0, v[148:149]
	global_load_lds_dwordx4 v[2:3], off
	v_lshl_add_u64 v[2:3], s[78:79], 0, v[146:147]
	s_mov_b32 m0, s47
	s_nop 0
	global_load_lds_dwordx4 v[2:3], off
	s_waitcnt vmcnt(6)
	s_barrier
	s_setprio 1
	v_mfma_f32_16x16x128_f8f6f4 v[66:69], v[220:227], v[186:193], v[66:69]
	v_mfma_f32_16x16x128_f8f6f4 v[58:61], v[228:235], v[186:193], v[58:61]
	v_mfma_f32_16x16x128_f8f6f4 v[50:53], v[220:227], v[194:201], v[50:53]
	v_mfma_f32_16x16x128_f8f6f4 v[42:45], v[228:235], v[194:201], v[42:45]
	v_mfma_f32_16x16x128_f8f6f4 v[34:37], v[220:227], v[202:209], v[34:37]
	v_mfma_f32_16x16x128_f8f6f4 v[26:29], v[228:235], v[202:209], v[26:29]
	v_mfma_f32_16x16x128_f8f6f4 v[22:25], v[220:227], v[210:217], v[22:25]
	v_mfma_f32_16x16x128_f8f6f4 v[18:21], v[228:235], v[210:217], v[18:21]
	s_setprio 0
	s_barrier
	ds_read_b128 v[2:5], v169
	ds_read_b128 v[6:9], v177
	ds_read_b128 v[10:13], v178
	ds_read_b128 v[14:17], v179
	s_add_u32 s40, s40, 0x20000
	s_addc_u32 s41, s41, 0
	s_mov_b32 m0, s48
	v_lshl_add_u64 v[220:221], s[40:41], 0, v[148:149]
	ds_read_b128 v[186:189], v184 offset:32768
	ds_read_b128 v[190:193], v184 offset:33792
	ds_read_b128 v[194:197], v184 offset:34816
	ds_read_b128 v[198:201], v184 offset:35840
	ds_read_b128 v[202:205], v184 offset:36864
	ds_read_b128 v[206:209], v184 offset:37888
	ds_read_b128 v[210:213], v184 offset:38912
	ds_read_b128 v[214:217], v184 offset:39936
	global_load_lds_dwordx4 v[220:221], off
	v_lshl_add_u64 v[220:221], s[40:41], 0, v[146:147]
	s_mov_b32 m0, s49
	s_nop 0
	global_load_lds_dwordx4 v[220:221], off
	s_waitcnt lgkmcnt(8)
	s_barrier
	s_waitcnt lgkmcnt(0)
	s_setprio 1
	s_waitcnt lgkmcnt(0)
	v_mfma_f32_16x16x128_f8f6f4 v[142:145], v[2:9], v[186:193], v[142:145]
	v_mfma_f32_16x16x128_f8f6f4 v[138:141], v[10:17], v[186:193], v[138:141]
	v_mfma_f32_16x16x128_f8f6f4 v[134:137], v[2:9], v[194:201], v[134:137]
	v_mfma_f32_16x16x128_f8f6f4 v[126:129], v[10:17], v[194:201], v[126:129]
	v_mfma_f32_16x16x128_f8f6f4 v[118:121], v[2:9], v[202:209], v[118:121]
	v_mfma_f32_16x16x128_f8f6f4 v[110:113], v[10:17], v[202:209], v[110:113]
	v_mfma_f32_16x16x128_f8f6f4 v[102:105], v[2:9], v[210:217], v[102:105]
	v_mfma_f32_16x16x128_f8f6f4 v[94:97], v[10:17], v[210:217], v[94:97]
	s_setprio 0
	s_barrier
	s_mov_b32 m0, s55
	v_lshl_add_u64 v[158:159], v[158:159], 0, s[20:21]
	ds_read_b128 v[220:223], v170
	ds_read_b128 v[224:227], v180
	ds_read_b128 v[228:231], v181
	ds_read_b128 v[232:235], v182
	global_load_lds_dwordx4 v[158:159], off
	v_lshl_add_u64 v[158:159], v[160:161], 0, s[20:21]
	s_mov_b32 m0, s64
	s_nop 0
	global_load_lds_dwordx4 v[158:159], off
	s_barrier
	s_waitcnt lgkmcnt(0)
	s_setprio 1
	s_waitcnt lgkmcnt(0)
	v_mfma_f32_16x16x128_f8f6f4 v[130:133], v[220:227], v[186:193], v[130:133]
	v_mfma_f32_16x16x128_f8f6f4 v[122:125], v[228:235], v[186:193], v[122:125]
	v_mfma_f32_16x16x128_f8f6f4 v[114:117], v[220:227], v[194:201], v[114:117]
	v_mfma_f32_16x16x128_f8f6f4 v[106:109], v[228:235], v[194:201], v[106:109]
	v_mfma_f32_16x16x128_f8f6f4 v[98:101], v[220:227], v[202:209], v[98:101]
	v_mfma_f32_16x16x128_f8f6f4 v[90:93], v[228:235], v[202:209], v[90:93]
	v_mfma_f32_16x16x128_f8f6f4 v[86:89], v[220:227], v[210:217], v[86:89]
	v_mfma_f32_16x16x128_f8f6f4 v[82:85], v[228:235], v[210:217], v[82:85]
	s_setprio 0
	s_mov_b32 m0, s65
	v_lshl_add_u64 v[158:159], v[162:163], 0, s[20:21]
	s_barrier
	ds_read_b128 v[186:189], v184 offset:49152
	ds_read_b128 v[190:193], v184 offset:50176
	ds_read_b128 v[194:197], v184 offset:51200
	ds_read_b128 v[198:201], v184 offset:52224
	ds_read_b128 v[202:205], v184 offset:53248
	ds_read_b128 v[206:209], v184 offset:54272
	ds_read_b128 v[210:213], v184 offset:55296
	ds_read_b128 v[214:217], v184 offset:56320
	global_load_lds_dwordx4 v[158:159], off
	v_lshl_add_u64 v[158:159], v[164:165], 0, s[20:21]
	s_mov_b32 m0, s66
	s_nop 0
	global_load_lds_dwordx4 v[158:159], off
	s_barrier
	s_waitcnt lgkmcnt(0)
	s_setprio 1
	s_waitcnt lgkmcnt(0)
	v_mfma_f32_16x16x128_f8f6f4 v[78:81], v[2:9], v[186:193], v[78:81]
	v_mfma_f32_16x16x128_f8f6f4 v[74:77], v[10:17], v[186:193], v[74:77]
	v_mfma_f32_16x16x128_f8f6f4 v[70:73], v[2:9], v[194:201], v[70:73]
	v_mfma_f32_16x16x128_f8f6f4 v[62:65], v[10:17], v[194:201], v[62:65]
	v_mfma_f32_16x16x128_f8f6f4 v[54:57], v[2:9], v[202:209], v[54:57]
	v_mfma_f32_16x16x128_f8f6f4 v[46:49], v[10:17], v[202:209], v[46:49]
	v_mfma_f32_16x16x128_f8f6f4 v[38:41], v[2:9], v[210:217], v[38:41]
	v_mfma_f32_16x16x128_f8f6f4 v[30:33], v[10:17], v[210:217], v[30:33]
	s_setprio 0
	s_barrier
	s_add_u32 s38, s38, 0x20080
	s_addc_u32 s39, s39, 0
	s_mov_b32 m0, s67
	v_lshl_add_u64 v[2:3], s[38:39], 0, v[148:149]
	global_load_lds_dwordx4 v[2:3], off
	v_lshl_add_u64 v[2:3], s[38:39], 0, v[146:147]
	s_mov_b32 m0, s68
	s_nop 0
	global_load_lds_dwordx4 v[2:3], off
	s_waitcnt vmcnt(6)
	s_barrier
	s_setprio 1
	v_mfma_f32_16x16x128_f8f6f4 v[66:69], v[220:227], v[186:193], v[66:69]
	v_mfma_f32_16x16x128_f8f6f4 v[58:61], v[228:235], v[186:193], v[58:61]
	v_mfma_f32_16x16x128_f8f6f4 v[50:53], v[220:227], v[194:201], v[50:53]
	v_mfma_f32_16x16x128_f8f6f4 v[42:45], v[228:235], v[194:201], v[42:45]
	v_mfma_f32_16x16x128_f8f6f4 v[34:37], v[220:227], v[202:209], v[34:37]
	v_mfma_f32_16x16x128_f8f6f4 v[26:29], v[228:235], v[202:209], v[26:29]
	v_mfma_f32_16x16x128_f8f6f4 v[22:25], v[220:227], v[210:217], v[22:25]
	v_mfma_f32_16x16x128_f8f6f4 v[18:21], v[228:235], v[210:217], v[18:21]
	s_setprio 0
	s_add_i32 s76, s76, 2
	s_add_u32 s74, s74, 0x100
	s_addc_u32 s75, s75, 0
	s_add_u32 s36, s36, 0x100
	s_addc_u32 s37, s37, 0
	s_cmp_gt_u32 s76, 5
	s_barrier
	s_cbranch_scc0 .LBB0_3420
	v_bfe_u32 v160, v0, 4, 1
	v_mul_u32_u24_e32 v160, 24, v160
	v_mov_b32_e32 v161, 0
	v_lshl_or_b32 v4, s71, 8, v183
	v_pk_mul_f32 v[2:3], v[144:145], s[22:23] op_sel_hi:[1,0]
	v_pk_mul_f32 v[6:7], v[142:143], s[22:23] op_sel_hi:[1,0]
	v_lshl_add_u32 v12, s34, 8, v166
	v_cvt_pk_bf16_f32 v6, v6, v7
	v_cvt_pk_bf16_f32 v7, v2, v3
	v_mov_b64_e32 v[2:3], s[16:17]
	v_ashrrev_i32_e32 v5, 31, v4
	v_mad_i64_i32 v[8:9], s[36:37], v12, s70, v[2:3]
	v_lshlrev_b64 v[4:5], 1, v[4:5]
	v_lshl_add_u64 v[8:9], v[8:9], 0, v[4:5]
	s_nop 15
	s_nop 15
	v_mov_b32_e32 v188, v6
	v_mov_b32_e32 v189, v7
	v_pk_mul_f32 v[6:7], v[140:141], s[22:23] op_sel_hi:[1,0]
	v_pk_mul_f32 v[10:11], v[138:139], s[22:23] op_sel_hi:[1,0]
	s_and_b64 vcc, exec, s[12:13]
	v_cvt_pk_bf16_f32 v10, v10, v11
	v_cvt_pk_bf16_f32 v11, v6, v7
	v_mov_b32_e32 v190, v10
	v_mov_b32_e32 v191, v11
	v_lshl_add_u64 v[162:163], v[8:9], 0, v[160:161]
	s_nop 0
	v_permlane16_swap_b32 v188, v190
	v_permlane16_swap_b32 v189, v191
	global_store_dwordx4 v[162:163], v[188:191], off
	v_pk_mul_f32 v[6:7], v[132:133], s[22:23] op_sel_hi:[1,0]
	v_pk_mul_f32 v[10:11], v[130:131], s[22:23] op_sel_hi:[1,0]
	s_mov_b32 s71, s24
	v_cvt_pk_bf16_f32 v10, v10, v11
	v_cvt_pk_bf16_f32 v11, v6, v7
	v_mov_b32_e32 v192, v10
	v_mov_b32_e32 v193, v11
	v_pk_mul_f32 v[6:7], v[124:125], s[22:23] op_sel_hi:[1,0]
	v_pk_mul_f32 v[10:11], v[122:123], s[22:23] op_sel_hi:[1,0]
	s_mov_b32 s34, s26
	v_cvt_pk_bf16_f32 v10, v10, v11
	v_cvt_pk_bf16_f32 v11, v6, v7
	v_mov_b32_e32 v194, v10
	v_mov_b32_e32 v195, v11
	v_lshl_add_u64 v[162:163], v[8:9], 0, v[160:161]
	s_nop 0
	v_permlane16_swap_b32 v192, v194
	v_permlane16_swap_b32 v193, v195
	global_store_dwordx4 v[162:163], v[192:195], off offset:256
	v_or_b32_e32 v10, 16, v12
	v_pk_mul_f32 v[6:7], v[136:137], s[22:23] op_sel_hi:[1,0]
	v_pk_mul_f32 v[8:9], v[134:135], s[22:23] op_sel_hi:[1,0]
	s_mov_b64 s[38:39], s[28:29]
	v_cvt_pk_bf16_f32 v8, v8, v9
	v_cvt_pk_bf16_f32 v9, v6, v7
	v_mad_i64_i32 v[6:7], s[36:37], v10, s70, v[2:3]
	v_lshl_add_u64 v[6:7], v[6:7], 0, v[4:5]
	v_mov_b32_e32 v196, v8
	v_mov_b32_e32 v197, v9
	v_pk_mul_f32 v[8:9], v[128:129], s[22:23] op_sel_hi:[1,0]
	v_pk_mul_f32 v[10:11], v[126:127], s[22:23] op_sel_hi:[1,0]
	s_nop 0
	v_cvt_pk_bf16_f32 v10, v10, v11
	v_cvt_pk_bf16_f32 v11, v8, v9
	v_mov_b32_e32 v198, v10
	v_mov_b32_e32 v199, v11
	v_lshl_add_u64 v[162:163], v[6:7], 0, v[160:161]
	s_nop 0
	v_permlane16_swap_b32 v196, v198
	v_permlane16_swap_b32 v197, v199
	global_store_dwordx4 v[162:163], v[196:199], off
	v_pk_mul_f32 v[8:9], v[116:117], s[22:23] op_sel_hi:[1,0]
	v_pk_mul_f32 v[10:11], v[114:115], s[22:23] op_sel_hi:[1,0]
	s_nop 0
	v_cvt_pk_bf16_f32 v10, v10, v11
	v_cvt_pk_bf16_f32 v11, v8, v9
	v_mov_b32_e32 v188, v10
	v_mov_b32_e32 v189, v11
	v_pk_mul_f32 v[8:9], v[108:109], s[22:23] op_sel_hi:[1,0]
	v_pk_mul_f32 v[10:11], v[106:107], s[22:23] op_sel_hi:[1,0]
	s_nop 0
	v_cvt_pk_bf16_f32 v10, v10, v11
	v_cvt_pk_bf16_f32 v11, v8, v9
	v_mov_b32_e32 v190, v10
	v_mov_b32_e32 v191, v11
	v_lshl_add_u64 v[162:163], v[6:7], 0, v[160:161]
	s_nop 0
	v_permlane16_swap_b32 v188, v190
	v_permlane16_swap_b32 v189, v191
	global_store_dwordx4 v[162:163], v[188:191], off offset:256
	v_or_b32_e32 v10, 32, v12
	v_pk_mul_f32 v[6:7], v[120:121], s[22:23] op_sel_hi:[1,0]
	v_pk_mul_f32 v[8:9], v[118:119], s[22:23] op_sel_hi:[1,0]
	s_nop 0
	v_cvt_pk_bf16_f32 v8, v8, v9
	v_cvt_pk_bf16_f32 v9, v6, v7
	v_mad_i64_i32 v[6:7], s[36:37], v10, s70, v[2:3]
	v_lshl_add_u64 v[6:7], v[6:7], 0, v[4:5]
	v_mov_b32_e32 v192, v8
	v_mov_b32_e32 v193, v9
	v_pk_mul_f32 v[8:9], v[112:113], s[22:23] op_sel_hi:[1,0]
	v_pk_mul_f32 v[10:11], v[110:111], s[22:23] op_sel_hi:[1,0]
	s_nop 0
	v_cvt_pk_bf16_f32 v10, v10, v11
	v_cvt_pk_bf16_f32 v11, v8, v9
	v_mov_b32_e32 v194, v10
	v_mov_b32_e32 v195, v11
	v_lshl_add_u64 v[162:163], v[6:7], 0, v[160:161]
	s_nop 0
	v_permlane16_swap_b32 v192, v194
	v_permlane16_swap_b32 v193, v195
	global_store_dwordx4 v[162:163], v[192:195], off
	v_pk_mul_f32 v[8:9], v[100:101], s[22:23] op_sel_hi:[1,0]
	v_pk_mul_f32 v[10:11], v[98:99], s[22:23] op_sel_hi:[1,0]
	s_nop 0
	v_cvt_pk_bf16_f32 v10, v10, v11
	v_cvt_pk_bf16_f32 v11, v8, v9
	v_mov_b32_e32 v196, v10
	v_mov_b32_e32 v197, v11
	v_pk_mul_f32 v[8:9], v[92:93], s[22:23] op_sel_hi:[1,0]
	v_pk_mul_f32 v[10:11], v[90:91], s[22:23] op_sel_hi:[1,0]
	s_nop 0
	v_cvt_pk_bf16_f32 v10, v10, v11
	v_cvt_pk_bf16_f32 v11, v8, v9
	v_mov_b32_e32 v198, v10
	v_mov_b32_e32 v199, v11
	v_lshl_add_u64 v[162:163], v[6:7], 0, v[160:161]
	s_nop 0
	v_permlane16_swap_b32 v196, v198
	v_permlane16_swap_b32 v197, v199
	global_store_dwordx4 v[162:163], v[196:199], off offset:256
	v_or_b32_e32 v10, 48, v12
	v_pk_mul_f32 v[6:7], v[104:105], s[22:23] op_sel_hi:[1,0]
	v_pk_mul_f32 v[8:9], v[102:103], s[22:23] op_sel_hi:[1,0]
	s_nop 0
	v_cvt_pk_bf16_f32 v8, v8, v9
	v_cvt_pk_bf16_f32 v9, v6, v7
	v_mad_i64_i32 v[6:7], s[36:37], v10, s70, v[2:3]
	v_lshl_add_u64 v[6:7], v[6:7], 0, v[4:5]
	v_mov_b32_e32 v188, v8
	v_mov_b32_e32 v189, v9
	v_pk_mul_f32 v[8:9], v[96:97], s[22:23] op_sel_hi:[1,0]
	v_pk_mul_f32 v[10:11], v[94:95], s[22:23] op_sel_hi:[1,0]
	s_nop 0
	v_cvt_pk_bf16_f32 v10, v10, v11
	v_cvt_pk_bf16_f32 v11, v8, v9
	v_mov_b32_e32 v190, v10
	v_mov_b32_e32 v191, v11
	v_lshl_add_u64 v[162:163], v[6:7], 0, v[160:161]
	s_nop 0
	v_permlane16_swap_b32 v188, v190
	v_permlane16_swap_b32 v189, v191
	global_store_dwordx4 v[162:163], v[188:191], off
	v_pk_mul_f32 v[8:9], v[88:89], s[22:23] op_sel_hi:[1,0]
	v_pk_mul_f32 v[10:11], v[86:87], s[22:23] op_sel_hi:[1,0]
	s_nop 0
	v_cvt_pk_bf16_f32 v10, v10, v11
	v_cvt_pk_bf16_f32 v11, v8, v9
	v_mov_b32_e32 v192, v10
	v_mov_b32_e32 v193, v11
	v_pk_mul_f32 v[8:9], v[84:85], s[22:23] op_sel_hi:[1,0]
	v_pk_mul_f32 v[10:11], v[82:83], s[22:23] op_sel_hi:[1,0]
	s_nop 0
	v_cvt_pk_bf16_f32 v10, v10, v11
	v_cvt_pk_bf16_f32 v11, v8, v9
	v_mov_b32_e32 v194, v10
	v_mov_b32_e32 v195, v11
	v_lshl_add_u64 v[162:163], v[6:7], 0, v[160:161]
	s_nop 0
	v_permlane16_swap_b32 v192, v194
	v_permlane16_swap_b32 v193, v195
	global_store_dwordx4 v[162:163], v[192:195], off offset:256
	v_add_u32_e32 v10, 0x80, v12
	v_pk_mul_f32 v[6:7], v[80:81], s[22:23] op_sel_hi:[1,0]
	v_pk_mul_f32 v[8:9], v[78:79], s[22:23] op_sel_hi:[1,0]
	s_nop 0
	v_cvt_pk_bf16_f32 v8, v8, v9
	v_cvt_pk_bf16_f32 v9, v6, v7
	v_mad_i64_i32 v[6:7], s[36:37], v10, s70, v[2:3]
	v_lshl_add_u64 v[6:7], v[6:7], 0, v[4:5]
	v_mov_b32_e32 v196, v8
	v_mov_b32_e32 v197, v9
	v_pk_mul_f32 v[8:9], v[76:77], s[22:23] op_sel_hi:[1,0]
	v_pk_mul_f32 v[10:11], v[74:75], s[22:23] op_sel_hi:[1,0]
	s_nop 0
	v_cvt_pk_bf16_f32 v10, v10, v11
	v_cvt_pk_bf16_f32 v11, v8, v9
	v_mov_b32_e32 v198, v10
	v_mov_b32_e32 v199, v11
	v_lshl_add_u64 v[162:163], v[6:7], 0, v[160:161]
	s_nop 0
	v_permlane16_swap_b32 v196, v198
	v_permlane16_swap_b32 v197, v199
	global_store_dwordx4 v[162:163], v[196:199], off
	v_pk_mul_f32 v[8:9], v[68:69], s[22:23] op_sel_hi:[1,0]
	v_pk_mul_f32 v[10:11], v[66:67], s[22:23] op_sel_hi:[1,0]
	s_nop 0
	v_cvt_pk_bf16_f32 v10, v10, v11
	v_cvt_pk_bf16_f32 v11, v8, v9
	v_mov_b32_e32 v188, v10
	v_mov_b32_e32 v189, v11
	v_pk_mul_f32 v[8:9], v[60:61], s[22:23] op_sel_hi:[1,0]
	v_pk_mul_f32 v[10:11], v[58:59], s[22:23] op_sel_hi:[1,0]
	s_nop 0
	v_cvt_pk_bf16_f32 v10, v10, v11
	v_cvt_pk_bf16_f32 v11, v8, v9
	v_mov_b32_e32 v190, v10
	v_mov_b32_e32 v191, v11
	v_lshl_add_u64 v[162:163], v[6:7], 0, v[160:161]
	s_nop 0
	v_permlane16_swap_b32 v188, v190
	v_permlane16_swap_b32 v189, v191
	global_store_dwordx4 v[162:163], v[188:191], off offset:256
	v_add_u32_e32 v10, 0x90, v12
	v_pk_mul_f32 v[6:7], v[72:73], s[22:23] op_sel_hi:[1,0]
	v_pk_mul_f32 v[8:9], v[70:71], s[22:23] op_sel_hi:[1,0]
	s_nop 0
	v_cvt_pk_bf16_f32 v8, v8, v9
	v_cvt_pk_bf16_f32 v9, v6, v7
	v_mad_i64_i32 v[6:7], s[36:37], v10, s70, v[2:3]
	v_lshl_add_u64 v[6:7], v[6:7], 0, v[4:5]
	v_mov_b32_e32 v192, v8
	v_mov_b32_e32 v193, v9
	v_pk_mul_f32 v[8:9], v[64:65], s[22:23] op_sel_hi:[1,0]
	v_pk_mul_f32 v[10:11], v[62:63], s[22:23] op_sel_hi:[1,0]
	s_nop 0
	v_cvt_pk_bf16_f32 v10, v10, v11
	v_cvt_pk_bf16_f32 v11, v8, v9
	v_mov_b32_e32 v194, v10
	v_mov_b32_e32 v195, v11
	v_lshl_add_u64 v[162:163], v[6:7], 0, v[160:161]
	s_nop 0
	v_permlane16_swap_b32 v192, v194
	v_permlane16_swap_b32 v193, v195
	global_store_dwordx4 v[162:163], v[192:195], off
	v_pk_mul_f32 v[8:9], v[52:53], s[22:23] op_sel_hi:[1,0]
	v_pk_mul_f32 v[10:11], v[50:51], s[22:23] op_sel_hi:[1,0]
	s_nop 0
	v_cvt_pk_bf16_f32 v10, v10, v11
	v_cvt_pk_bf16_f32 v11, v8, v9
	v_mov_b32_e32 v196, v10
	v_mov_b32_e32 v197, v11
	v_pk_mul_f32 v[8:9], v[44:45], s[22:23] op_sel_hi:[1,0]
	v_pk_mul_f32 v[10:11], v[42:43], s[22:23] op_sel_hi:[1,0]
	s_nop 0
	v_cvt_pk_bf16_f32 v10, v10, v11
	v_cvt_pk_bf16_f32 v11, v8, v9
	v_mov_b32_e32 v198, v10
	v_mov_b32_e32 v199, v11
	v_lshl_add_u64 v[162:163], v[6:7], 0, v[160:161]
	s_nop 0
	v_permlane16_swap_b32 v196, v198
	v_permlane16_swap_b32 v197, v199
	global_store_dwordx4 v[162:163], v[196:199], off offset:256
	v_add_u32_e32 v10, 0xa0, v12
	v_pk_mul_f32 v[6:7], v[56:57], s[22:23] op_sel_hi:[1,0]
	v_pk_mul_f32 v[8:9], v[54:55], s[22:23] op_sel_hi:[1,0]
	s_nop 0
	v_cvt_pk_bf16_f32 v8, v8, v9
	v_cvt_pk_bf16_f32 v9, v6, v7
	v_mad_i64_i32 v[6:7], s[36:37], v10, s70, v[2:3]
	v_lshl_add_u64 v[6:7], v[6:7], 0, v[4:5]
	v_mov_b32_e32 v188, v8
	v_mov_b32_e32 v189, v9
	v_pk_mul_f32 v[8:9], v[48:49], s[22:23] op_sel_hi:[1,0]
	v_pk_mul_f32 v[10:11], v[46:47], s[22:23] op_sel_hi:[1,0]
	s_nop 0
	v_cvt_pk_bf16_f32 v10, v10, v11
	v_cvt_pk_bf16_f32 v11, v8, v9
	v_mov_b32_e32 v190, v10
	v_mov_b32_e32 v191, v11
	v_lshl_add_u64 v[162:163], v[6:7], 0, v[160:161]
	s_nop 0
	v_permlane16_swap_b32 v188, v190
	v_permlane16_swap_b32 v189, v191
	global_store_dwordx4 v[162:163], v[188:191], off
	v_pk_mul_f32 v[8:9], v[36:37], s[22:23] op_sel_hi:[1,0]
	v_pk_mul_f32 v[10:11], v[34:35], s[22:23] op_sel_hi:[1,0]
	s_nop 0
	v_cvt_pk_bf16_f32 v10, v10, v11
	v_cvt_pk_bf16_f32 v11, v8, v9
	v_mov_b32_e32 v192, v10
	v_mov_b32_e32 v193, v11
	v_pk_mul_f32 v[8:9], v[28:29], s[22:23] op_sel_hi:[1,0]
	v_pk_mul_f32 v[10:11], v[26:27], s[22:23] op_sel_hi:[1,0]
	s_nop 0
	v_cvt_pk_bf16_f32 v10, v10, v11
	v_cvt_pk_bf16_f32 v11, v8, v9
	v_mov_b32_e32 v194, v10
	v_mov_b32_e32 v195, v11
	v_lshl_add_u64 v[162:163], v[6:7], 0, v[160:161]
	s_nop 0
	v_permlane16_swap_b32 v192, v194
	v_permlane16_swap_b32 v193, v195
	global_store_dwordx4 v[162:163], v[192:195], off offset:256
	v_add_u32_e32 v10, 0xb0, v12
	v_pk_mul_f32 v[6:7], v[40:41], s[22:23] op_sel_hi:[1,0]
	v_pk_mul_f32 v[8:9], v[38:39], s[22:23] op_sel_hi:[1,0]
	v_mad_i64_i32 v[2:3], s[36:37], v10, s70, v[2:3]
	v_cvt_pk_bf16_f32 v8, v8, v9
	v_cvt_pk_bf16_f32 v9, v6, v7
	v_lshl_add_u64 v[2:3], v[2:3], 0, v[4:5]
	v_pk_mul_f32 v[4:5], v[32:33], s[22:23] op_sel_hi:[1,0]
	v_pk_mul_f32 v[6:7], v[30:31], s[22:23] op_sel_hi:[1,0]
	s_mov_b64 s[36:37], s[30:31]
	v_cvt_pk_bf16_f32 v6, v6, v7
	v_cvt_pk_bf16_f32 v7, v4, v5
	v_mov_b32_e32 v198, v6
	v_mov_b32_e32 v199, v7
	v_pk_mul_f32 v[4:5], v[24:25], s[22:23] op_sel_hi:[1,0]
	v_pk_mul_f32 v[6:7], v[22:23], s[22:23] op_sel_hi:[1,0]
	v_mov_b32_e32 v196, v8
	v_mov_b32_e32 v197, v9
	v_lshl_add_u64 v[162:163], v[2:3], 0, v[160:161]
	s_nop 0
	v_permlane16_swap_b32 v196, v198
	v_permlane16_swap_b32 v197, v199
	global_store_dwordx4 v[162:163], v[196:199], off
	v_cvt_pk_bf16_f32 v6, v6, v7
	v_cvt_pk_bf16_f32 v7, v4, v5
	v_mov_b32_e32 v188, v6
	v_mov_b32_e32 v189, v7
	v_pk_mul_f32 v[4:5], v[20:21], s[22:23] op_sel_hi:[1,0]
	v_pk_mul_f32 v[6:7], v[18:19], s[22:23] op_sel_hi:[1,0]
	s_nop 0
	v_cvt_pk_bf16_f32 v6, v6, v7
	v_cvt_pk_bf16_f32 v7, v4, v5
	v_mov_b32_e32 v190, v6
	v_mov_b32_e32 v191, v7
	v_lshl_add_u64 v[162:163], v[2:3], 0, v[160:161]
	s_nop 0
	v_permlane16_swap_b32 v188, v190
	v_permlane16_swap_b32 v189, v191
	global_store_dwordx4 v[162:163], v[188:191], off offset:256
	s_cbranch_vccz .LBB0_3417
	s_waitcnt vmcnt(0)
	s_cmpk_gt_u32 s3, 0xff
	v_readlane_b32 s4, v252, 8
	s_cbranch_scc1 .LBB0_3424
	s_barrier

.LBB0_4318:
	ds_read_b128 v[2:5], v167
	ds_read_b128 v[6:9], v171
	ds_read_b128 v[10:13], v172
	ds_read_b128 v[14:17], v173
	s_add_u32 s0, s30, 0xfffe0080
	s_addc_u32 s1, s31, -1
	s_cmp_eq_u32 s73, 4
	s_cselect_b32 s37, s23, s1
	s_cselect_b32 s36, s69, s0
	s_cselect_b32 s35, s21, s72
	s_cselect_b32 s34, s70, s71
	v_lshl_add_u64 v[158:159], s[30:31], 0, v[152:153]
	s_add_i32 m0, s29, 0xc000
	ds_read_b128 v[186:189], v184
	ds_read_b128 v[190:193], v184 offset:1024
	ds_read_b128 v[194:197], v184 offset:2048
	ds_read_b128 v[198:201], v184 offset:3072
	ds_read_b128 v[202:205], v184 offset:4096
	ds_read_b128 v[206:209], v184 offset:5120
	ds_read_b128 v[210:213], v184 offset:6144
	ds_read_b128 v[214:217], v184 offset:7168
	global_load_lds_dwordx4 v[158:159], off
	v_lshl_add_u64 v[158:159], s[30:31], 0, v[150:151]
	s_add_i32 m0, s29, 0xe000
	s_nop 0
	global_load_lds_dwordx4 v[158:159], off
	s_waitcnt lgkmcnt(8)
	s_barrier
	s_waitcnt lgkmcnt(0)
	s_setprio 1
	s_waitcnt lgkmcnt(0)
	v_mfma_f32_16x16x128_f8f6f4 v[142:145], v[2:9], v[186:193], v[142:145]
	v_mfma_f32_16x16x128_f8f6f4 v[138:141], v[10:17], v[186:193], v[138:141]
	v_mfma_f32_16x16x128_f8f6f4 v[126:129], v[2:9], v[194:201], v[126:129]
	v_mfma_f32_16x16x128_f8f6f4 v[122:125], v[10:17], v[194:201], v[122:125]
	v_mfma_f32_16x16x128_f8f6f4 v[110:113], v[2:9], v[202:209], v[110:113]
	v_mfma_f32_16x16x128_f8f6f4 v[106:109], v[10:17], v[202:209], v[106:109]
	v_mfma_f32_16x16x128_f8f6f4 v[94:97], v[2:9], v[210:217], v[94:97]
	v_mfma_f32_16x16x128_f8f6f4 v[90:93], v[10:17], v[210:217], v[90:93]
	s_setprio 0
	s_barrier
	s_mov_b32 m0, s43
	v_lshl_add_u64 v[158:159], s[34:35], 0, v[148:149]
	ds_read_b128 v[220:223], v168
	ds_read_b128 v[224:227], v174
	ds_read_b128 v[228:231], v175
	ds_read_b128 v[232:235], v176
	global_load_lds_dwordx4 v[158:159], off
	v_lshl_add_u64 v[160:161], s[34:35], 0, v[146:147]
	s_mov_b32 m0, s44
	s_nop 0
	global_load_lds_dwordx4 v[160:161], off
	s_barrier
	s_waitcnt lgkmcnt(0)
	s_setprio 1
	s_waitcnt lgkmcnt(0)
	v_mfma_f32_16x16x128_f8f6f4 v[134:137], v[220:227], v[186:193], v[134:137]
	v_mfma_f32_16x16x128_f8f6f4 v[130:133], v[228:235], v[186:193], v[130:133]
	v_mfma_f32_16x16x128_f8f6f4 v[118:121], v[220:227], v[194:201], v[118:121]
	v_mfma_f32_16x16x128_f8f6f4 v[114:117], v[228:235], v[194:201], v[114:117]
	v_mfma_f32_16x16x128_f8f6f4 v[102:105], v[220:227], v[202:209], v[102:105]
	v_mfma_f32_16x16x128_f8f6f4 v[98:101], v[228:235], v[202:209], v[98:101]
	v_mfma_f32_16x16x128_f8f6f4 v[86:89], v[220:227], v[210:217], v[86:89]
	v_mfma_f32_16x16x128_f8f6f4 v[82:85], v[228:235], v[210:217], v[82:85]
	s_setprio 0
	s_mov_b32 m0, s29
	v_lshl_add_u64 v[162:163], s[36:37], 0, v[148:149]
	s_barrier
	ds_read_b128 v[186:189], v184 offset:16384
	ds_read_b128 v[190:193], v184 offset:17408
	ds_read_b128 v[194:197], v184 offset:18432
	ds_read_b128 v[198:201], v184 offset:19456
	ds_read_b128 v[202:205], v184 offset:20480
	ds_read_b128 v[206:209], v184 offset:21504
	ds_read_b128 v[210:213], v184 offset:22528
	ds_read_b128 v[214:217], v184 offset:23552
	global_load_lds_dwordx4 v[162:163], off
	v_lshl_add_u64 v[164:165], s[36:37], 0, v[146:147]
	s_mov_b32 m0, s45
	s_nop 0
	global_load_lds_dwordx4 v[164:165], off
	s_barrier
	s_waitcnt lgkmcnt(0)
	s_setprio 1
	s_waitcnt lgkmcnt(0)
	v_mfma_f32_16x16x128_f8f6f4 v[78:81], v[2:9], v[186:193], v[78:81]
	v_mfma_f32_16x16x128_f8f6f4 v[74:77], v[10:17], v[186:193], v[74:77]
	v_mfma_f32_16x16x128_f8f6f4 v[62:65], v[2:9], v[194:201], v[62:65]
	v_mfma_f32_16x16x128_f8f6f4 v[58:61], v[10:17], v[194:201], v[58:61]
	v_mfma_f32_16x16x128_f8f6f4 v[46:49], v[2:9], v[202:209], v[46:49]
	v_mfma_f32_16x16x128_f8f6f4 v[42:45], v[10:17], v[202:209], v[42:45]
	v_mfma_f32_16x16x128_f8f6f4 v[30:33], v[2:9], v[210:217], v[30:33]
	v_mfma_f32_16x16x128_f8f6f4 v[26:29], v[10:17], v[210:217], v[26:29]
	s_setprio 0
	s_barrier
	s_add_u32 s74, s34, 0x20000
	s_addc_u32 s75, s35, 0
	s_mov_b32 m0, s46
	v_lshl_add_u64 v[2:3], s[74:75], 0, v[148:149]
	global_load_lds_dwordx4 v[2:3], off
	v_lshl_add_u64 v[2:3], s[74:75], 0, v[146:147]
	s_mov_b32 m0, s47
	s_nop 0
	global_load_lds_dwordx4 v[2:3], off
	s_waitcnt vmcnt(6)
	s_barrier
	s_setprio 1
	v_mfma_f32_16x16x128_f8f6f4 v[70:73], v[220:227], v[186:193], v[70:73]
	v_mfma_f32_16x16x128_f8f6f4 v[66:69], v[228:235], v[186:193], v[66:69]
	v_mfma_f32_16x16x128_f8f6f4 v[54:57], v[220:227], v[194:201], v[54:57]
	v_mfma_f32_16x16x128_f8f6f4 v[50:53], v[228:235], v[194:201], v[50:53]
	v_mfma_f32_16x16x128_f8f6f4 v[38:41], v[220:227], v[202:209], v[38:41]
	v_mfma_f32_16x16x128_f8f6f4 v[34:37], v[228:235], v[202:209], v[34:37]
	v_mfma_f32_16x16x128_f8f6f4 v[22:25], v[220:227], v[210:217], v[22:25]
	v_mfma_f32_16x16x128_f8f6f4 v[18:21], v[228:235], v[210:217], v[18:21]
	s_setprio 0
	s_barrier
	ds_read_b128 v[2:5], v169
	ds_read_b128 v[6:9], v177
	ds_read_b128 v[10:13], v178
	ds_read_b128 v[14:17], v179
	s_add_u32 s36, s36, 0x20000
	s_addc_u32 s37, s37, 0
	s_mov_b32 m0, s48
	v_lshl_add_u64 v[220:221], s[36:37], 0, v[148:149]
	ds_read_b128 v[186:189], v184 offset:32768
	ds_read_b128 v[190:193], v184 offset:33792
	ds_read_b128 v[194:197], v184 offset:34816
	ds_read_b128 v[198:201], v184 offset:35840
	ds_read_b128 v[202:205], v184 offset:36864
	ds_read_b128 v[206:209], v184 offset:37888
	ds_read_b128 v[210:213], v184 offset:38912
	ds_read_b128 v[214:217], v184 offset:39936
	global_load_lds_dwordx4 v[220:221], off
	v_lshl_add_u64 v[220:221], s[36:37], 0, v[146:147]
	s_mov_b32 m0, s49
	s_nop 0
	global_load_lds_dwordx4 v[220:221], off
	s_waitcnt lgkmcnt(8)
	s_barrier
	s_waitcnt lgkmcnt(0)
	s_setprio 1
	s_waitcnt lgkmcnt(0)
	v_mfma_f32_16x16x128_f8f6f4 v[142:145], v[2:9], v[186:193], v[142:145]
	v_mfma_f32_16x16x128_f8f6f4 v[138:141], v[10:17], v[186:193], v[138:141]
	v_mfma_f32_16x16x128_f8f6f4 v[126:129], v[2:9], v[194:201], v[126:129]
	v_mfma_f32_16x16x128_f8f6f4 v[122:125], v[10:17], v[194:201], v[122:125]
	v_mfma_f32_16x16x128_f8f6f4 v[110:113], v[2:9], v[202:209], v[110:113]
	v_mfma_f32_16x16x128_f8f6f4 v[106:109], v[10:17], v[202:209], v[106:109]
	v_mfma_f32_16x16x128_f8f6f4 v[94:97], v[2:9], v[210:217], v[94:97]
	v_mfma_f32_16x16x128_f8f6f4 v[90:93], v[10:17], v[210:217], v[90:93]
	s_setprio 0
	s_barrier
	s_mov_b32 m0, s53
	v_lshl_add_u64 v[158:159], v[158:159], 0, s[16:17]
	ds_read_b128 v[220:223], v170
	ds_read_b128 v[224:227], v180
	ds_read_b128 v[228:231], v181
	ds_read_b128 v[232:235], v182
	global_load_lds_dwordx4 v[158:159], off
	v_lshl_add_u64 v[158:159], v[160:161], 0, s[16:17]
	s_mov_b32 m0, s55
	s_nop 0
	global_load_lds_dwordx4 v[158:159], off
	s_barrier
	s_waitcnt lgkmcnt(0)
	s_setprio 1
	s_waitcnt lgkmcnt(0)
	v_mfma_f32_16x16x128_f8f6f4 v[134:137], v[220:227], v[186:193], v[134:137]
	v_mfma_f32_16x16x128_f8f6f4 v[130:133], v[228:235], v[186:193], v[130:133]
	v_mfma_f32_16x16x128_f8f6f4 v[118:121], v[220:227], v[194:201], v[118:121]
	v_mfma_f32_16x16x128_f8f6f4 v[114:117], v[228:235], v[194:201], v[114:117]
	v_mfma_f32_16x16x128_f8f6f4 v[102:105], v[220:227], v[202:209], v[102:105]
	v_mfma_f32_16x16x128_f8f6f4 v[98:101], v[228:235], v[202:209], v[98:101]
	v_mfma_f32_16x16x128_f8f6f4 v[86:89], v[220:227], v[210:217], v[86:89]
	v_mfma_f32_16x16x128_f8f6f4 v[82:85], v[228:235], v[210:217], v[82:85]
	s_setprio 0
	s_mov_b32 m0, s62
	v_lshl_add_u64 v[158:159], v[162:163], 0, s[16:17]
	s_barrier
	ds_read_b128 v[186:189], v184 offset:49152
	ds_read_b128 v[190:193], v184 offset:50176
	ds_read_b128 v[194:197], v184 offset:51200
	ds_read_b128 v[198:201], v184 offset:52224
	ds_read_b128 v[202:205], v184 offset:53248
	ds_read_b128 v[206:209], v184 offset:54272
	ds_read_b128 v[210:213], v184 offset:55296
	ds_read_b128 v[214:217], v184 offset:56320
	global_load_lds_dwordx4 v[158:159], off
	v_lshl_add_u64 v[158:159], v[164:165], 0, s[16:17]
	s_mov_b32 m0, s63
	s_nop 0
	global_load_lds_dwordx4 v[158:159], off
	s_barrier
	s_waitcnt lgkmcnt(0)
	s_setprio 1
	s_waitcnt lgkmcnt(0)
	v_mfma_f32_16x16x128_f8f6f4 v[78:81], v[2:9], v[186:193], v[78:81]
	v_mfma_f32_16x16x128_f8f6f4 v[74:77], v[10:17], v[186:193], v[74:77]
	v_mfma_f32_16x16x128_f8f6f4 v[62:65], v[2:9], v[194:201], v[62:65]
	v_mfma_f32_16x16x128_f8f6f4 v[58:61], v[10:17], v[194:201], v[58:61]
	v_mfma_f32_16x16x128_f8f6f4 v[46:49], v[2:9], v[202:209], v[46:49]
	v_mfma_f32_16x16x128_f8f6f4 v[42:45], v[10:17], v[202:209], v[42:45]
	v_mfma_f32_16x16x128_f8f6f4 v[30:33], v[2:9], v[210:217], v[30:33]
	v_mfma_f32_16x16x128_f8f6f4 v[26:29], v[10:17], v[210:217], v[26:29]
	s_setprio 0
	s_barrier
	s_add_u32 s34, s34, 0x20080
	s_addc_u32 s35, s35, 0
	s_mov_b32 m0, s64
	v_lshl_add_u64 v[2:3], s[34:35], 0, v[148:149]
	global_load_lds_dwordx4 v[2:3], off
	v_lshl_add_u64 v[2:3], s[34:35], 0, v[146:147]
	s_mov_b32 m0, s65
	s_nop 0
	global_load_lds_dwordx4 v[2:3], off
	s_waitcnt vmcnt(6)
	s_barrier
	s_setprio 1
	v_mfma_f32_16x16x128_f8f6f4 v[70:73], v[220:227], v[186:193], v[70:73]
	v_mfma_f32_16x16x128_f8f6f4 v[66:69], v[228:235], v[186:193], v[66:69]
	v_mfma_f32_16x16x128_f8f6f4 v[54:57], v[220:227], v[194:201], v[54:57]
	v_mfma_f32_16x16x128_f8f6f4 v[50:53], v[228:235], v[194:201], v[50:53]
	v_mfma_f32_16x16x128_f8f6f4 v[38:41], v[220:227], v[202:209], v[38:41]
	v_mfma_f32_16x16x128_f8f6f4 v[34:37], v[228:235], v[202:209], v[34:37]
	v_mfma_f32_16x16x128_f8f6f4 v[22:25], v[220:227], v[210:217], v[22:25]
	v_mfma_f32_16x16x128_f8f6f4 v[18:21], v[228:235], v[210:217], v[18:21]
	s_setprio 0
	s_add_i32 s73, s73, 2
	s_add_u32 s71, s71, 0x100
	s_addc_u32 s72, s72, 0
	s_add_u32 s30, s30, 0x100
	s_addc_u32 s31, s31, 0
	s_cmp_gt_u32 s73, 5
	s_barrier
	s_cbranch_scc0 .LBB0_4318
	v_bfe_u32 v196, v0, 4, 1
	v_mul_u32_u24_e32 v196, 24, v196
	v_mov_b32_e32 v197, 0
	v_lshl_or_b32 v10, s68, 8, v183
	v_or_b32_e32 v2, 0x80, v10
	v_ashrrev_i32_e32 v3, 31, v2
	v_lshl_add_u64 v[14:15], v[2:3], 2, s[14:15]
	v_or_b32_e32 v2, 16, v10
	v_ashrrev_i32_e32 v11, 31, v10
	v_ashrrev_i32_e32 v3, 31, v2
	s_nop 15
	s_nop 15
	v_lshl_add_u64 v[16:17], v[10:11], 2, s[14:15]
	v_lshl_add_u64 v[158:159], v[2:3], 2, s[14:15]
	global_load_dwordx4 v[186:189], v[16:17], off
	global_load_dwordx4 v[190:193], v[158:159], off
	global_load_dwordx4 v[6:9], v[14:15], off
	v_or_b32_e32 v2, 0x90, v10
	v_ashrrev_i32_e32 v3, 31, v2
	v_lshl_add_u64 v[160:161], v[2:3], 2, s[14:15]
	global_load_dwordx4 v[2:5], v[160:161], off
	v_lshl_add_u32 v162, s28, 8, v166
	v_mov_b64_e32 v[12:13], s[12:13]
	v_mad_i64_i32 v[164:165], s[30:31], v162, s67, v[12:13]
	v_lshlrev_b64 v[10:11], 1, v[10:11]
	v_lshl_add_u64 v[164:165], v[164:165], 0, v[10:11]
	s_and_b64 vcc, exec, s[8:9]
	s_mov_b32 s68, s20
	s_mov_b32 s28, s22
	s_mov_b64 s[34:35], s[24:25]
	s_waitcnt vmcnt(0)
	v_pk_fma_f32 v[142:143], v[142:143], s[18:19], v[186:187] op_sel_hi:[1,0,1]
	v_pk_fma_f32 v[136:137], v[136:137], s[18:19], v[8:9] op_sel_hi:[1,0,1]
	v_pk_fma_f32 v[134:135], v[134:135], s[18:19], v[6:7] op_sel_hi:[1,0,1]
	v_mul_f32_e32 v142, 0xbfb8aa3b, v142
	v_mul_f32_e32 v143, 0xbfb8aa3b, v143
	v_mul_f32_e32 v134, 0xbfb8aa3b, v134
	v_mul_f32_e32 v135, 0xbfb8aa3b, v135
	v_mul_f32_e32 v136, 0xbfb8aa3b, v136
	v_mul_f32_e32 v137, 0xbfb8aa3b, v137
	v_pk_fma_f32 v[144:145], v[144:145], s[18:19], v[188:189] op_sel_hi:[1,0,1]
	v_exp_f32_e32 v142, v142
	v_exp_f32_e32 v143, v143
	v_exp_f32_e32 v134, v134
	v_exp_f32_e32 v135, v135
	v_exp_f32_e32 v136, v136
	v_exp_f32_e32 v137, v137
	v_mul_f32_e32 v144, 0xbfb8aa3b, v144
	v_mul_f32_e32 v145, 0xbfb8aa3b, v145
	v_pk_fma_f32 v[140:141], v[140:141], s[18:19], v[192:193] op_sel_hi:[1,0,1]
	v_pk_fma_f32 v[138:139], v[138:139], s[18:19], v[190:191] op_sel_hi:[1,0,1]
	v_pk_fma_f32 v[132:133], v[132:133], s[18:19], v[4:5] op_sel_hi:[1,0,1]
	v_pk_fma_f32 v[130:131], v[130:131], s[18:19], v[2:3] op_sel_hi:[1,0,1]
	v_exp_f32_e32 v144, v144
	v_exp_f32_e32 v145, v145
	v_mul_f32_e32 v138, 0xbfb8aa3b, v138
	v_mul_f32_e32 v139, 0xbfb8aa3b, v139
	v_mul_f32_e32 v140, 0xbfb8aa3b, v140
	v_mul_f32_e32 v141, 0xbfb8aa3b, v141
	v_mul_f32_e32 v130, 0xbfb8aa3b, v130
	v_mul_f32_e32 v132, 0xbfb8aa3b, v132
	v_mul_f32_e32 v133, 0xbfb8aa3b, v133
	v_exp_f32_e32 v138, v138
	v_exp_f32_e32 v139, v139
	v_exp_f32_e32 v140, v140
	v_exp_f32_e32 v141, v141
	v_exp_f32_e32 v130, v130
	v_exp_f32_e32 v163, v132
	v_exp_f32_e32 v133, v133
	v_add_f32_e32 v132, 1.0, v142
	v_add_f32_e32 v142, 1.0, v143
	v_add_f32_e32 v134, 1.0, v134
	v_add_f32_e32 v135, 1.0, v135
	v_add_f32_e32 v136, 1.0, v136
	v_add_f32_e32 v137, 1.0, v137
	v_rcp_f32_e32 v132, v132
	v_rcp_f32_e32 v142, v142
	v_rcp_f32_e32 v134, v134
	v_rcp_f32_e32 v135, v135
	v_rcp_f32_e32 v136, v136
	v_rcp_f32_e32 v137, v137
	v_mul_f32_e32 v131, 0xbfb8aa3b, v131
	v_add_f32_e32 v143, 1.0, v144
	v_add_f32_e32 v144, 1.0, v145
	v_exp_f32_e32 v131, v131
	v_rcp_f32_e32 v143, v143
	v_rcp_f32_e32 v144, v144
	v_add_f32_e32 v138, 1.0, v138
	v_add_f32_e32 v139, 1.0, v139
	v_add_f32_e32 v140, 1.0, v140
	v_add_f32_e32 v141, 1.0, v141
	v_add_f32_e32 v130, 1.0, v130
	v_rcp_f32_e32 v138, v138
	v_rcp_f32_e32 v139, v139
	v_rcp_f32_e32 v140, v140
	v_rcp_f32_e32 v141, v141
	v_add_f32_e32 v133, 1.0, v133
	v_pk_fma_f32 v[126:127], v[126:127], s[18:19], v[186:187] op_sel_hi:[1,0,1]
	v_pk_fma_f32 v[6:7], v[118:119], s[18:19], v[6:7] op_sel_hi:[1,0,1]
	v_rcp_f32_e32 v185, v130
	v_cvt_pk_bf16_f32 v130, v132, v142
	v_cvt_pk_bf16_f32 v132, v134, v135
	v_rcp_f32_e32 v134, v133
	v_cvt_pk_bf16_f32 v133, v136, v137
	v_mul_f32_e32 v126, 0xbfb8aa3b, v126
	v_mul_f32_e32 v6, 0xbfb8aa3b, v6
	global_store_dwordx2 v[164:165], v[132:133], off offset:256
	v_exp_f32_e32 v132, v126
	v_mul_f32_e32 v126, 0xbfb8aa3b, v127
	v_exp_f32_e32 v118, v6
	v_mul_f32_e32 v6, 0xbfb8aa3b, v7
	v_add_f32_e32 v145, 1.0, v131
	v_cvt_pk_bf16_f32 v131, v143, v144
	v_exp_f32_e32 v133, v126
	v_exp_f32_e32 v119, v6
	v_mov_b32_e32 v200, v130
	v_mov_b32_e32 v201, v131
	v_cvt_pk_bf16_f32 v130, v138, v139
	v_cvt_pk_bf16_f32 v131, v140, v141
	v_pk_fma_f32 v[126:127], v[128:129], s[18:19], v[188:189] op_sel_hi:[1,0,1]
	v_mov_b32_e32 v202, v130
	v_mov_b32_e32 v203, v131
	v_lshl_add_u64 v[198:199], v[164:165], 0, v[196:197]
	s_nop 0
	v_permlane16_swap_b32 v200, v202
	v_permlane16_swap_b32 v201, v203
	global_store_dwordx4 v[198:199], v[200:203], off
	v_add_f32_e32 v131, 1.0, v163
	v_mul_f32_e32 v126, 0xbfb8aa3b, v126
	v_rcp_f32_e32 v130, v145
	v_rcp_f32_e32 v131, v131
	v_exp_f32_e32 v126, v126
	v_mul_f32_e32 v127, 0xbfb8aa3b, v127
	v_add_f32_e32 v128, 1.0, v132
	v_add_f32_e32 v129, 1.0, v133
	v_exp_f32_e32 v127, v127
	v_pk_fma_f32 v[6:7], v[120:121], s[18:19], v[8:9] op_sel_hi:[1,0,1]
	v_add_f32_e32 v8, 1.0, v118
	v_add_f32_e32 v9, 1.0, v119
	v_rcp_f32_e32 v128, v128
	v_rcp_f32_e32 v129, v129
	v_rcp_f32_e32 v8, v8
	v_rcp_f32_e32 v9, v9
	v_cvt_pk_bf16_f32 v130, v185, v130
	v_cvt_pk_bf16_f32 v131, v131, v134
	v_add_f32_e32 v126, 1.0, v126
	v_pk_fma_f32 v[122:123], v[122:123], s[18:19], v[190:191] op_sel_hi:[1,0,1]
	v_mul_f32_e32 v6, 0xbfb8aa3b, v6
	v_pk_fma_f32 v[2:3], v[114:115], s[18:19], v[2:3] op_sel_hi:[1,0,1]
	v_rcp_f32_e32 v132, v126
	v_add_f32_e32 v126, 1.0, v127
	global_store_dwordx2 v[164:165], v[130:131], off offset:288
	v_or_b32_e32 v130, 16, v162
	v_mul_f32_e32 v122, 0xbfb8aa3b, v122
	v_exp_f32_e32 v118, v6
	v_mul_f32_e32 v6, 0xbfb8aa3b, v7
	v_mul_f32_e32 v2, 0xbfb8aa3b, v2
	v_rcp_f32_e32 v127, v126
	v_cvt_pk_bf16_f32 v126, v128, v129
	v_mad_i64_i32 v[128:129], s[30:31], v130, s67, v[12:13]
	v_exp_f32_e32 v130, v122
	v_mul_f32_e32 v122, 0xbfb8aa3b, v123
	v_exp_f32_e32 v7, v6
	v_cvt_pk_bf16_f32 v6, v8, v9
	v_exp_f32_e32 v9, v2
	v_mul_f32_e32 v2, 0xbfb8aa3b, v3
	v_exp_f32_e32 v131, v122
	v_pk_fma_f32 v[122:123], v[124:125], s[18:19], v[192:193] op_sel_hi:[1,0,1]
	v_exp_f32_e32 v114, v2
	v_pk_fma_f32 v[2:3], v[116:117], s[18:19], v[4:5] op_sel_hi:[1,0,1]
	v_mul_f32_e32 v122, 0xbfb8aa3b, v122
	v_mul_f32_e32 v2, 0xbfb8aa3b, v2
	v_exp_f32_e32 v122, v122
	v_mul_f32_e32 v123, 0xbfb8aa3b, v123
	v_exp_f32_e32 v2, v2
	v_mul_f32_e32 v3, 0xbfb8aa3b, v3
	v_exp_f32_e32 v123, v123
	v_exp_f32_e32 v3, v3
	v_add_f32_e32 v122, 1.0, v122
	v_add_f32_e32 v2, 1.0, v2
	v_add_f32_e32 v124, 1.0, v130
	v_add_f32_e32 v125, 1.0, v131
	v_rcp_f32_e32 v130, v122
	v_add_f32_e32 v122, 1.0, v123
	v_add_f32_e32 v8, 1.0, v118
	v_add_f32_e32 v7, 1.0, v7
	v_add_f32_e32 v4, 1.0, v9
	v_add_f32_e32 v5, 1.0, v114
	v_rcp_f32_e32 v9, v2
	v_add_f32_e32 v2, 1.0, v3
	v_rcp_f32_e32 v124, v124
	v_rcp_f32_e32 v125, v125
	v_rcp_f32_e32 v131, v122
	v_rcp_f32_e32 v8, v8
	v_rcp_f32_e32 v7, v7
	v_rcp_f32_e32 v4, v4
	v_rcp_f32_e32 v5, v5
	v_rcp_f32_e32 v3, v2
	v_cvt_pk_bf16_f32 v127, v132, v127
	v_lshl_add_u64 v[122:123], v[128:129], 0, v[10:11]
	v_cvt_pk_bf16_f32 v124, v124, v125
	v_cvt_pk_bf16_f32 v125, v130, v131
	v_cvt_pk_bf16_f32 v7, v8, v7
	v_cvt_pk_bf16_f32 v2, v4, v5
	v_cvt_pk_bf16_f32 v3, v9, v3
	v_mov_b32_e32 v204, v126
	v_mov_b32_e32 v205, v127
	v_mov_b32_e32 v206, v124
	v_mov_b32_e32 v207, v125
	v_lshl_add_u64 v[198:199], v[122:123], 0, v[196:197]
	s_nop 0
	v_permlane16_swap_b32 v204, v206
	v_permlane16_swap_b32 v205, v207
	global_store_dwordx4 v[198:199], v[204:207], off
	v_mov_b32_e32 v208, v6
	v_mov_b32_e32 v209, v7
	v_mov_b32_e32 v210, v2
	v_mov_b32_e32 v211, v3
	v_lshl_add_u64 v[198:199], v[122:123], 0, v[196:197]
	s_nop 0
	v_permlane16_swap_b32 v208, v210
	v_permlane16_swap_b32 v209, v211
	global_store_dwordx4 v[198:199], v[208:211], off offset:256
	global_load_dwordx4 v[6:9], v[16:17], off
	s_nop 0
	global_load_dwordx4 v[114:117], v[158:159], off
	global_load_dwordx4 v[118:121], v[14:15], off
	global_load_dwordx4 v[2:5], v[160:161], off
	s_waitcnt vmcnt(0)
	v_pk_fma_f32 v[110:111], v[110:111], s[18:19], v[6:7] op_sel_hi:[1,0,1]
	s_nop 0
	v_mul_f32_e32 v110, 0xbfb8aa3b, v110
	v_exp_f32_e32 v122, v110
	v_mul_f32_e32 v110, 0xbfb8aa3b, v111
	v_exp_f32_e32 v123, v110
	v_pk_fma_f32 v[110:111], v[112:113], s[18:19], v[8:9] op_sel_hi:[1,0,1]
	v_pk_fma_f32 v[6:7], v[94:95], s[18:19], v[6:7] op_sel_hi:[1,0,1]
	v_mul_f32_e32 v110, 0xbfb8aa3b, v110
	v_exp_f32_e32 v110, v110
	v_mul_f32_e32 v111, 0xbfb8aa3b, v111
	v_exp_f32_e32 v111, v111
	v_mul_f32_e32 v6, 0xbfb8aa3b, v6
	v_add_f32_e32 v110, 1.0, v110
	v_exp_f32_e32 v94, v6
	v_mul_f32_e32 v6, 0xbfb8aa3b, v7
	v_add_f32_e32 v112, 1.0, v122
	v_rcp_f32_e32 v122, v110
	v_add_f32_e32 v110, 1.0, v111
	v_exp_f32_e32 v95, v6
	v_pk_fma_f32 v[6:7], v[96:97], s[18:19], v[8:9] op_sel_hi:[1,0,1]
	v_add_f32_e32 v113, 1.0, v123
	v_rcp_f32_e32 v111, v110
	v_mul_f32_e32 v6, 0xbfb8aa3b, v6
	v_rcp_f32_e32 v112, v112
	v_rcp_f32_e32 v113, v113
	v_exp_f32_e32 v6, v6
	v_mul_f32_e32 v7, 0xbfb8aa3b, v7
	v_pk_fma_f32 v[106:107], v[106:107], s[18:19], v[114:115] op_sel_hi:[1,0,1]
	v_exp_f32_e32 v7, v7
	v_mul_f32_e32 v106, 0xbfb8aa3b, v106
	v_or_b32_e32 v123, 32, v162
	v_cvt_pk_bf16_f32 v111, v122, v111
	v_exp_f32_e32 v122, v106
	v_mul_f32_e32 v106, 0xbfb8aa3b, v107
	v_cvt_pk_bf16_f32 v110, v112, v113
	v_mad_i64_i32 v[112:113], s[30:31], v123, s67, v[12:13]
	v_exp_f32_e32 v123, v106
	v_pk_fma_f32 v[106:107], v[108:109], s[18:19], v[116:117] op_sel_hi:[1,0,1]
	v_add_f32_e32 v6, 1.0, v6
	v_mul_f32_e32 v106, 0xbfb8aa3b, v106
	v_add_f32_e32 v8, 1.0, v94
	v_rcp_f32_e32 v94, v6
	v_add_f32_e32 v6, 1.0, v7
	v_exp_f32_e32 v106, v106
	v_mul_f32_e32 v107, 0xbfb8aa3b, v107
	v_add_f32_e32 v9, 1.0, v95
	v_rcp_f32_e32 v7, v6
	v_exp_f32_e32 v107, v107
	v_rcp_f32_e32 v8, v8
	v_rcp_f32_e32 v9, v9
	v_pk_fma_f32 v[90:91], v[90:91], s[18:19], v[114:115] op_sel_hi:[1,0,1]
	v_add_f32_e32 v106, 1.0, v106
	v_mul_f32_e32 v90, 0xbfb8aa3b, v90
	v_or_b32_e32 v95, 48, v162
	v_cvt_pk_bf16_f32 v7, v94, v7
	v_exp_f32_e32 v94, v90
	v_mul_f32_e32 v90, 0xbfb8aa3b, v91
	v_add_f32_e32 v108, 1.0, v122
	v_add_f32_e32 v109, 1.0, v123
	v_rcp_f32_e32 v122, v106
	v_add_f32_e32 v106, 1.0, v107
	v_cvt_pk_bf16_f32 v6, v8, v9
	v_mad_i64_i32 v[8:9], s[30:31], v95, s67, v[12:13]
	v_exp_f32_e32 v95, v90
	v_pk_fma_f32 v[90:91], v[92:93], s[18:19], v[116:117] op_sel_hi:[1,0,1]
	v_rcp_f32_e32 v108, v108
	v_rcp_f32_e32 v109, v109
	v_rcp_f32_e32 v123, v106
	v_mul_f32_e32 v90, 0xbfb8aa3b, v90
	v_mul_f32_e32 v91, 0xbfb8aa3b, v91
	v_exp_f32_e32 v90, v90
	v_exp_f32_e32 v91, v91
	v_pk_fma_f32 v[102:103], v[102:103], s[18:19], v[118:119] op_sel_hi:[1,0,1]
	v_lshl_add_u64 v[106:107], v[112:113], 0, v[10:11]
	v_cvt_pk_bf16_f32 v108, v108, v109
	v_cvt_pk_bf16_f32 v109, v122, v123
	v_mul_f32_e32 v102, 0xbfb8aa3b, v102
	global_store_dwordx2 v[106:107], v[108:109], off offset:32
	v_exp_f32_e32 v108, v102
	v_mul_f32_e32 v102, 0xbfb8aa3b, v103
	v_add_f32_e32 v92, 1.0, v94
	v_add_f32_e32 v93, 1.0, v95
	v_add_f32_e32 v90, 1.0, v90
	v_add_f32_e32 v91, 1.0, v91
	v_exp_f32_e32 v109, v102
	v_rcp_f32_e32 v92, v92
	v_rcp_f32_e32 v93, v93
	v_rcp_f32_e32 v90, v90
	v_rcp_f32_e32 v91, v91
	v_lshl_add_u64 v[8:9], v[8:9], 0, v[10:11]
	v_pk_fma_f32 v[102:103], v[104:105], s[18:19], v[120:121] op_sel_hi:[1,0,1]
	v_add_f32_e32 v104, 1.0, v108
	v_add_f32_e32 v105, 1.0, v109
	v_mov_b32_e32 v200, v6
	v_mov_b32_e32 v201, v7
	v_cvt_pk_bf16_f32 v6, v92, v93
	v_cvt_pk_bf16_f32 v7, v90, v91
	v_rcp_f32_e32 v104, v104
	v_rcp_f32_e32 v105, v105
	v_mul_f32_e32 v102, 0xbfb8aa3b, v102
	v_mov_b32_e32 v202, v6
	v_mov_b32_e32 v203, v7
	v_lshl_add_u64 v[198:199], v[8:9], 0, v[196:197]
	s_nop 0
	v_permlane16_swap_b32 v200, v202
	v_permlane16_swap_b32 v201, v203
	global_store_dwordx4 v[198:199], v[200:203], off
	v_pk_fma_f32 v[6:7], v[86:87], s[18:19], v[118:119] op_sel_hi:[1,0,1]
	v_exp_f32_e32 v108, v102
	v_mul_f32_e32 v6, 0xbfb8aa3b, v6
	v_pk_fma_f32 v[98:99], v[98:99], s[18:19], v[2:3] op_sel_hi:[1,0,1]
	v_exp_f32_e32 v86, v6
	v_mul_f32_e32 v6, 0xbfb8aa3b, v7
	v_pk_fma_f32 v[2:3], v[82:83], s[18:19], v[2:3] op_sel_hi:[1,0,1]
	v_mul_f32_e32 v102, 0xbfb8aa3b, v103
	v_mul_f32_e32 v98, 0xbfb8aa3b, v98
	v_exp_f32_e32 v87, v6
	v_mul_f32_e32 v2, 0xbfb8aa3b, v2
	v_exp_f32_e32 v103, v102
	v_cvt_pk_bf16_f32 v102, v104, v105
	v_exp_f32_e32 v105, v98
	v_mul_f32_e32 v98, 0xbfb8aa3b, v99
	v_exp_f32_e32 v82, v2
	v_mul_f32_e32 v2, 0xbfb8aa3b, v3
	v_add_f32_e32 v104, 1.0, v108
	v_exp_f32_e32 v108, v98
	v_pk_fma_f32 v[98:99], v[100:101], s[18:19], v[4:5] op_sel_hi:[1,0,1]
	v_pk_fma_f32 v[6:7], v[88:89], s[18:19], v[120:121] op_sel_hi:[1,0,1]
	v_exp_f32_e32 v83, v2
	v_pk_fma_f32 v[2:3], v[84:85], s[18:19], v[4:5] op_sel_hi:[1,0,1]
	v_mul_f32_e32 v98, 0xbfb8aa3b, v98
	v_mul_f32_e32 v6, 0xbfb8aa3b, v6
	v_mul_f32_e32 v2, 0xbfb8aa3b, v2
	v_exp_f32_e32 v98, v98
	v_mul_f32_e32 v99, 0xbfb8aa3b, v99
	v_add_f32_e32 v86, 1.0, v86
	v_add_f32_e32 v87, 1.0, v87
	v_exp_f32_e32 v88, v6
	v_mul_f32_e32 v6, 0xbfb8aa3b, v7
	v_exp_f32_e32 v2, v2
	v_mul_f32_e32 v3, 0xbfb8aa3b, v3
	v_exp_f32_e32 v99, v99
	v_rcp_f32_e32 v86, v86
	v_rcp_f32_e32 v87, v87
	v_exp_f32_e32 v7, v6
	v_exp_f32_e32 v3, v3
	v_add_f32_e32 v98, 1.0, v98
	v_add_f32_e32 v2, 1.0, v2
	v_add_f32_e32 v103, 1.0, v103
	v_add_f32_e32 v100, 1.0, v105
	v_add_f32_e32 v101, 1.0, v108
	v_rcp_f32_e32 v105, v98
	v_add_f32_e32 v98, 1.0, v99
	v_cvt_pk_bf16_f32 v6, v86, v87
	v_add_f32_e32 v86, 1.0, v88
	v_add_f32_e32 v7, 1.0, v7
	v_add_f32_e32 v4, 1.0, v82
	v_add_f32_e32 v5, 1.0, v83
	v_rcp_f32_e32 v82, v2
	v_add_f32_e32 v2, 1.0, v3
	v_rcp_f32_e32 v104, v104
	v_rcp_f32_e32 v103, v103
	v_rcp_f32_e32 v100, v100
	v_rcp_f32_e32 v101, v101
	v_rcp_f32_e32 v99, v98
	v_rcp_f32_e32 v86, v86
	v_rcp_f32_e32 v7, v7
	v_rcp_f32_e32 v4, v4
	v_rcp_f32_e32 v5, v5
	v_rcp_f32_e32 v3, v2
	v_cvt_pk_bf16_f32 v103, v104, v103
	v_cvt_pk_bf16_f32 v98, v100, v101
	v_cvt_pk_bf16_f32 v99, v105, v99
	v_cvt_pk_bf16_f32 v7, v86, v7
	v_cvt_pk_bf16_f32 v2, v4, v5
	v_cvt_pk_bf16_f32 v3, v82, v3
	global_store_dwordx2 v[106:107], v[110:111], off
	v_mov_b32_e32 v204, v102
	v_mov_b32_e32 v205, v103
	v_mov_b32_e32 v206, v98
	v_mov_b32_e32 v207, v99
	v_lshl_add_u64 v[198:199], v[106:107], 0, v[196:197]
	s_nop 0
	v_permlane16_swap_b32 v204, v206
	v_permlane16_swap_b32 v205, v207
	global_store_dwordx4 v[198:199], v[204:207], off offset:256
	v_mov_b32_e32 v208, v6
	v_mov_b32_e32 v209, v7
	v_mov_b32_e32 v210, v2
	v_mov_b32_e32 v211, v3
	v_lshl_add_u64 v[198:199], v[8:9], 0, v[196:197]
	s_nop 0
	v_permlane16_swap_b32 v208, v210
	v_permlane16_swap_b32 v209, v211
	global_store_dwordx4 v[198:199], v[208:211], off offset:256
	global_load_dwordx4 v[6:9], v[16:17], off
	s_nop 0
	global_load_dwordx4 v[82:85], v[158:159], off
	global_load_dwordx4 v[86:89], v[14:15], off
	global_load_dwordx4 v[2:5], v[160:161], off
	s_waitcnt vmcnt(0)
	v_pk_fma_f32 v[78:79], v[78:79], s[18:19], v[6:7] op_sel_hi:[1,0,1]
	s_nop 0
	v_mul_f32_e32 v78, 0xbfb8aa3b, v78
	v_exp_f32_e32 v90, v78
	v_mul_f32_e32 v78, 0xbfb8aa3b, v79
	v_exp_f32_e32 v91, v78
	v_pk_fma_f32 v[78:79], v[80:81], s[18:19], v[8:9] op_sel_hi:[1,0,1]
	v_pk_fma_f32 v[6:7], v[62:63], s[18:19], v[6:7] op_sel_hi:[1,0,1]
	v_mul_f32_e32 v78, 0xbfb8aa3b, v78
	v_exp_f32_e32 v78, v78
	v_mul_f32_e32 v79, 0xbfb8aa3b, v79
	v_exp_f32_e32 v79, v79
	v_mul_f32_e32 v6, 0xbfb8aa3b, v6
	v_add_f32_e32 v78, 1.0, v78
	v_exp_f32_e32 v62, v6
	v_mul_f32_e32 v6, 0xbfb8aa3b, v7
	v_add_f32_e32 v80, 1.0, v90
	v_rcp_f32_e32 v90, v78
	v_add_f32_e32 v78, 1.0, v79
	v_exp_f32_e32 v63, v6
	v_pk_fma_f32 v[6:7], v[64:65], s[18:19], v[8:9] op_sel_hi:[1,0,1]
	v_add_f32_e32 v81, 1.0, v91
	v_rcp_f32_e32 v79, v78
	v_mul_f32_e32 v6, 0xbfb8aa3b, v6
	v_rcp_f32_e32 v80, v80
	v_rcp_f32_e32 v81, v81
	v_exp_f32_e32 v6, v6
	v_mul_f32_e32 v7, 0xbfb8aa3b, v7
	v_pk_fma_f32 v[74:75], v[74:75], s[18:19], v[82:83] op_sel_hi:[1,0,1]
	v_exp_f32_e32 v7, v7
	v_mul_f32_e32 v74, 0xbfb8aa3b, v74
	v_add_u32_e32 v91, 0x80, v162
	v_cvt_pk_bf16_f32 v79, v90, v79
	v_exp_f32_e32 v90, v74
	v_mul_f32_e32 v74, 0xbfb8aa3b, v75
	v_cvt_pk_bf16_f32 v78, v80, v81
	v_mad_i64_i32 v[80:81], s[30:31], v91, s67, v[12:13]
	v_exp_f32_e32 v91, v74
	v_pk_fma_f32 v[74:75], v[76:77], s[18:19], v[84:85] op_sel_hi:[1,0,1]
	v_add_f32_e32 v6, 1.0, v6
	v_mul_f32_e32 v74, 0xbfb8aa3b, v74
	v_add_f32_e32 v8, 1.0, v62
	v_rcp_f32_e32 v62, v6
	v_add_f32_e32 v6, 1.0, v7
	v_exp_f32_e32 v74, v74
	v_mul_f32_e32 v75, 0xbfb8aa3b, v75
	v_add_f32_e32 v9, 1.0, v63
	v_rcp_f32_e32 v7, v6
	v_exp_f32_e32 v75, v75
	v_rcp_f32_e32 v8, v8
	v_rcp_f32_e32 v9, v9
	v_pk_fma_f32 v[58:59], v[58:59], s[18:19], v[82:83] op_sel_hi:[1,0,1]
	v_add_f32_e32 v74, 1.0, v74
	v_mul_f32_e32 v58, 0xbfb8aa3b, v58
	v_add_u32_e32 v63, 0x90, v162
	v_cvt_pk_bf16_f32 v7, v62, v7
	v_exp_f32_e32 v62, v58
	v_mul_f32_e32 v58, 0xbfb8aa3b, v59
	v_add_f32_e32 v76, 1.0, v90
	v_add_f32_e32 v77, 1.0, v91
	v_rcp_f32_e32 v90, v74
	v_add_f32_e32 v74, 1.0, v75
	v_cvt_pk_bf16_f32 v6, v8, v9
	v_mad_i64_i32 v[8:9], s[30:31], v63, s67, v[12:13]
	v_exp_f32_e32 v63, v58
	v_pk_fma_f32 v[58:59], v[60:61], s[18:19], v[84:85] op_sel_hi:[1,0,1]
	v_rcp_f32_e32 v76, v76
	v_rcp_f32_e32 v77, v77
	v_rcp_f32_e32 v91, v74
	v_mul_f32_e32 v58, 0xbfb8aa3b, v58
	v_mul_f32_e32 v59, 0xbfb8aa3b, v59
	v_exp_f32_e32 v58, v58
	v_exp_f32_e32 v59, v59
	v_pk_fma_f32 v[70:71], v[70:71], s[18:19], v[86:87] op_sel_hi:[1,0,1]
	v_lshl_add_u64 v[74:75], v[80:81], 0, v[10:11]
	v_cvt_pk_bf16_f32 v76, v76, v77
	v_cvt_pk_bf16_f32 v77, v90, v91
	v_mul_f32_e32 v70, 0xbfb8aa3b, v70
	global_store_dwordx2 v[74:75], v[76:77], off offset:32
	v_exp_f32_e32 v76, v70
	v_mul_f32_e32 v70, 0xbfb8aa3b, v71
	v_add_f32_e32 v60, 1.0, v62
	v_add_f32_e32 v61, 1.0, v63
	v_add_f32_e32 v58, 1.0, v58
	v_add_f32_e32 v59, 1.0, v59
	v_exp_f32_e32 v77, v70
	v_rcp_f32_e32 v60, v60
	v_rcp_f32_e32 v61, v61
	v_rcp_f32_e32 v58, v58
	v_rcp_f32_e32 v59, v59
	v_lshl_add_u64 v[8:9], v[8:9], 0, v[10:11]
	v_pk_fma_f32 v[70:71], v[72:73], s[18:19], v[88:89] op_sel_hi:[1,0,1]
	v_add_f32_e32 v72, 1.0, v76
	v_add_f32_e32 v73, 1.0, v77
	v_mov_b32_e32 v200, v6
	v_mov_b32_e32 v201, v7
	v_cvt_pk_bf16_f32 v6, v60, v61
	v_cvt_pk_bf16_f32 v7, v58, v59
	v_rcp_f32_e32 v72, v72
	v_rcp_f32_e32 v73, v73
	v_mul_f32_e32 v70, 0xbfb8aa3b, v70
	v_mov_b32_e32 v202, v6
	v_mov_b32_e32 v203, v7
	v_lshl_add_u64 v[198:199], v[8:9], 0, v[196:197]
	s_nop 0
	v_permlane16_swap_b32 v200, v202
	v_permlane16_swap_b32 v201, v203
	global_store_dwordx4 v[198:199], v[200:203], off
	v_pk_fma_f32 v[6:7], v[54:55], s[18:19], v[86:87] op_sel_hi:[1,0,1]
	v_exp_f32_e32 v76, v70
	v_mul_f32_e32 v6, 0xbfb8aa3b, v6
	v_pk_fma_f32 v[66:67], v[66:67], s[18:19], v[2:3] op_sel_hi:[1,0,1]
	v_exp_f32_e32 v54, v6
	v_mul_f32_e32 v6, 0xbfb8aa3b, v7
	v_pk_fma_f32 v[2:3], v[50:51], s[18:19], v[2:3] op_sel_hi:[1,0,1]
	v_mul_f32_e32 v70, 0xbfb8aa3b, v71
	v_mul_f32_e32 v66, 0xbfb8aa3b, v66
	v_exp_f32_e32 v55, v6
	v_mul_f32_e32 v2, 0xbfb8aa3b, v2
	v_exp_f32_e32 v71, v70
	v_cvt_pk_bf16_f32 v70, v72, v73
	v_exp_f32_e32 v73, v66
	v_mul_f32_e32 v66, 0xbfb8aa3b, v67
	v_exp_f32_e32 v50, v2
	v_mul_f32_e32 v2, 0xbfb8aa3b, v3
	v_add_f32_e32 v72, 1.0, v76
	v_exp_f32_e32 v76, v66
	v_pk_fma_f32 v[66:67], v[68:69], s[18:19], v[4:5] op_sel_hi:[1,0,1]
	v_pk_fma_f32 v[6:7], v[56:57], s[18:19], v[88:89] op_sel_hi:[1,0,1]
	v_exp_f32_e32 v51, v2
	v_pk_fma_f32 v[2:3], v[52:53], s[18:19], v[4:5] op_sel_hi:[1,0,1]
	v_mul_f32_e32 v66, 0xbfb8aa3b, v66
	v_mul_f32_e32 v6, 0xbfb8aa3b, v6
	v_mul_f32_e32 v2, 0xbfb8aa3b, v2
	v_exp_f32_e32 v66, v66
	v_mul_f32_e32 v67, 0xbfb8aa3b, v67
	v_add_f32_e32 v54, 1.0, v54
	v_add_f32_e32 v55, 1.0, v55
	v_exp_f32_e32 v56, v6
	v_mul_f32_e32 v6, 0xbfb8aa3b, v7
	v_exp_f32_e32 v2, v2
	v_mul_f32_e32 v3, 0xbfb8aa3b, v3
	v_exp_f32_e32 v67, v67
	v_rcp_f32_e32 v54, v54
	v_rcp_f32_e32 v55, v55
	v_exp_f32_e32 v7, v6
	v_exp_f32_e32 v3, v3
	v_add_f32_e32 v66, 1.0, v66
	v_add_f32_e32 v2, 1.0, v2
	v_add_f32_e32 v71, 1.0, v71
	v_add_f32_e32 v68, 1.0, v73
	v_add_f32_e32 v69, 1.0, v76
	v_rcp_f32_e32 v73, v66
	v_add_f32_e32 v66, 1.0, v67
	v_cvt_pk_bf16_f32 v6, v54, v55
	v_add_f32_e32 v54, 1.0, v56
	v_add_f32_e32 v7, 1.0, v7
	v_add_f32_e32 v4, 1.0, v50
	v_add_f32_e32 v5, 1.0, v51
	v_rcp_f32_e32 v50, v2
	v_add_f32_e32 v2, 1.0, v3
	v_rcp_f32_e32 v72, v72
	v_rcp_f32_e32 v71, v71
	v_rcp_f32_e32 v68, v68
	v_rcp_f32_e32 v69, v69
	v_rcp_f32_e32 v67, v66
	v_rcp_f32_e32 v54, v54
	v_rcp_f32_e32 v7, v7
	v_rcp_f32_e32 v4, v4
	v_rcp_f32_e32 v5, v5
	v_rcp_f32_e32 v3, v2
	v_cvt_pk_bf16_f32 v71, v72, v71
	v_cvt_pk_bf16_f32 v66, v68, v69
	v_cvt_pk_bf16_f32 v67, v73, v67
	v_cvt_pk_bf16_f32 v7, v54, v7
	v_cvt_pk_bf16_f32 v2, v4, v5
	v_cvt_pk_bf16_f32 v3, v50, v3
	global_store_dwordx2 v[74:75], v[78:79], off
	v_mov_b32_e32 v204, v70
	v_mov_b32_e32 v205, v71
	v_mov_b32_e32 v206, v66
	v_mov_b32_e32 v207, v67
	v_lshl_add_u64 v[198:199], v[74:75], 0, v[196:197]
	s_nop 0
	v_permlane16_swap_b32 v204, v206
	v_permlane16_swap_b32 v205, v207
	global_store_dwordx4 v[198:199], v[204:207], off offset:256
	v_mov_b32_e32 v208, v6
	v_mov_b32_e32 v209, v7
	v_mov_b32_e32 v210, v2
	v_mov_b32_e32 v211, v3
	v_lshl_add_u64 v[198:199], v[8:9], 0, v[196:197]
	s_nop 0
	v_permlane16_swap_b32 v208, v210
	v_permlane16_swap_b32 v209, v211
	global_store_dwordx4 v[198:199], v[208:211], off offset:256
	global_load_dwordx4 v[6:9], v[16:17], off
	s_nop 0
	global_load_dwordx4 v[50:53], v[158:159], off
	s_nop 0
	global_load_dwordx4 v[14:17], v[14:15], off
	s_nop 0
	global_load_dwordx4 v[2:5], v[160:161], off
	s_waitcnt vmcnt(0)
	v_pk_fma_f32 v[46:47], v[46:47], s[18:19], v[6:7] op_sel_hi:[1,0,1]
	v_pk_fma_f32 v[6:7], v[30:31], s[18:19], v[6:7] op_sel_hi:[1,0,1]
	v_mul_f32_e32 v46, 0xbfb8aa3b, v46
	v_mul_f32_e32 v6, 0xbfb8aa3b, v6
	v_exp_f32_e32 v54, v46
	v_mul_f32_e32 v46, 0xbfb8aa3b, v47
	v_exp_f32_e32 v30, v6
	v_mul_f32_e32 v6, 0xbfb8aa3b, v7
	v_exp_f32_e32 v55, v46
	v_pk_fma_f32 v[46:47], v[48:49], s[18:19], v[8:9] op_sel_hi:[1,0,1]
	v_exp_f32_e32 v31, v6
	v_mul_f32_e32 v46, 0xbfb8aa3b, v46
	v_pk_fma_f32 v[6:7], v[32:33], s[18:19], v[8:9] op_sel_hi:[1,0,1]
	v_exp_f32_e32 v46, v46
	v_mul_f32_e32 v47, 0xbfb8aa3b, v47
	v_mul_f32_e32 v6, 0xbfb8aa3b, v6
	v_exp_f32_e32 v47, v47
	v_exp_f32_e32 v6, v6
	v_mul_f32_e32 v7, 0xbfb8aa3b, v7
	v_add_f32_e32 v48, 1.0, v54
	v_add_f32_e32 v49, 1.0, v55
	v_add_f32_e32 v8, 1.0, v30
	v_add_f32_e32 v9, 1.0, v31
	v_exp_f32_e32 v7, v7
	v_rcp_f32_e32 v48, v48
	v_rcp_f32_e32 v49, v49
	v_rcp_f32_e32 v8, v8
	v_rcp_f32_e32 v9, v9
	v_add_f32_e32 v46, 1.0, v46
	v_rcp_f32_e32 v54, v46
	v_add_f32_e32 v46, 1.0, v47
	v_add_f32_e32 v6, 1.0, v6
	v_rcp_f32_e32 v47, v46
	v_add_u32_e32 v55, 0xa0, v162
	v_rcp_f32_e32 v30, v6
	v_add_f32_e32 v6, 1.0, v7
	v_add_u32_e32 v31, 0xb0, v162
	v_cvt_pk_bf16_f32 v46, v48, v49
	v_mad_i64_i32 v[48:49], s[30:31], v55, s67, v[12:13]
	v_rcp_f32_e32 v7, v6
	v_cvt_pk_bf16_f32 v6, v8, v9
	v_mad_i64_i32 v[8:9], s[30:31], v31, s67, v[12:13]
	v_pk_fma_f32 v[12:13], v[26:27], s[18:19], v[50:51] op_sel_hi:[1,0,1]
	v_pk_fma_f32 v[42:43], v[42:43], s[18:19], v[50:51] op_sel_hi:[1,0,1]
	v_mul_f32_e32 v12, 0xbfb8aa3b, v12
	v_mul_f32_e32 v42, 0xbfb8aa3b, v42
	v_exp_f32_e32 v26, v12
	v_mul_f32_e32 v12, 0xbfb8aa3b, v13
	v_cvt_pk_bf16_f32 v47, v54, v47
	v_exp_f32_e32 v54, v42
	v_mul_f32_e32 v42, 0xbfb8aa3b, v43
	v_exp_f32_e32 v27, v12
	v_pk_fma_f32 v[12:13], v[28:29], s[18:19], v[52:53] op_sel_hi:[1,0,1]
	v_exp_f32_e32 v55, v42
	v_pk_fma_f32 v[42:43], v[44:45], s[18:19], v[52:53] op_sel_hi:[1,0,1]
	v_mul_f32_e32 v12, 0xbfb8aa3b, v12
	v_mul_f32_e32 v13, 0xbfb8aa3b, v13
	v_mul_f32_e32 v42, 0xbfb8aa3b, v42
	v_exp_f32_e32 v12, v12
	v_exp_f32_e32 v13, v13
	v_exp_f32_e32 v42, v42
	v_mul_f32_e32 v43, 0xbfb8aa3b, v43
	v_exp_f32_e32 v43, v43
	v_add_f32_e32 v26, 1.0, v26
	v_add_f32_e32 v27, 1.0, v27
	v_add_f32_e32 v12, 1.0, v12
	v_add_f32_e32 v13, 1.0, v13
	v_add_f32_e32 v42, 1.0, v42
	v_rcp_f32_e32 v26, v26
	v_rcp_f32_e32 v27, v27
	v_rcp_f32_e32 v12, v12
	v_rcp_f32_e32 v13, v13
	v_add_f32_e32 v44, 1.0, v54
	v_add_f32_e32 v45, 1.0, v55
	v_rcp_f32_e32 v54, v42
	v_add_f32_e32 v42, 1.0, v43
	v_rcp_f32_e32 v44, v44
	v_rcp_f32_e32 v45, v45
	v_rcp_f32_e32 v55, v42
	v_cvt_pk_bf16_f32 v7, v30, v7
	v_lshl_add_u64 v[8:9], v[8:9], 0, v[10:11]
	v_mov_b32_e32 v200, v6
	v_mov_b32_e32 v201, v7
	v_cvt_pk_bf16_f32 v6, v26, v27
	v_cvt_pk_bf16_f32 v7, v12, v13
	v_pk_fma_f32 v[38:39], v[38:39], s[18:19], v[14:15] op_sel_hi:[1,0,1]
	v_mov_b32_e32 v202, v6
	v_mov_b32_e32 v203, v7
	v_lshl_add_u64 v[198:199], v[8:9], 0, v[196:197]
	s_nop 0
	v_permlane16_swap_b32 v200, v202
	v_permlane16_swap_b32 v201, v203
	global_store_dwordx4 v[198:199], v[200:203], off
	v_pk_fma_f32 v[6:7], v[22:23], s[18:19], v[14:15] op_sel_hi:[1,0,1]
	v_lshl_add_u64 v[42:43], v[48:49], 0, v[10:11]
	v_cvt_pk_bf16_f32 v44, v44, v45
	v_cvt_pk_bf16_f32 v45, v54, v55
	v_mul_f32_e32 v38, 0xbfb8aa3b, v38
	v_mul_f32_e32 v6, 0xbfb8aa3b, v6
	v_mov_b32_e32 v206, v44
	v_mov_b32_e32 v207, v45
	v_exp_f32_e32 v44, v38
	v_mul_f32_e32 v38, 0xbfb8aa3b, v39
	v_exp_f32_e32 v10, v6
	v_mul_f32_e32 v6, 0xbfb8aa3b, v7
	v_exp_f32_e32 v45, v38
	v_exp_f32_e32 v11, v6
	v_pk_fma_f32 v[38:39], v[40:41], s[18:19], v[16:17] op_sel_hi:[1,0,1]
	v_add_f32_e32 v40, 1.0, v44
	v_add_f32_e32 v41, 1.0, v45
	v_pk_fma_f32 v[6:7], v[24:25], s[18:19], v[16:17] op_sel_hi:[1,0,1]
	v_add_f32_e32 v10, 1.0, v10
	v_add_f32_e32 v11, 1.0, v11
	v_rcp_f32_e32 v40, v40
	v_rcp_f32_e32 v41, v41
	v_mul_f32_e32 v38, 0xbfb8aa3b, v38
	v_rcp_f32_e32 v10, v10
	v_rcp_f32_e32 v11, v11
	v_mul_f32_e32 v6, 0xbfb8aa3b, v6
	v_exp_f32_e32 v44, v38
	v_exp_f32_e32 v12, v6
	v_pk_fma_f32 v[34:35], v[34:35], s[18:19], v[2:3] op_sel_hi:[1,0,1]
	v_pk_fma_f32 v[2:3], v[18:19], s[18:19], v[2:3] op_sel_hi:[1,0,1]
	v_mul_f32_e32 v38, 0xbfb8aa3b, v39
	v_mul_f32_e32 v34, 0xbfb8aa3b, v34
	v_mul_f32_e32 v6, 0xbfb8aa3b, v7
	v_mul_f32_e32 v2, 0xbfb8aa3b, v2
	v_exp_f32_e32 v39, v38
	v_cvt_pk_bf16_f32 v38, v40, v41
	v_exp_f32_e32 v41, v34
	v_mul_f32_e32 v34, 0xbfb8aa3b, v35
	v_exp_f32_e32 v7, v6
	v_cvt_pk_bf16_f32 v6, v10, v11
	v_exp_f32_e32 v11, v2
	v_mul_f32_e32 v2, 0xbfb8aa3b, v3
	v_add_f32_e32 v40, 1.0, v44
	v_exp_f32_e32 v44, v34
	v_pk_fma_f32 v[34:35], v[36:37], s[18:19], v[4:5] op_sel_hi:[1,0,1]
	v_add_f32_e32 v10, 1.0, v12
	v_exp_f32_e32 v12, v2
	v_pk_fma_f32 v[2:3], v[20:21], s[18:19], v[4:5] op_sel_hi:[1,0,1]
	v_mul_f32_e32 v34, 0xbfb8aa3b, v34
	v_mul_f32_e32 v2, 0xbfb8aa3b, v2
	v_exp_f32_e32 v34, v34
	v_mul_f32_e32 v35, 0xbfb8aa3b, v35
	v_exp_f32_e32 v2, v2
	v_mul_f32_e32 v3, 0xbfb8aa3b, v3
	v_exp_f32_e32 v35, v35
	v_exp_f32_e32 v3, v3
	v_add_f32_e32 v34, 1.0, v34
	v_add_f32_e32 v2, 1.0, v2
	v_add_f32_e32 v39, 1.0, v39
	v_add_f32_e32 v36, 1.0, v41
	v_add_f32_e32 v37, 1.0, v44
	v_rcp_f32_e32 v41, v34
	v_add_f32_e32 v34, 1.0, v35
	v_add_f32_e32 v7, 1.0, v7
	v_add_f32_e32 v4, 1.0, v11
	v_add_f32_e32 v5, 1.0, v12
	v_rcp_f32_e32 v11, v2
	v_add_f32_e32 v2, 1.0, v3
	v_rcp_f32_e32 v40, v40
	v_rcp_f32_e32 v39, v39
	v_rcp_f32_e32 v36, v36
	v_rcp_f32_e32 v37, v37
	v_rcp_f32_e32 v35, v34
	v_rcp_f32_e32 v10, v10
	v_rcp_f32_e32 v7, v7
	v_rcp_f32_e32 v4, v4
	v_rcp_f32_e32 v5, v5
	v_rcp_f32_e32 v3, v2
	v_cvt_pk_bf16_f32 v39, v40, v39
	v_cvt_pk_bf16_f32 v34, v36, v37
	v_cvt_pk_bf16_f32 v35, v41, v35
	v_cvt_pk_bf16_f32 v7, v10, v7
	v_cvt_pk_bf16_f32 v2, v4, v5
	v_cvt_pk_bf16_f32 v3, v11, v3
	s_mov_b64 s[30:31], s[26:27]
	v_mov_b32_e32 v204, v46
	v_mov_b32_e32 v205, v47
	v_lshl_add_u64 v[198:199], v[42:43], 0, v[196:197]
	s_nop 0
	v_permlane16_swap_b32 v204, v206
	v_permlane16_swap_b32 v205, v207
	global_store_dwordx4 v[198:199], v[204:207], off
	v_mov_b32_e32 v208, v38
	v_mov_b32_e32 v209, v39
	v_mov_b32_e32 v210, v34
	v_mov_b32_e32 v211, v35
	v_lshl_add_u64 v[198:199], v[42:43], 0, v[196:197]
	s_nop 0
	v_permlane16_swap_b32 v208, v210
	v_permlane16_swap_b32 v209, v211
	global_store_dwordx4 v[198:199], v[208:211], off offset:256
	v_mov_b32_e32 v200, v6
	v_mov_b32_e32 v201, v7
	v_mov_b32_e32 v202, v2
	v_mov_b32_e32 v203, v3
	v_lshl_add_u64 v[198:199], v[8:9], 0, v[196:197]
	s_nop 0
	v_permlane16_swap_b32 v200, v202
	v_permlane16_swap_b32 v201, v203
	global_store_dwordx4 v[198:199], v[200:203], off offset:256
	s_cbranch_vccz .LBB0_4315
	s_waitcnt vmcnt(0)
	s_cmpk_gt_u32 s3, 0xff
	s_cbranch_scc1 .LBB0_4322
	s_barrier

.LBB0_5692:
	ds_read_b128 v[2:5], v167
	ds_read_b128 v[6:9], v171
	ds_read_b128 v[10:13], v172
	ds_read_b128 v[14:17], v173
	s_add_u32 s28, s26, 0x100
	s_addc_u32 s29, s27, 0
	s_cmp_eq_u32 s70, 18
	s_cselect_b32 s35, s9, s29
	s_cselect_b32 s34, s8, s28
	s_cselect_b32 s31, s11, s69
	s_cselect_b32 s30, s10, s68
	v_lshl_add_u64 v[158:159], s[26:27], 0, v[152:153]
	s_add_i32 m0, s41, 0xc000
	ds_read_b128 v[186:189], v184
	ds_read_b128 v[190:193], v184 offset:1024
	ds_read_b128 v[194:197], v184 offset:2048
	ds_read_b128 v[198:201], v184 offset:3072
	ds_read_b128 v[202:205], v184 offset:4096
	ds_read_b128 v[206:209], v184 offset:5120
	ds_read_b128 v[210:213], v184 offset:6144
	ds_read_b128 v[214:217], v184 offset:7168
	global_load_lds_dwordx4 v[158:159], off
	v_lshl_add_u64 v[158:159], s[26:27], 0, v[150:151]
	s_add_i32 m0, s41, 0xe000
	s_nop 0
	global_load_lds_dwordx4 v[158:159], off
	s_waitcnt lgkmcnt(8)
	s_barrier
	s_waitcnt lgkmcnt(0)
	s_setprio 1
	s_waitcnt lgkmcnt(0)
	v_mfma_f32_16x16x128_f8f6f4 v[142:145], v[2:9], v[186:193], v[142:145]
	v_mfma_f32_16x16x128_f8f6f4 v[138:141], v[10:17], v[186:193], v[138:141]
	v_mfma_f32_16x16x128_f8f6f4 v[134:137], v[2:9], v[194:201], v[134:137]
	v_mfma_f32_16x16x128_f8f6f4 v[130:133], v[10:17], v[194:201], v[130:133]
	v_mfma_f32_16x16x128_f8f6f4 v[110:113], v[2:9], v[202:209], v[110:113]
	v_mfma_f32_16x16x128_f8f6f4 v[106:109], v[10:17], v[202:209], v[106:109]
	v_mfma_f32_16x16x128_f8f6f4 v[102:105], v[2:9], v[210:217], v[102:105]
	v_mfma_f32_16x16x128_f8f6f4 v[98:101], v[10:17], v[210:217], v[98:101]
	s_setprio 0
	s_barrier
	s_mov_b32 m0, s42
	v_lshl_add_u64 v[158:159], s[30:31], 0, v[146:147]
	ds_read_b128 v[220:223], v168
	ds_read_b128 v[224:227], v174
	ds_read_b128 v[228:231], v175
	ds_read_b128 v[232:235], v176
	global_load_lds_dwordx4 v[158:159], off
	v_lshl_add_u64 v[160:161], s[30:31], 0, v[148:149]
	s_mov_b32 m0, s43
	s_nop 0
	global_load_lds_dwordx4 v[160:161], off
	s_barrier
	s_waitcnt lgkmcnt(0)
	s_setprio 1
	s_waitcnt lgkmcnt(0)
	v_mfma_f32_16x16x128_f8f6f4 v[126:129], v[220:227], v[186:193], v[126:129]
	v_mfma_f32_16x16x128_f8f6f4 v[122:125], v[228:235], v[186:193], v[122:125]
	v_mfma_f32_16x16x128_f8f6f4 v[118:121], v[220:227], v[194:201], v[118:121]
	v_mfma_f32_16x16x128_f8f6f4 v[114:117], v[228:235], v[194:201], v[114:117]
	v_mfma_f32_16x16x128_f8f6f4 v[94:97], v[220:227], v[202:209], v[94:97]
	v_mfma_f32_16x16x128_f8f6f4 v[90:93], v[228:235], v[202:209], v[90:93]
	v_mfma_f32_16x16x128_f8f6f4 v[86:89], v[220:227], v[210:217], v[86:89]
	v_mfma_f32_16x16x128_f8f6f4 v[82:85], v[228:235], v[210:217], v[82:85]
	s_setprio 0
	s_mov_b32 m0, s41
	v_lshl_add_u64 v[162:163], s[34:35], 0, v[146:147]
	s_barrier
	ds_read_b128 v[186:189], v184 offset:16384
	ds_read_b128 v[190:193], v184 offset:17408
	ds_read_b128 v[194:197], v184 offset:18432
	ds_read_b128 v[198:201], v184 offset:19456
	ds_read_b128 v[202:205], v184 offset:20480
	ds_read_b128 v[206:209], v184 offset:21504
	ds_read_b128 v[210:213], v184 offset:22528
	ds_read_b128 v[214:217], v184 offset:23552
	global_load_lds_dwordx4 v[162:163], off
	v_lshl_add_u64 v[164:165], s[34:35], 0, v[148:149]
	s_mov_b32 m0, s44
	s_nop 0
	global_load_lds_dwordx4 v[164:165], off
	s_barrier
	s_waitcnt lgkmcnt(0)
	s_setprio 1
	s_waitcnt lgkmcnt(0)
	v_mfma_f32_16x16x128_f8f6f4 v[78:81], v[2:9], v[186:193], v[78:81]
	v_mfma_f32_16x16x128_f8f6f4 v[74:77], v[10:17], v[186:193], v[74:77]
	v_mfma_f32_16x16x128_f8f6f4 v[70:73], v[2:9], v[194:201], v[70:73]
	v_mfma_f32_16x16x128_f8f6f4 v[66:69], v[10:17], v[194:201], v[66:69]
	v_mfma_f32_16x16x128_f8f6f4 v[46:49], v[2:9], v[202:209], v[46:49]
	v_mfma_f32_16x16x128_f8f6f4 v[42:45], v[10:17], v[202:209], v[42:45]
	v_mfma_f32_16x16x128_f8f6f4 v[38:41], v[2:9], v[210:217], v[38:41]
	v_mfma_f32_16x16x128_f8f6f4 v[34:37], v[10:17], v[210:217], v[34:37]
	s_setprio 0
	s_barrier
	s_add_u32 s26, s30, 0x58000
	s_addc_u32 s27, s31, 0
	s_mov_b32 m0, s45
	v_lshl_add_u64 v[2:3], s[26:27], 0, v[146:147]
	global_load_lds_dwordx4 v[2:3], off
	v_lshl_add_u64 v[2:3], s[26:27], 0, v[148:149]
	s_mov_b32 m0, s46
	s_nop 0
	global_load_lds_dwordx4 v[2:3], off
	s_waitcnt vmcnt(6)
	s_barrier
	s_setprio 1
	v_mfma_f32_16x16x128_f8f6f4 v[62:65], v[220:227], v[186:193], v[62:65]
	v_mfma_f32_16x16x128_f8f6f4 v[58:61], v[228:235], v[186:193], v[58:61]
	v_mfma_f32_16x16x128_f8f6f4 v[54:57], v[220:227], v[194:201], v[54:57]
	v_mfma_f32_16x16x128_f8f6f4 v[50:53], v[228:235], v[194:201], v[50:53]
	v_mfma_f32_16x16x128_f8f6f4 v[30:33], v[220:227], v[202:209], v[30:33]
	v_mfma_f32_16x16x128_f8f6f4 v[26:29], v[228:235], v[202:209], v[26:29]
	v_mfma_f32_16x16x128_f8f6f4 v[22:25], v[220:227], v[210:217], v[22:25]
	v_mfma_f32_16x16x128_f8f6f4 v[18:21], v[228:235], v[210:217], v[18:21]
	s_setprio 0
	s_barrier
	ds_read_b128 v[2:5], v169
	ds_read_b128 v[6:9], v177
	ds_read_b128 v[10:13], v178
	ds_read_b128 v[14:17], v179
	s_add_u32 s26, s34, 0x58000
	s_addc_u32 s27, s35, 0
	s_mov_b32 m0, s47
	v_lshl_add_u64 v[220:221], s[26:27], 0, v[146:147]
	ds_read_b128 v[186:189], v184 offset:32768
	ds_read_b128 v[190:193], v184 offset:33792
	ds_read_b128 v[194:197], v184 offset:34816
	ds_read_b128 v[198:201], v184 offset:35840
	ds_read_b128 v[202:205], v184 offset:36864
	ds_read_b128 v[206:209], v184 offset:37888
	ds_read_b128 v[210:213], v184 offset:38912
	ds_read_b128 v[214:217], v184 offset:39936
	global_load_lds_dwordx4 v[220:221], off
	v_lshl_add_u64 v[220:221], s[26:27], 0, v[148:149]
	s_mov_b32 m0, s48
	s_nop 0
	global_load_lds_dwordx4 v[220:221], off
	s_waitcnt lgkmcnt(8)
	s_barrier
	s_waitcnt lgkmcnt(0)
	s_setprio 1
	s_waitcnt lgkmcnt(0)
	v_mfma_f32_16x16x128_f8f6f4 v[142:145], v[2:9], v[186:193], v[142:145]
	v_mfma_f32_16x16x128_f8f6f4 v[138:141], v[10:17], v[186:193], v[138:141]
	v_mfma_f32_16x16x128_f8f6f4 v[134:137], v[2:9], v[194:201], v[134:137]
	v_mfma_f32_16x16x128_f8f6f4 v[130:133], v[10:17], v[194:201], v[130:133]
	v_mfma_f32_16x16x128_f8f6f4 v[110:113], v[2:9], v[202:209], v[110:113]
	v_mfma_f32_16x16x128_f8f6f4 v[106:109], v[10:17], v[202:209], v[106:109]
	v_mfma_f32_16x16x128_f8f6f4 v[102:105], v[2:9], v[210:217], v[102:105]
	v_mfma_f32_16x16x128_f8f6f4 v[98:101], v[10:17], v[210:217], v[98:101]
	s_setprio 0
	s_barrier
	s_mov_b32 m0, s50
	v_lshl_add_u64 v[158:159], v[158:159], 0, s[18:19]
	ds_read_b128 v[220:223], v170
	ds_read_b128 v[224:227], v180
	ds_read_b128 v[228:231], v181
	ds_read_b128 v[232:235], v182
	global_load_lds_dwordx4 v[158:159], off
	v_lshl_add_u64 v[158:159], v[160:161], 0, s[18:19]
	s_mov_b32 m0, s51
	s_nop 0
	global_load_lds_dwordx4 v[158:159], off
	s_barrier
	s_waitcnt lgkmcnt(0)
	s_setprio 1
	s_waitcnt lgkmcnt(0)
	v_mfma_f32_16x16x128_f8f6f4 v[126:129], v[220:227], v[186:193], v[126:129]
	v_mfma_f32_16x16x128_f8f6f4 v[122:125], v[228:235], v[186:193], v[122:125]
	v_mfma_f32_16x16x128_f8f6f4 v[118:121], v[220:227], v[194:201], v[118:121]
	v_mfma_f32_16x16x128_f8f6f4 v[114:117], v[228:235], v[194:201], v[114:117]
	v_mfma_f32_16x16x128_f8f6f4 v[94:97], v[220:227], v[202:209], v[94:97]
	v_mfma_f32_16x16x128_f8f6f4 v[90:93], v[228:235], v[202:209], v[90:93]
	v_mfma_f32_16x16x128_f8f6f4 v[86:89], v[220:227], v[210:217], v[86:89]
	v_mfma_f32_16x16x128_f8f6f4 v[82:85], v[228:235], v[210:217], v[82:85]
	s_setprio 0
	s_mov_b32 m0, s52
	v_lshl_add_u64 v[158:159], v[162:163], 0, s[18:19]
	s_barrier
	ds_read_b128 v[186:189], v184 offset:49152
	ds_read_b128 v[190:193], v184 offset:50176
	ds_read_b128 v[194:197], v184 offset:51200
	ds_read_b128 v[198:201], v184 offset:52224
	ds_read_b128 v[202:205], v184 offset:53248
	ds_read_b128 v[206:209], v184 offset:54272
	ds_read_b128 v[210:213], v184 offset:55296
	ds_read_b128 v[214:217], v184 offset:56320
	global_load_lds_dwordx4 v[158:159], off
	v_lshl_add_u64 v[158:159], v[164:165], 0, s[18:19]
	s_mov_b32 m0, s53
	s_nop 0
	global_load_lds_dwordx4 v[158:159], off
	s_barrier
	s_waitcnt lgkmcnt(0)
	s_setprio 1
	s_waitcnt lgkmcnt(0)
	v_mfma_f32_16x16x128_f8f6f4 v[78:81], v[2:9], v[186:193], v[78:81]
	v_mfma_f32_16x16x128_f8f6f4 v[74:77], v[10:17], v[186:193], v[74:77]
	v_mfma_f32_16x16x128_f8f6f4 v[70:73], v[2:9], v[194:201], v[70:73]
	v_mfma_f32_16x16x128_f8f6f4 v[66:69], v[10:17], v[194:201], v[66:69]
	v_mfma_f32_16x16x128_f8f6f4 v[46:49], v[2:9], v[202:209], v[46:49]
	v_mfma_f32_16x16x128_f8f6f4 v[42:45], v[10:17], v[202:209], v[42:45]
	v_mfma_f32_16x16x128_f8f6f4 v[38:41], v[2:9], v[210:217], v[38:41]
	v_mfma_f32_16x16x128_f8f6f4 v[34:37], v[10:17], v[210:217], v[34:37]
	s_setprio 0
	s_barrier
	s_add_u32 s26, s30, 0x58080
	s_addc_u32 s27, s31, 0
	s_mov_b32 m0, s55
	v_lshl_add_u64 v[2:3], s[26:27], 0, v[146:147]
	global_load_lds_dwordx4 v[2:3], off
	v_lshl_add_u64 v[2:3], s[26:27], 0, v[148:149]
	s_mov_b32 m0, s58
	s_nop 0
	global_load_lds_dwordx4 v[2:3], off
	s_waitcnt vmcnt(6)
	s_barrier
	s_setprio 1
	v_mfma_f32_16x16x128_f8f6f4 v[62:65], v[220:227], v[186:193], v[62:65]
	v_mfma_f32_16x16x128_f8f6f4 v[58:61], v[228:235], v[186:193], v[58:61]
	v_mfma_f32_16x16x128_f8f6f4 v[54:57], v[220:227], v[194:201], v[54:57]
	v_mfma_f32_16x16x128_f8f6f4 v[50:53], v[228:235], v[194:201], v[50:53]
	v_mfma_f32_16x16x128_f8f6f4 v[30:33], v[220:227], v[202:209], v[30:33]
	v_mfma_f32_16x16x128_f8f6f4 v[26:29], v[228:235], v[202:209], v[26:29]
	v_mfma_f32_16x16x128_f8f6f4 v[22:25], v[220:227], v[210:217], v[22:25]
	v_mfma_f32_16x16x128_f8f6f4 v[18:21], v[228:235], v[210:217], v[18:21]
	s_setprio 0
	s_add_i32 s70, s70, 2
	s_add_u32 s68, s68, 0x100
	s_addc_u32 s69, s69, 0
	s_cmp_gt_u32 s70, 19
	s_mov_b64 s[26:27], s[28:29]
	s_barrier
	s_cbranch_scc0 .LBB0_5692
	v_bfe_u32 v160, v0, 4, 1
	v_mul_u32_u24_e32 v160, 24, v160
	v_mov_b32_e32 v161, 0
	v_lshl_add_u32 v6, s67, 8, v166
	v_ashrrev_i32_e32 v7, 31, v6
	v_or_b32_e32 v4, 16, v6
	s_nop 15
	s_nop 15
	v_lshl_add_u64 v[2:3], v[6:7], 2, s[16:17]
	v_ashrrev_i32_e32 v5, 31, v4
	global_load_dword v158, v[2:3], off
	v_lshl_add_u64 v[8:9], v[4:5], 2, s[16:17]
	global_load_dword v159, v[8:9], off
	s_ashr_i32 s0, s66, 31
	s_lshr_b32 s0, s0, 30
	s_add_i32 s0, s66, s0
	s_and_b32 s0, s0, 0xfffffc
	v_lshlrev_b64 v[4:5], 11, v[4:5]
	s_sub_i32 s0, s66, s0
	v_lshl_add_u64 v[14:15], s[14:15], 0, v[4:5]
	v_lshl_or_b32 v4, s0, 8, v183
	v_lshlrev_b64 v[10:11], 11, v[6:7]
	v_ashrrev_i32_e32 v5, 31, v4
	v_lshl_add_u64 v[10:11], s[14:15], 0, v[10:11]
	v_lshlrev_b64 v[16:17], 1, v[4:5]
	v_lshl_add_u64 v[4:5], v[10:11], 0, v[16:17]
	v_lshl_add_u64 v[10:11], v[14:15], 0, v[16:17]
	v_or_b32_e32 v8, 32, v6
	v_ashrrev_i32_e32 v9, 31, v8
	v_lshl_add_u64 v[12:13], v[8:9], 2, s[16:17]
	v_or_b32_e32 v6, 48, v6
	v_ashrrev_i32_e32 v7, 31, v6
	v_lshlrev_b64 v[8:9], 11, v[8:9]
	v_lshlrev_b64 v[6:7], 11, v[6:7]
	v_lshl_add_u64 v[8:9], s[14:15], 0, v[8:9]
	v_lshl_add_u64 v[6:7], s[14:15], 0, v[6:7]
	v_lshl_add_u64 v[8:9], v[8:9], 0, v[16:17]
	v_lshl_add_u64 v[6:7], v[6:7], 0, v[16:17]
	s_mov_b32 s67, s64
	s_mov_b64 s[28:29], s[10:11]
	s_mov_b64 s[26:27], s[8:9]
	s_mov_b32 s66, s65
	s_waitcnt vmcnt(0)
	v_mul_f32_e32 v14, 0x3b800000, v158
	v_pk_mul_f32 v[142:143], v[142:143], v[14:15] op_sel_hi:[1,0]
	v_pk_mul_f32 v[144:145], v[144:145], v[14:15] op_sel_hi:[1,0]
	v_pk_mul_f32 v[138:139], v[138:139], v[14:15] op_sel_hi:[1,0]
	v_pk_mul_f32 v[140:141], v[140:141], v[14:15] op_sel_hi:[1,0]
	v_pk_mul_f32 v[126:127], v[126:127], v[14:15] op_sel_hi:[1,0]
	v_pk_mul_f32 v[128:129], v[128:129], v[14:15] op_sel_hi:[1,0]
	v_pk_mul_f32 v[122:123], v[122:123], v[14:15] op_sel_hi:[1,0]
	v_pk_mul_f32 v[14:15], v[124:125], v[14:15] op_sel_hi:[1,0]
	v_mul_f32_e32 v124, 0x3b800000, v159
	v_cvt_pk_bf16_f32 v126, v126, v127
	v_cvt_pk_bf16_f32 v127, v128, v129
	v_cvt_pk_bf16_f32 v122, v122, v123
	v_cvt_pk_bf16_f32 v123, v14, v15
	v_pk_mul_f32 v[14:15], v[134:135], v[124:125] op_sel_hi:[1,0]
	v_pk_mul_f32 v[128:129], v[136:137], v[124:125] op_sel_hi:[1,0]
	v_cvt_pk_bf16_f32 v142, v142, v143
	v_cvt_pk_bf16_f32 v143, v144, v145
	v_pk_mul_f32 v[130:131], v[130:131], v[124:125] op_sel_hi:[1,0]
	v_pk_mul_f32 v[132:133], v[132:133], v[124:125] op_sel_hi:[1,0]
	v_pk_mul_f32 v[118:119], v[118:119], v[124:125] op_sel_hi:[1,0]
	v_pk_mul_f32 v[120:121], v[120:121], v[124:125] op_sel_hi:[1,0]
	v_pk_mul_f32 v[114:115], v[114:115], v[124:125] op_sel_hi:[1,0]
	v_pk_mul_f32 v[116:117], v[116:117], v[124:125] op_sel_hi:[1,0]
	v_cvt_pk_bf16_f32 v14, v14, v15
	v_cvt_pk_bf16_f32 v15, v128, v129
	v_cvt_pk_bf16_f32 v138, v138, v139
	v_cvt_pk_bf16_f32 v139, v140, v141
	v_mov_b32_e32 v188, v142
	v_mov_b32_e32 v189, v143
	v_mov_b32_e32 v190, v138
	v_mov_b32_e32 v191, v139
	v_lshl_add_u64 v[162:163], v[4:5], 0, v[160:161]
	s_nop 0
	v_permlane16_swap_b32 v188, v190
	v_permlane16_swap_b32 v189, v191
	global_store_dwordx4 v[162:163], v[188:191], off
	v_mov_b32_e32 v192, v126
	v_mov_b32_e32 v193, v127
	v_mov_b32_e32 v194, v122
	v_mov_b32_e32 v195, v123
	v_lshl_add_u64 v[162:163], v[4:5], 0, v[160:161]
	s_nop 0
	v_permlane16_swap_b32 v192, v194
	v_permlane16_swap_b32 v193, v195
	global_store_dwordx4 v[162:163], v[192:195], off offset:256
	v_cvt_pk_bf16_f32 v122, v130, v131
	v_cvt_pk_bf16_f32 v123, v132, v133
	v_cvt_pk_bf16_f32 v118, v118, v119
	v_cvt_pk_bf16_f32 v119, v120, v121
	v_cvt_pk_bf16_f32 v114, v114, v115
	v_cvt_pk_bf16_f32 v115, v116, v117
	v_mov_b32_e32 v196, v14
	v_mov_b32_e32 v197, v15
	v_mov_b32_e32 v198, v122
	v_mov_b32_e32 v199, v123
	v_lshl_add_u64 v[162:163], v[10:11], 0, v[160:161]
	s_nop 0
	v_permlane16_swap_b32 v196, v198
	v_permlane16_swap_b32 v197, v199
	global_store_dwordx4 v[162:163], v[196:199], off
	v_mov_b32_e32 v188, v118
	v_mov_b32_e32 v189, v119
	v_mov_b32_e32 v190, v114
	v_mov_b32_e32 v191, v115
	v_lshl_add_u64 v[162:163], v[10:11], 0, v[160:161]
	s_nop 0
	v_permlane16_swap_b32 v188, v190
	v_permlane16_swap_b32 v189, v191
	global_store_dwordx4 v[162:163], v[188:191], off offset:256
	global_load_dword v10, v[12:13], off
	s_nop 0
	global_load_dword v11, v[2:3], off offset:192
	s_waitcnt vmcnt(0)
	v_mul_f32_e32 v10, 0x3b800000, v10
	v_mul_f32_e32 v12, 0x3b800000, v11
	v_pk_mul_f32 v[14:15], v[110:111], v[10:11] op_sel_hi:[1,0]
	v_pk_mul_f32 v[16:17], v[112:113], v[10:11] op_sel_hi:[1,0]
	v_pk_mul_f32 v[106:107], v[106:107], v[10:11] op_sel_hi:[1,0]
	v_pk_mul_f32 v[108:109], v[108:109], v[10:11] op_sel_hi:[1,0]
	v_pk_mul_f32 v[94:95], v[94:95], v[10:11] op_sel_hi:[1,0]
	v_pk_mul_f32 v[96:97], v[96:97], v[10:11] op_sel_hi:[1,0]
	v_pk_mul_f32 v[90:91], v[90:91], v[10:11] op_sel_hi:[1,0]
	v_pk_mul_f32 v[10:11], v[92:93], v[10:11] op_sel_hi:[1,0]
	v_pk_mul_f32 v[92:93], v[102:103], v[12:13] op_sel_hi:[1,0]
	v_pk_mul_f32 v[102:103], v[104:105], v[12:13] op_sel_hi:[1,0]
	v_pk_mul_f32 v[98:99], v[98:99], v[12:13] op_sel_hi:[1,0]
	v_pk_mul_f32 v[100:101], v[100:101], v[12:13] op_sel_hi:[1,0]
	v_pk_mul_f32 v[86:87], v[86:87], v[12:13] op_sel_hi:[1,0]
	v_pk_mul_f32 v[88:89], v[88:89], v[12:13] op_sel_hi:[1,0]
	v_pk_mul_f32 v[82:83], v[82:83], v[12:13] op_sel_hi:[1,0]
	v_pk_mul_f32 v[12:13], v[84:85], v[12:13] op_sel_hi:[1,0]
	v_cvt_pk_bf16_f32 v14, v14, v15
	v_cvt_pk_bf16_f32 v15, v16, v17
	v_cvt_pk_bf16_f32 v16, v106, v107
	v_cvt_pk_bf16_f32 v17, v108, v109
	v_cvt_pk_bf16_f32 v84, v94, v95
	v_cvt_pk_bf16_f32 v85, v96, v97
	v_cvt_pk_bf16_f32 v90, v90, v91
	v_cvt_pk_bf16_f32 v91, v10, v11
	v_cvt_pk_bf16_f32 v10, v92, v93
	v_cvt_pk_bf16_f32 v11, v102, v103
	v_cvt_pk_bf16_f32 v92, v98, v99
	v_cvt_pk_bf16_f32 v93, v100, v101
	v_cvt_pk_bf16_f32 v86, v86, v87
	v_cvt_pk_bf16_f32 v87, v88, v89
	v_cvt_pk_bf16_f32 v82, v82, v83
	v_cvt_pk_bf16_f32 v83, v12, v13
	v_mov_b32_e32 v192, v14
	v_mov_b32_e32 v193, v15
	v_mov_b32_e32 v194, v16
	v_mov_b32_e32 v195, v17
	v_lshl_add_u64 v[162:163], v[8:9], 0, v[160:161]
	s_nop 0
	v_permlane16_swap_b32 v192, v194
	v_permlane16_swap_b32 v193, v195
	global_store_dwordx4 v[162:163], v[192:195], off
	v_mov_b32_e32 v196, v84
	v_mov_b32_e32 v197, v85
	v_mov_b32_e32 v198, v90
	v_mov_b32_e32 v199, v91
	v_lshl_add_u64 v[162:163], v[8:9], 0, v[160:161]
	s_nop 0
	v_permlane16_swap_b32 v196, v198
	v_permlane16_swap_b32 v197, v199
	global_store_dwordx4 v[162:163], v[196:199], off offset:256
	v_mov_b32_e32 v188, v10
	v_mov_b32_e32 v189, v11
	v_mov_b32_e32 v190, v92
	v_mov_b32_e32 v191, v93
	v_lshl_add_u64 v[162:163], v[6:7], 0, v[160:161]
	s_nop 0
	v_permlane16_swap_b32 v188, v190
	v_permlane16_swap_b32 v189, v191
	global_store_dwordx4 v[162:163], v[188:191], off
	v_mov_b32_e32 v192, v86
	v_mov_b32_e32 v193, v87
	v_mov_b32_e32 v194, v82
	v_mov_b32_e32 v195, v83
	v_lshl_add_u64 v[162:163], v[6:7], 0, v[160:161]
	s_nop 0
	v_permlane16_swap_b32 v192, v194
	v_permlane16_swap_b32 v193, v195
	global_store_dwordx4 v[162:163], v[192:195], off offset:256
	global_load_dword v14, v[2:3], off offset:512
	global_load_dword v15, v[2:3], off offset:576
	v_add_co_u32_e32 v8, vcc, s60, v4
	v_lshl_add_u64 v[6:7], v[4:5], 0, s[20:21]
	s_nop 0
	v_addc_co_u32_e32 v9, vcc, 0, v5, vcc
	v_add_co_u32_e32 v12, vcc, s61, v4
	v_lshl_add_u64 v[10:11], v[4:5], 0, s[22:23]
	s_nop 0
	v_addc_co_u32_e32 v13, vcc, 0, v5, vcc
	s_and_b64 vcc, exec, s[6:7]
	s_waitcnt vmcnt(0)
	v_mul_f32_e32 v14, 0x3b800000, v14
	v_mul_f32_e32 v16, 0x3b800000, v15
	v_pk_mul_f32 v[78:79], v[78:79], v[14:15] op_sel_hi:[1,0]
	v_pk_mul_f32 v[80:81], v[80:81], v[14:15] op_sel_hi:[1,0]
	v_pk_mul_f32 v[74:75], v[74:75], v[14:15] op_sel_hi:[1,0]
	v_pk_mul_f32 v[76:77], v[76:77], v[14:15] op_sel_hi:[1,0]
	v_pk_mul_f32 v[62:63], v[62:63], v[14:15] op_sel_hi:[1,0]
	v_pk_mul_f32 v[64:65], v[64:65], v[14:15] op_sel_hi:[1,0]
	v_pk_mul_f32 v[58:59], v[58:59], v[14:15] op_sel_hi:[1,0]
	v_pk_mul_f32 v[14:15], v[60:61], v[14:15] op_sel_hi:[1,0]
	v_pk_mul_f32 v[60:61], v[70:71], v[16:17] op_sel_hi:[1,0]
	v_pk_mul_f32 v[70:71], v[72:73], v[16:17] op_sel_hi:[1,0]
	v_pk_mul_f32 v[66:67], v[66:67], v[16:17] op_sel_hi:[1,0]
	v_pk_mul_f32 v[68:69], v[68:69], v[16:17] op_sel_hi:[1,0]
	v_pk_mul_f32 v[54:55], v[54:55], v[16:17] op_sel_hi:[1,0]
	v_pk_mul_f32 v[56:57], v[56:57], v[16:17] op_sel_hi:[1,0]
	v_pk_mul_f32 v[50:51], v[50:51], v[16:17] op_sel_hi:[1,0]
	v_pk_mul_f32 v[16:17], v[52:53], v[16:17] op_sel_hi:[1,0]
	v_cvt_pk_bf16_f32 v52, v78, v79
	v_cvt_pk_bf16_f32 v53, v80, v81
	v_cvt_pk_bf16_f32 v72, v74, v75
	v_cvt_pk_bf16_f32 v73, v76, v77
	v_cvt_pk_bf16_f32 v62, v62, v63
	v_cvt_pk_bf16_f32 v63, v64, v65
	v_cvt_pk_bf16_f32 v58, v58, v59
	v_cvt_pk_bf16_f32 v59, v14, v15
	v_cvt_pk_bf16_f32 v14, v60, v61
	v_cvt_pk_bf16_f32 v15, v70, v71
	v_cvt_pk_bf16_f32 v60, v66, v67
	v_cvt_pk_bf16_f32 v61, v68, v69
	v_cvt_pk_bf16_f32 v54, v54, v55
	v_cvt_pk_bf16_f32 v55, v56, v57
	v_cvt_pk_bf16_f32 v50, v50, v51
	v_cvt_pk_bf16_f32 v51, v16, v17
	global_store_dwordx2 v[8:9], v[52:53], off
	global_store_dwordx2 v[6:7], v[72:73], off offset:32
	v_mov_b32_e32 v196, v62
	v_mov_b32_e32 v197, v63
	v_mov_b32_e32 v198, v58
	v_mov_b32_e32 v199, v59
	v_lshl_add_u64 v[162:163], v[6:7], 0, v[160:161]
	s_nop 0
	v_permlane16_swap_b32 v196, v198
	v_permlane16_swap_b32 v197, v199
	global_store_dwordx4 v[162:163], v[196:199], off offset:256
	global_store_dwordx2 v[12:13], v[14:15], off
	global_store_dwordx2 v[10:11], v[60:61], off offset:32
	v_mov_b32_e32 v188, v54
	v_mov_b32_e32 v189, v55
	v_mov_b32_e32 v190, v50
	v_mov_b32_e32 v191, v51
	v_lshl_add_u64 v[162:163], v[10:11], 0, v[160:161]
	s_nop 0
	v_permlane16_swap_b32 v188, v190
	v_permlane16_swap_b32 v189, v191
	global_store_dwordx4 v[162:163], v[188:191], off offset:256
	global_load_dword v10, v[2:3], off offset:640
	s_nop 0
	global_load_dword v11, v[2:3], off offset:704
	v_add_co_u32_e64 v6, s[6:7], s62, v4
	v_lshl_add_u64 v[2:3], v[4:5], 0, s[24:25]
	s_nop 0
	v_addc_co_u32_e64 v7, s[6:7], 0, v5, s[6:7]
	v_lshl_add_u64 v[8:9], v[4:5], 0, s[12:13]
	v_add_co_u32_e64 v4, s[6:7], s63, v4
	s_waitcnt vmcnt(0)
	v_mul_f32_e32 v10, 0x3b800000, v10
	v_mul_f32_e32 v12, 0x3b800000, v11
	v_pk_mul_f32 v[14:15], v[46:47], v[10:11] op_sel_hi:[1,0]
	v_pk_mul_f32 v[16:17], v[48:49], v[10:11] op_sel_hi:[1,0]
	v_pk_mul_f32 v[42:43], v[42:43], v[10:11] op_sel_hi:[1,0]
	v_pk_mul_f32 v[44:45], v[44:45], v[10:11] op_sel_hi:[1,0]
	v_pk_mul_f32 v[30:31], v[30:31], v[10:11] op_sel_hi:[1,0]
	v_pk_mul_f32 v[32:33], v[32:33], v[10:11] op_sel_hi:[1,0]
	v_pk_mul_f32 v[26:27], v[26:27], v[10:11] op_sel_hi:[1,0]
	v_pk_mul_f32 v[10:11], v[28:29], v[10:11] op_sel_hi:[1,0]
	v_pk_mul_f32 v[28:29], v[38:39], v[12:13] op_sel_hi:[1,0]
	v_pk_mul_f32 v[38:39], v[40:41], v[12:13] op_sel_hi:[1,0]
	v_pk_mul_f32 v[34:35], v[34:35], v[12:13] op_sel_hi:[1,0]
	v_pk_mul_f32 v[36:37], v[36:37], v[12:13] op_sel_hi:[1,0]
	v_pk_mul_f32 v[22:23], v[22:23], v[12:13] op_sel_hi:[1,0]
	v_pk_mul_f32 v[24:25], v[24:25], v[12:13] op_sel_hi:[1,0]
	v_pk_mul_f32 v[18:19], v[18:19], v[12:13] op_sel_hi:[1,0]
	v_pk_mul_f32 v[12:13], v[20:21], v[12:13] op_sel_hi:[1,0]
	v_cvt_pk_bf16_f32 v14, v14, v15
	v_cvt_pk_bf16_f32 v15, v16, v17
	v_addc_co_u32_e64 v5, s[6:7], 0, v5, s[6:7]
	v_cvt_pk_bf16_f32 v16, v42, v43
	v_cvt_pk_bf16_f32 v17, v44, v45
	v_cvt_pk_bf16_f32 v20, v30, v31
	v_cvt_pk_bf16_f32 v21, v32, v33
	v_cvt_pk_bf16_f32 v26, v26, v27
	v_cvt_pk_bf16_f32 v27, v10, v11
	v_cvt_pk_bf16_f32 v10, v28, v29
	v_cvt_pk_bf16_f32 v11, v38, v39
	v_cvt_pk_bf16_f32 v28, v34, v35
	v_cvt_pk_bf16_f32 v29, v36, v37
	v_cvt_pk_bf16_f32 v22, v22, v23
	v_cvt_pk_bf16_f32 v23, v24, v25
	v_cvt_pk_bf16_f32 v18, v18, v19
	v_cvt_pk_bf16_f32 v19, v12, v13
	global_store_dwordx2 v[6:7], v[14:15], off
	global_store_dwordx2 v[2:3], v[16:17], off offset:32
	v_mov_b32_e32 v192, v20
	v_mov_b32_e32 v193, v21
	v_mov_b32_e32 v194, v26
	v_mov_b32_e32 v195, v27
	v_lshl_add_u64 v[162:163], v[2:3], 0, v[160:161]
	s_nop 0
	v_permlane16_swap_b32 v192, v194
	v_permlane16_swap_b32 v193, v195
	global_store_dwordx4 v[162:163], v[192:195], off offset:256
	global_store_dwordx2 v[4:5], v[10:11], off
	global_store_dwordx2 v[8:9], v[28:29], off offset:32
	v_mov_b32_e32 v196, v22
	v_mov_b32_e32 v197, v23
	v_mov_b32_e32 v198, v18
	v_mov_b32_e32 v199, v19
	v_lshl_add_u64 v[162:163], v[8:9], 0, v[160:161]
	s_nop 0
	v_permlane16_swap_b32 v196, v198
	v_permlane16_swap_b32 v197, v199
	global_store_dwordx4 v[162:163], v[196:199], off offset:256
	s_cbranch_vccz .LBB0_5681
	s_waitcnt vmcnt(0)
	s_cmpk_gt_u32 s3, 0xff
	s_cbranch_scc1 .LBB0_5696
	s_barrier
